# GEMM K-loops of phases 1,2,8,9,10: remaining LDS-DMA address VALU removed (scalar T pairs = base + half-tile step computed by SALU at segment start); no 64-bit VALU address ops left in those loops
# speedup vs baseline: 1.0099x; 1.0099x over previous
; #define PG8_STAGE(bufoff, gbase, voff) do { _Pragma("unroll") for (int _i = 0; _i < 2; ++_i) \
;         __builtin_amdgcn_global_load_lds((const unsigned*)((const char*)(gbase) + (voff)[_i]), (LAS unsigned*)(lds + (bufoff) + ldsw + _i * 8192), 16, 0, 0); } while (0)
; #define PG8_LDA(dst, b, h) do { _Pragma("unroll") for (int m = 0; m < 4; ++m) _Pragma("unroll") for (int k = 0; k < 2; ++k) dst[m][k] = *(const LAS bf16x8*)(lds + PG8_SA(b, h) + aoff + m * 2048 + k * 1024); } while (0)
; #define PG8_LDB(dst, b, h) do { _Pragma("unroll") for (int n = 0; n < 2; ++n) _Pragma("unroll") for (int k = 0; k < 2; ++k) dst[n][k] = *(const LAS bf16x8*)(lds + PG8_SB(b, h) + boff + n * 2048 + k * 1024); } while (0)
; #define PG8_MMA(ai, bj, At, Bt) do { __builtin_amdgcn_s_setprio(1); _Pragma("unroll") for (int m = 0; m < 4; ++m) _Pragma("unroll") for (int n = 0; n < 2; ++n) _Pragma("unroll") for (int k = 0; k < 2; ++k) \
;         acc[ai][bj][m][n] = __builtin_amdgcn_mfma_f32_16x16x32_bf16(Bt[n][k], At[m][k], acc[ai][bj][m][n], 0, 0, 0); __builtin_amdgcn_s_setprio(0); } while (0)
; #define PG8_WAIT_V(n) asm volatile("s_waitcnt vmcnt(" #n ")" ::: "memory")
; #define PG8_WAIT_L(n) asm volatile("s_waitcnt lgkmcnt(" #n ")" ::: "memory")
; #define PG8_BAR __builtin_amdgcn_s_barrier()
; #define PG8_SCHED __builtin_amdgcn_sched_barrier(0)
; template <class Epi, class Sched>
; DI void gemm_phase(LAS unsigned char* lds, const Gemm g, const Sched& S, const Epi& E) {
;     ...
;             PG8_LDB(B0, 0, 0); PG8_LDB(B1, 0, 1); PG8_SCHED; PG8_LDA(At, 0, 0); PG8_STAGE(PG8_SA(1, 1), a1 + hstepA, voffA);
;             PG8_WAIT_V(8); PG8_WAIT_L(0); PG8_BAR; PG8_MMA(0, 0, At, B0); PG8_MMA(0, 1, At, B1); PG8_BAR; PG8_SCHED;
;             PG8_LDA(At, 0, 1); PG8_STAGE(PG8_SB(0, 0), b2, voffB); PG8_STAGE(PG8_SB(0, 1), b2 + hstepB, voffB); PG8_STAGE(PG8_SA(0, 0), a2, voffA);
;             PG8_WAIT_V(8); PG8_WAIT_L(0); PG8_BAR; PG8_MMA(1, 0, At, B0); PG8_MMA(1, 1, At, B1); PG8_BAR; PG8_SCHED;
.Lpk0_w1:
	s_waitcnt lgkmcnt(0)
	s_barrier
	s_setprio 1
	v_mfma_f32_16x16x32_bf16 v[126:129], v[168:171], v[202:205], 0
	v_mfma_f32_16x16x32_bf16 v[118:121], v[176:179], v[202:205], 0
	v_mfma_f32_16x16x32_bf16 v[110:113], v[168:171], v[210:213], 0
	v_mfma_f32_16x16x32_bf16 v[102:105], v[176:179], v[210:213], 0
	v_mfma_f32_16x16x32_bf16 v[94:97], v[168:171], v[218:221], 0
	v_mfma_f32_16x16x32_bf16 v[86:89], v[176:179], v[218:221], 0
	v_mfma_f32_16x16x32_bf16 v[78:81], v[168:171], v[226:229], 0
	v_mfma_f32_16x16x32_bf16 v[70:73], v[176:179], v[226:229], 0
	v_mfma_f32_16x16x32_bf16 v[126:129], v[172:175], v[206:209], v[126:129]
	v_mfma_f32_16x16x32_bf16 v[118:121], v[180:183], v[206:209], v[118:121]
	v_mfma_f32_16x16x32_bf16 v[110:113], v[172:175], v[214:217], v[110:113]
	v_mfma_f32_16x16x32_bf16 v[102:105], v[180:183], v[214:217], v[102:105]
	v_mfma_f32_16x16x32_bf16 v[94:97], v[172:175], v[222:225], v[94:97]
	v_mfma_f32_16x16x32_bf16 v[86:89], v[180:183], v[222:225], v[86:89]
	v_mfma_f32_16x16x32_bf16 v[78:81], v[172:175], v[230:233], v[78:81]
	v_mfma_f32_16x16x32_bf16 v[70:73], v[180:183], v[230:233], v[70:73]
	v_mfma_f32_16x16x32_bf16 v[122:125], v[186:189], v[202:205], 0
	v_mfma_f32_16x16x32_bf16 v[114:117], v[194:197], v[202:205], 0
	v_mfma_f32_16x16x32_bf16 v[106:109], v[186:189], v[210:213], 0
	v_mfma_f32_16x16x32_bf16 v[98:101], v[194:197], v[210:213], 0
	v_mfma_f32_16x16x32_bf16 v[90:93], v[186:189], v[218:221], 0
	v_mfma_f32_16x16x32_bf16 v[82:85], v[194:197], v[218:221], 0
	v_mfma_f32_16x16x32_bf16 v[74:77], v[186:189], v[226:229], 0
	v_mfma_f32_16x16x32_bf16 v[66:69], v[194:197], v[226:229], 0
	v_mfma_f32_16x16x32_bf16 v[122:125], v[190:193], v[206:209], v[122:125]
	v_mfma_f32_16x16x32_bf16 v[114:117], v[198:201], v[206:209], v[114:117]
	v_mfma_f32_16x16x32_bf16 v[106:109], v[190:193], v[214:217], v[106:109]
	v_mfma_f32_16x16x32_bf16 v[98:101], v[198:201], v[214:217], v[98:101]
	v_mfma_f32_16x16x32_bf16 v[90:93], v[190:193], v[222:225], v[90:93]
	v_mfma_f32_16x16x32_bf16 v[82:85], v[198:201], v[222:225], v[82:85]
	v_mfma_f32_16x16x32_bf16 v[74:77], v[190:193], v[230:233], v[74:77]
	v_mfma_f32_16x16x32_bf16 v[66:69], v[198:201], v[230:233], v[66:69]
	s_setprio 0
	s_barrier
	s_add_u32 s88, s42, s16
	s_addc_u32 s89, s43, s17
	s_add_u32 s90, s44, s16
	s_addc_u32 s91, s45, s17
	s_add_i32 s66, s57, s46
	s_mov_b32 m0, s66
	ds_read_b128 v[202:205], v160 offset:16384
	ds_read_b128 v[206:209], v160 offset:17408
	ds_read_b128 v[210:213], v160 offset:18432
	ds_read_b128 v[214:217], v160 offset:19456
	ds_read_b128 v[218:221], v160 offset:20480
	ds_read_b128 v[222:225], v160 offset:21504
	ds_read_b128 v[226:229], v160 offset:22528
	ds_read_b128 v[230:233], v160 offset:23552
	global_load_lds_dwordx4 v134, s[42:43]
	s_add_i32 m0, s66, 0x2000
	s_add_u32 s66, s42, 0x40000
	s_addc_u32 s67, s43, 0
	s_add_i32 s68, s58, s46
	global_load_lds_dwordx4 v130, s[42:43]
	s_mov_b32 m0, s68
	s_nop 0
	global_load_lds_dwordx4 v134, s[66:67]
	s_add_i32 m0, s68, 0x2000
	s_nop 0
	global_load_lds_dwordx4 v130, s[66:67]
	s_mov_b32 m0, s49
	s_nop 0
	global_load_lds_dwordx4 v136, s[44:45]
	s_mov_b32 m0, s50
	s_nop 0
	global_load_lds_dwordx4 v132, s[44:45]
	s_cmp_lg_u32 s99, 0
	s_cbranch_scc1 .Lpk0_w2
	s_waitcnt vmcnt(8)
.Lpk0_w2:
	s_mov_b32 s99, 0
	s_waitcnt lgkmcnt(0)
	s_barrier
	s_setprio 1
	v_mfma_f32_16x16x32_bf16 v[62:65], v[168:171], v[202:205], 0
	v_mfma_f32_16x16x32_bf16 v[54:57], v[176:179], v[202:205], 0
	v_mfma_f32_16x16x32_bf16 v[46:49], v[168:171], v[210:213], 0
	v_mfma_f32_16x16x32_bf16 v[38:41], v[176:179], v[210:213], 0
	v_mfma_f32_16x16x32_bf16 v[30:33], v[168:171], v[218:221], 0
	v_mfma_f32_16x16x32_bf16 v[22:25], v[176:179], v[218:221], 0
	v_mfma_f32_16x16x32_bf16 v[14:17], v[168:171], v[226:229], 0
	v_mfma_f32_16x16x32_bf16 v[6:9], v[176:179], v[226:229], 0
	v_mfma_f32_16x16x32_bf16 v[62:65], v[172:175], v[206:209], v[62:65]
	v_mfma_f32_16x16x32_bf16 v[54:57], v[180:183], v[206:209], v[54:57]
	v_mfma_f32_16x16x32_bf16 v[46:49], v[172:175], v[214:217], v[46:49]
	v_mfma_f32_16x16x32_bf16 v[38:41], v[180:183], v[214:217], v[38:41]
	v_mfma_f32_16x16x32_bf16 v[30:33], v[172:175], v[222:225], v[30:33]
	v_mfma_f32_16x16x32_bf16 v[22:25], v[180:183], v[222:225], v[22:25]
	v_mfma_f32_16x16x32_bf16 v[14:17], v[172:175], v[230:233], v[14:17]
	v_mfma_f32_16x16x32_bf16 v[6:9], v[180:183], v[230:233], v[6:9]
	v_mfma_f32_16x16x32_bf16 v[58:61], v[186:189], v[202:205], 0
	v_mfma_f32_16x16x32_bf16 v[50:53], v[194:197], v[202:205], 0
	v_mfma_f32_16x16x32_bf16 v[42:45], v[186:189], v[210:213], 0
	v_mfma_f32_16x16x32_bf16 v[34:37], v[194:197], v[210:213], 0
	v_mfma_f32_16x16x32_bf16 v[26:29], v[186:189], v[218:221], 0
	v_mfma_f32_16x16x32_bf16 v[18:21], v[194:197], v[218:221], 0
	v_mfma_f32_16x16x32_bf16 v[10:13], v[186:189], v[226:229], 0
	v_mfma_f32_16x16x32_bf16 v[2:5], v[194:197], v[226:229], 0
	v_mfma_f32_16x16x32_bf16 v[58:61], v[190:193], v[206:209], v[58:61]
	v_mfma_f32_16x16x32_bf16 v[50:53], v[198:201], v[206:209], v[50:53]
	v_mfma_f32_16x16x32_bf16 v[42:45], v[190:193], v[214:217], v[42:45]
	v_mfma_f32_16x16x32_bf16 v[34:37], v[198:201], v[214:217], v[34:37]
	v_mfma_f32_16x16x32_bf16 v[26:29], v[190:193], v[222:225], v[26:29]
	v_mfma_f32_16x16x32_bf16 v[18:21], v[198:201], v[222:225], v[18:21]
	v_mfma_f32_16x16x32_bf16 v[10:13], v[190:193], v[230:233], v[10:13]
	v_mfma_f32_16x16x32_bf16 v[2:5], v[198:201], v[230:233], v[2:5]
	s_setprio 0
	s_barrier
; #define PG8_STAGE(bufoff, gbase, voff) do { _Pragma("unroll") for (int _i = 0; _i < 2; ++_i) \
;         __builtin_amdgcn_global_load_lds((const unsigned*)((const char*)(gbase) + (voff)[_i]), (LAS unsigned*)(lds + (bufoff) + ldsw + _i * 8192), 16, 0, 0); } while (0)
; #define PG8_LDA(dst, b, h) do { _Pragma("unroll") for (int m = 0; m < 4; ++m) _Pragma("unroll") for (int k = 0; k < 2; ++k) dst[m][k] = *(const LAS bf16x8*)(lds + PG8_SA(b, h) + aoff + m * 2048 + k * 1024); } while (0)
; #define PG8_LDB(dst, b, h) do { _Pragma("unroll") for (int n = 0; n < 2; ++n) _Pragma("unroll") for (int k = 0; k < 2; ++k) dst[n][k] = *(const LAS bf16x8*)(lds + PG8_SB(b, h) + boff + n * 2048 + k * 1024); } while (0)
; #define PG8_MMA(ai, bj, At, Bt) do { __builtin_amdgcn_s_setprio(1); _Pragma("unroll") for (int m = 0; m < 4; ++m) _Pragma("unroll") for (int n = 0; n < 2; ++n) _Pragma("unroll") for (int k = 0; k < 2; ++k) \
;         acc[ai][bj][m][n] = __builtin_amdgcn_mfma_f32_16x16x32_bf16(Bt[n][k], At[m][k], acc[ai][bj][m][n], 0, 0, 0); __builtin_amdgcn_s_setprio(0); } while (0)
; #define PG8_WAIT_V(n) asm volatile("s_waitcnt vmcnt(" #n ")" ::: "memory")
; #define PG8_WAIT_L(n) asm volatile("s_waitcnt lgkmcnt(" #n ")" ::: "memory")
; #define PG8_BAR __builtin_amdgcn_s_barrier()
; #define PG8_SCHED __builtin_amdgcn_sched_barrier(0)
; template <class Epi, class Sched>
; DI void gemm_phase(LAS unsigned char* lds, const Gemm g, const Sched& S, const Epi& E) {
;     ...
;             PG8_LDB(B0, 1, 0); PG8_LDB(B1, 1, 1); PG8_SCHED; PG8_LDA(At, 1, 0); PG8_STAGE(PG8_SA(0, 1), a2 + hstepA, voffA);
;             PG8_WAIT_V(8); PG8_WAIT_L(0); PG8_BAR; PG8_MMA(0, 0, At, B0); PG8_MMA(0, 1, At, B1); PG8_BAR; PG8_SCHED;
;             PG8_LDA(At, 1, 1); PG8_STAGE(PG8_SB(1, 0), b3, voffB); PG8_STAGE(PG8_SB(1, 1), b3 + hstepB, voffB); PG8_STAGE(PG8_SA(1, 0), a3, voffA);
;             PG8_WAIT_V(8); PG8_WAIT_L(0); PG8_BAR; PG8_MMA(1, 0, At, B0); PG8_MMA(1, 1, At, B1); PG8_BAR; PG8_SCHED;
;         }
	s_add_i32 s66, 0, 0x18000
	v_add_u32_e32 v167, s66, v158
	s_add_i32 s67, 0, 0x1c000
	ds_read_b128 v[168:171], v167
	ds_read_b128 v[172:175], v167 offset:1024
	ds_read_b128 v[176:179], v167 offset:2048
	ds_read_b128 v[180:183], v167 offset:3072
	v_add_u32_e32 v167, s67, v158
	ds_read_b128 v[186:189], v167
	ds_read_b128 v[190:193], v167 offset:1024
	ds_read_b128 v[194:197], v167 offset:2048
	ds_read_b128 v[198:201], v167 offset:3072
	s_add_u32 s44, s44, 0x40000
	s_addc_u32 s45, s45, 0
	s_mov_b32 m0, s51
	ds_read_b128 v[202:205], v160 offset:32768
	ds_read_b128 v[206:209], v160 offset:33792
	ds_read_b128 v[210:213], v160 offset:34816
	ds_read_b128 v[214:217], v160 offset:35840
	ds_read_b128 v[218:221], v160 offset:36864
	ds_read_b128 v[222:225], v160 offset:37888
	ds_read_b128 v[226:229], v160 offset:38912
	ds_read_b128 v[230:233], v160 offset:39936
	global_load_lds_dwordx4 v136, s[44:45]
	s_mov_b32 m0, s52
	s_nop 0
	global_load_lds_dwordx4 v132, s[44:45]
	s_waitcnt vmcnt(8)
	s_waitcnt lgkmcnt(0)
	s_barrier
	s_setprio 1
	v_mfma_f32_16x16x32_bf16 v[126:129], v[168:171], v[202:205], v[126:129]
	v_mfma_f32_16x16x32_bf16 v[118:121], v[176:179], v[202:205], v[118:121]
	v_mfma_f32_16x16x32_bf16 v[110:113], v[168:171], v[210:213], v[110:113]
	v_mfma_f32_16x16x32_bf16 v[102:105], v[176:179], v[210:213], v[102:105]
	v_mfma_f32_16x16x32_bf16 v[94:97], v[168:171], v[218:221], v[94:97]
	v_mfma_f32_16x16x32_bf16 v[86:89], v[176:179], v[218:221], v[86:89]
	v_mfma_f32_16x16x32_bf16 v[78:81], v[168:171], v[226:229], v[78:81]
	v_mfma_f32_16x16x32_bf16 v[70:73], v[176:179], v[226:229], v[70:73]
	v_mfma_f32_16x16x32_bf16 v[126:129], v[172:175], v[206:209], v[126:129]
	v_mfma_f32_16x16x32_bf16 v[118:121], v[180:183], v[206:209], v[118:121]
	v_mfma_f32_16x16x32_bf16 v[110:113], v[172:175], v[214:217], v[110:113]
	v_mfma_f32_16x16x32_bf16 v[102:105], v[180:183], v[214:217], v[102:105]
	v_mfma_f32_16x16x32_bf16 v[94:97], v[172:175], v[222:225], v[94:97]
	v_mfma_f32_16x16x32_bf16 v[86:89], v[180:183], v[222:225], v[86:89]
	v_mfma_f32_16x16x32_bf16 v[78:81], v[172:175], v[230:233], v[78:81]
	v_mfma_f32_16x16x32_bf16 v[70:73], v[180:183], v[230:233], v[70:73]
	v_mfma_f32_16x16x32_bf16 v[122:125], v[186:189], v[202:205], v[122:125]
	v_mfma_f32_16x16x32_bf16 v[114:117], v[194:197], v[202:205], v[114:117]
	v_mfma_f32_16x16x32_bf16 v[106:109], v[186:189], v[210:213], v[106:109]
	v_mfma_f32_16x16x32_bf16 v[98:101], v[194:197], v[210:213], v[98:101]
	v_mfma_f32_16x16x32_bf16 v[90:93], v[186:189], v[218:221], v[90:93]
	v_mfma_f32_16x16x32_bf16 v[82:85], v[194:197], v[218:221], v[82:85]
	v_mfma_f32_16x16x32_bf16 v[74:77], v[186:189], v[226:229], v[74:77]
	v_mfma_f32_16x16x32_bf16 v[66:69], v[194:197], v[226:229], v[66:69]
	v_mfma_f32_16x16x32_bf16 v[122:125], v[190:193], v[206:209], v[122:125]
	v_mfma_f32_16x16x32_bf16 v[114:117], v[198:201], v[206:209], v[114:117]
	v_mfma_f32_16x16x32_bf16 v[106:109], v[190:193], v[214:217], v[106:109]
	v_mfma_f32_16x16x32_bf16 v[98:101], v[198:201], v[214:217], v[98:101]
	v_mfma_f32_16x16x32_bf16 v[90:93], v[190:193], v[222:225], v[90:93]
	v_mfma_f32_16x16x32_bf16 v[82:85], v[198:201], v[222:225], v[82:85]
	v_mfma_f32_16x16x32_bf16 v[74:77], v[190:193], v[230:233], v[74:77]
	v_mfma_f32_16x16x32_bf16 v[66:69], v[198:201], v[230:233], v[66:69]
	s_setprio 0
	s_barrier
	s_add_i32 s44, s66, s46
	s_mov_b32 m0, s44
	ds_read_b128 v[202:205], v160 offset:49152
	ds_read_b128 v[206:209], v160 offset:50176
	ds_read_b128 v[210:213], v160 offset:51200
	ds_read_b128 v[214:217], v160 offset:52224
	ds_read_b128 v[218:221], v160 offset:53248
	ds_read_b128 v[222:225], v160 offset:54272
	ds_read_b128 v[226:229], v160 offset:55296
	ds_read_b128 v[230:233], v160 offset:56320
	global_load_lds_dwordx4 v134, s[88:89]
	s_add_i32 m0, s44, 0x2000
	s_add_u32 s42, s42, 0x40080
	s_addc_u32 s43, s43, 0
	s_add_i32 s44, s67, s46
	global_load_lds_dwordx4 v130, s[88:89]
	s_mov_b32 m0, s44
	s_nop 0
	global_load_lds_dwordx4 v134, s[42:43]
	s_add_i32 m0, s44, 0x2000
	s_nop 0
	global_load_lds_dwordx4 v130, s[42:43]
	s_mov_b32 m0, s54
	s_nop 0
	global_load_lds_dwordx4 v136, s[90:91]
	s_mov_b32 m0, s55
	s_nop 0
	global_load_lds_dwordx4 v132, s[90:91]
	s_waitcnt vmcnt(8)
	s_waitcnt lgkmcnt(0)
	s_barrier
	s_setprio 1
	v_mfma_f32_16x16x32_bf16 v[62:65], v[168:171], v[202:205], v[62:65]
	v_mfma_f32_16x16x32_bf16 v[54:57], v[176:179], v[202:205], v[54:57]
	v_mfma_f32_16x16x32_bf16 v[46:49], v[168:171], v[210:213], v[46:49]
	v_mfma_f32_16x16x32_bf16 v[38:41], v[176:179], v[210:213], v[38:41]
	v_mfma_f32_16x16x32_bf16 v[30:33], v[168:171], v[218:221], v[30:33]
	v_mfma_f32_16x16x32_bf16 v[22:25], v[176:179], v[218:221], v[22:25]
	v_mfma_f32_16x16x32_bf16 v[14:17], v[168:171], v[226:229], v[14:17]
	v_mfma_f32_16x16x32_bf16 v[6:9], v[176:179], v[226:229], v[6:9]
	v_mfma_f32_16x16x32_bf16 v[62:65], v[172:175], v[206:209], v[62:65]
	v_mfma_f32_16x16x32_bf16 v[54:57], v[180:183], v[206:209], v[54:57]
	v_mfma_f32_16x16x32_bf16 v[46:49], v[172:175], v[214:217], v[46:49]
	v_mfma_f32_16x16x32_bf16 v[38:41], v[180:183], v[214:217], v[38:41]
	v_mfma_f32_16x16x32_bf16 v[30:33], v[172:175], v[222:225], v[30:33]
	v_mfma_f32_16x16x32_bf16 v[22:25], v[180:183], v[222:225], v[22:25]
	v_mfma_f32_16x16x32_bf16 v[14:17], v[172:175], v[230:233], v[14:17]
	v_mfma_f32_16x16x32_bf16 v[6:9], v[180:183], v[230:233], v[6:9]
	v_mfma_f32_16x16x32_bf16 v[58:61], v[186:189], v[202:205], v[58:61]
	v_mfma_f32_16x16x32_bf16 v[50:53], v[194:197], v[202:205], v[50:53]
	v_mfma_f32_16x16x32_bf16 v[42:45], v[186:189], v[210:213], v[42:45]
	v_mfma_f32_16x16x32_bf16 v[34:37], v[194:197], v[210:213], v[34:37]
	v_mfma_f32_16x16x32_bf16 v[26:29], v[186:189], v[218:221], v[26:29]
	v_mfma_f32_16x16x32_bf16 v[18:21], v[194:197], v[218:221], v[18:21]
	v_mfma_f32_16x16x32_bf16 v[10:13], v[186:189], v[226:229], v[10:13]
	v_mfma_f32_16x16x32_bf16 v[2:5], v[194:197], v[226:229], v[2:5]
	v_mfma_f32_16x16x32_bf16 v[58:61], v[190:193], v[206:209], v[58:61]
	v_mfma_f32_16x16x32_bf16 v[50:53], v[198:201], v[206:209], v[50:53]
	v_mfma_f32_16x16x32_bf16 v[42:45], v[190:193], v[214:217], v[42:45]
	v_mfma_f32_16x16x32_bf16 v[34:37], v[198:201], v[214:217], v[34:37]
	v_mfma_f32_16x16x32_bf16 v[26:29], v[190:193], v[222:225], v[26:29]
	v_mfma_f32_16x16x32_bf16 v[18:21], v[198:201], v[222:225], v[18:21]
	v_mfma_f32_16x16x32_bf16 v[10:13], v[190:193], v[230:233], v[10:13]
	v_mfma_f32_16x16x32_bf16 v[2:5], v[198:201], v[230:233], v[2:5]
	s_setprio 0
	s_barrier
	s_add_i32 s65, s65, 2
	s_add_u32 s40, s40, 0x100
	s_addc_u32 s41, s41, 0
	s_add_u32 s63, s63, 0x100
	s_addc_u32 s64, s64, 0
	s_cmp_gt_u32 s65, 13
; #define PG8_STAGE(bufoff, gbase, voff) do { _Pragma("unroll") for (int _i = 0; _i < 2; ++_i) \
;         __builtin_amdgcn_global_load_lds((const unsigned*)((const char*)(gbase) + (voff)[_i]), (LAS unsigned*)(lds + (bufoff) + ldsw + _i * 8192), 16, 0, 0); } while (0)
; #define PG8_LDA(dst, b, h) do { _Pragma("unroll") for (int m = 0; m < 4; ++m) _Pragma("unroll") for (int k = 0; k < 2; ++k) dst[m][k] = *(const LAS bf16x8*)(lds + PG8_SA(b, h) + aoff + m * 2048 + k * 1024); } while (0)
; #define PG8_LDB(dst, b, h) do { _Pragma("unroll") for (int n = 0; n < 2; ++n) _Pragma("unroll") for (int k = 0; k < 2; ++k) dst[n][k] = *(const LAS bf16x8*)(lds + PG8_SB(b, h) + boff + n * 2048 + k * 1024); } while (0)
; #define PG8_MMA(ai, bj, At, Bt) do { __builtin_amdgcn_s_setprio(1); _Pragma("unroll") for (int m = 0; m < 4; ++m) _Pragma("unroll") for (int n = 0; n < 2; ++n) _Pragma("unroll") for (int k = 0; k < 2; ++k) \
;         acc[ai][bj][m][n] = __builtin_amdgcn_mfma_f32_16x16x32_bf16(Bt[n][k], At[m][k], acc[ai][bj][m][n], 0, 0, 0); __builtin_amdgcn_s_setprio(0); } while (0)
; #define PG8_WAIT_V(n) asm volatile("s_waitcnt vmcnt(" #n ")" ::: "memory")
; #define PG8_WAIT_L(n) asm volatile("s_waitcnt lgkmcnt(" #n ")" ::: "memory")
; #define PG8_BAR __builtin_amdgcn_s_barrier()
; #define PG8_SCHED __builtin_amdgcn_sched_barrier(0)
; template <class Epi, class Sched>
; DI void gemm_phase(LAS unsigned char* lds, const Gemm g, const Sched& S, const Epi& E) {
;     ...
;             PG8_LDB(B0, 0, 0); PG8_LDB(B1, 0, 1); PG8_SCHED; PG8_LDA(At, 0, 0); PG8_STAGE(PG8_SA(1, 1), a1 + hstepA, voffA);
;             PG8_WAIT_V(8); PG8_WAIT_L(0); PG8_BAR; PG8_MMA(0, 0, At, B0); PG8_MMA(0, 1, At, B1); PG8_BAR; PG8_SCHED;
;             PG8_LDA(At, 0, 1); PG8_STAGE(PG8_SB(0, 0), b2, voffB); PG8_STAGE(PG8_SB(0, 1), b2 + hstepB, voffB); PG8_STAGE(PG8_SA(0, 0), a2, voffA);
;             PG8_WAIT_V(8); PG8_WAIT_L(0); PG8_BAR; PG8_MMA(1, 0, At, B0); PG8_MMA(1, 1, At, B1); PG8_BAR; PG8_SCHED;
.LBB0_179:
	ds_read_b128 v[168:171], v162
	ds_read_b128 v[172:175], v162 offset:1024
	ds_read_b128 v[176:179], v162 offset:2048
	ds_read_b128 v[180:183], v162 offset:3072
	ds_read_b128 v[186:189], v163
	ds_read_b128 v[190:193], v163 offset:1024
	ds_read_b128 v[194:197], v163 offset:2048
	ds_read_b128 v[198:201], v163 offset:3072
	s_add_u32 s42, s40, 0xfffc0080
	s_addc_u32 s43, s41, -1
	s_cmp_eq_u32 s65, 12
	s_cselect_b32 s45, s35, s43
	s_cselect_b32 s44, s61, s42
	s_cselect_b32 s43, s21, s64
	s_cselect_b32 s42, s62, s63
	s_add_i32 m0, s49, 0xc000
	ds_read_b128 v[202:205], v160
	ds_read_b128 v[206:209], v160 offset:1024
	ds_read_b128 v[210:213], v160 offset:2048
	ds_read_b128 v[214:217], v160 offset:3072
	ds_read_b128 v[218:221], v160 offset:4096
	ds_read_b128 v[222:225], v160 offset:5120
	ds_read_b128 v[226:229], v160 offset:6144
	ds_read_b128 v[230:233], v160 offset:7168
	global_load_lds_dwordx4 v138, s[40:41]
	s_add_i32 m0, s49, 0xe000
	s_nop 0
	global_load_lds_dwordx4 v140, s[40:41]
	s_waitcnt vmcnt(8)
	s_waitcnt lgkmcnt(0)
	s_barrier
	s_setprio 1
	v_mfma_f32_16x16x32_bf16 v[126:129], v[168:171], v[202:205], v[126:129]
	v_mfma_f32_16x16x32_bf16 v[118:121], v[176:179], v[202:205], v[118:121]
	v_mfma_f32_16x16x32_bf16 v[110:113], v[168:171], v[210:213], v[110:113]
	v_mfma_f32_16x16x32_bf16 v[102:105], v[176:179], v[210:213], v[102:105]
	v_mfma_f32_16x16x32_bf16 v[94:97], v[168:171], v[218:221], v[94:97]
	v_mfma_f32_16x16x32_bf16 v[86:89], v[176:179], v[218:221], v[86:89]
	v_mfma_f32_16x16x32_bf16 v[78:81], v[168:171], v[226:229], v[78:81]
	v_mfma_f32_16x16x32_bf16 v[70:73], v[176:179], v[226:229], v[70:73]
	v_mfma_f32_16x16x32_bf16 v[126:129], v[172:175], v[206:209], v[126:129]
	v_mfma_f32_16x16x32_bf16 v[118:121], v[180:183], v[206:209], v[118:121]
	v_mfma_f32_16x16x32_bf16 v[110:113], v[172:175], v[214:217], v[110:113]
	v_mfma_f32_16x16x32_bf16 v[102:105], v[180:183], v[214:217], v[102:105]
	v_mfma_f32_16x16x32_bf16 v[94:97], v[172:175], v[222:225], v[94:97]
	v_mfma_f32_16x16x32_bf16 v[86:89], v[180:183], v[222:225], v[86:89]
	v_mfma_f32_16x16x32_bf16 v[78:81], v[172:175], v[230:233], v[78:81]
	v_mfma_f32_16x16x32_bf16 v[70:73], v[180:183], v[230:233], v[70:73]
	v_mfma_f32_16x16x32_bf16 v[122:125], v[186:189], v[202:205], v[122:125]
	v_mfma_f32_16x16x32_bf16 v[114:117], v[194:197], v[202:205], v[114:117]
	v_mfma_f32_16x16x32_bf16 v[106:109], v[186:189], v[210:213], v[106:109]
	v_mfma_f32_16x16x32_bf16 v[98:101], v[194:197], v[210:213], v[98:101]
	v_mfma_f32_16x16x32_bf16 v[90:93], v[186:189], v[218:221], v[90:93]
	v_mfma_f32_16x16x32_bf16 v[82:85], v[194:197], v[218:221], v[82:85]
	v_mfma_f32_16x16x32_bf16 v[74:77], v[186:189], v[226:229], v[74:77]
	v_mfma_f32_16x16x32_bf16 v[66:69], v[194:197], v[226:229], v[66:69]
	v_mfma_f32_16x16x32_bf16 v[122:125], v[190:193], v[206:209], v[122:125]
	v_mfma_f32_16x16x32_bf16 v[114:117], v[198:201], v[206:209], v[114:117]
	v_mfma_f32_16x16x32_bf16 v[106:109], v[190:193], v[214:217], v[106:109]
	v_mfma_f32_16x16x32_bf16 v[98:101], v[198:201], v[214:217], v[98:101]
	v_mfma_f32_16x16x32_bf16 v[90:93], v[190:193], v[222:225], v[90:93]
	v_mfma_f32_16x16x32_bf16 v[82:85], v[198:201], v[222:225], v[82:85]
	v_mfma_f32_16x16x32_bf16 v[74:77], v[190:193], v[230:233], v[74:77]
	v_mfma_f32_16x16x32_bf16 v[66:69], v[198:201], v[230:233], v[66:69]
	s_setprio 0
	s_barrier
	s_add_u32 s88, s42, s16
	s_addc_u32 s89, s43, s17
	s_add_u32 s90, s44, s16
	s_addc_u32 s91, s45, s17
	s_add_i32 s66, s57, s46
	s_mov_b32 m0, s66
	ds_read_b128 v[202:205], v160 offset:16384
	ds_read_b128 v[206:209], v160 offset:17408
	ds_read_b128 v[210:213], v160 offset:18432
	ds_read_b128 v[214:217], v160 offset:19456
	ds_read_b128 v[218:221], v160 offset:20480
	ds_read_b128 v[222:225], v160 offset:21504
	ds_read_b128 v[226:229], v160 offset:22528
	ds_read_b128 v[230:233], v160 offset:23552
	global_load_lds_dwordx4 v134, s[42:43]
	s_add_i32 m0, s66, 0x2000
	s_add_u32 s66, s42, 0x40000
	s_addc_u32 s67, s43, 0
	s_add_i32 s68, s58, s46
	global_load_lds_dwordx4 v130, s[42:43]
	s_mov_b32 m0, s68
	s_nop 0
	global_load_lds_dwordx4 v134, s[66:67]
	s_add_i32 m0, s68, 0x2000
	s_nop 0
	global_load_lds_dwordx4 v130, s[66:67]
	s_mov_b32 m0, s49
	s_nop 0
	global_load_lds_dwordx4 v136, s[44:45]
	s_mov_b32 m0, s50
	s_nop 0
	global_load_lds_dwordx4 v132, s[44:45]
	s_waitcnt vmcnt(8)
	s_waitcnt lgkmcnt(0)
	s_barrier
	s_setprio 1
	v_mfma_f32_16x16x32_bf16 v[62:65], v[168:171], v[202:205], v[62:65]
	v_mfma_f32_16x16x32_bf16 v[54:57], v[176:179], v[202:205], v[54:57]
	v_mfma_f32_16x16x32_bf16 v[46:49], v[168:171], v[210:213], v[46:49]
	v_mfma_f32_16x16x32_bf16 v[38:41], v[176:179], v[210:213], v[38:41]
	v_mfma_f32_16x16x32_bf16 v[30:33], v[168:171], v[218:221], v[30:33]
	v_mfma_f32_16x16x32_bf16 v[22:25], v[176:179], v[218:221], v[22:25]
	v_mfma_f32_16x16x32_bf16 v[14:17], v[168:171], v[226:229], v[14:17]
	v_mfma_f32_16x16x32_bf16 v[6:9], v[176:179], v[226:229], v[6:9]
	v_mfma_f32_16x16x32_bf16 v[62:65], v[172:175], v[206:209], v[62:65]
	v_mfma_f32_16x16x32_bf16 v[54:57], v[180:183], v[206:209], v[54:57]
	v_mfma_f32_16x16x32_bf16 v[46:49], v[172:175], v[214:217], v[46:49]
	v_mfma_f32_16x16x32_bf16 v[38:41], v[180:183], v[214:217], v[38:41]
	v_mfma_f32_16x16x32_bf16 v[30:33], v[172:175], v[222:225], v[30:33]
	v_mfma_f32_16x16x32_bf16 v[22:25], v[180:183], v[222:225], v[22:25]
	v_mfma_f32_16x16x32_bf16 v[14:17], v[172:175], v[230:233], v[14:17]
	v_mfma_f32_16x16x32_bf16 v[6:9], v[180:183], v[230:233], v[6:9]
	v_mfma_f32_16x16x32_bf16 v[58:61], v[186:189], v[202:205], v[58:61]
	v_mfma_f32_16x16x32_bf16 v[50:53], v[194:197], v[202:205], v[50:53]
	v_mfma_f32_16x16x32_bf16 v[42:45], v[186:189], v[210:213], v[42:45]
	v_mfma_f32_16x16x32_bf16 v[34:37], v[194:197], v[210:213], v[34:37]
	v_mfma_f32_16x16x32_bf16 v[26:29], v[186:189], v[218:221], v[26:29]
	v_mfma_f32_16x16x32_bf16 v[18:21], v[194:197], v[218:221], v[18:21]
	v_mfma_f32_16x16x32_bf16 v[10:13], v[186:189], v[226:229], v[10:13]
	v_mfma_f32_16x16x32_bf16 v[2:5], v[194:197], v[226:229], v[2:5]
	v_mfma_f32_16x16x32_bf16 v[58:61], v[190:193], v[206:209], v[58:61]
	v_mfma_f32_16x16x32_bf16 v[50:53], v[198:201], v[206:209], v[50:53]
	v_mfma_f32_16x16x32_bf16 v[42:45], v[190:193], v[214:217], v[42:45]
	v_mfma_f32_16x16x32_bf16 v[34:37], v[198:201], v[214:217], v[34:37]
	v_mfma_f32_16x16x32_bf16 v[26:29], v[190:193], v[222:225], v[26:29]
	v_mfma_f32_16x16x32_bf16 v[18:21], v[198:201], v[222:225], v[18:21]
	v_mfma_f32_16x16x32_bf16 v[10:13], v[190:193], v[230:233], v[10:13]
	v_mfma_f32_16x16x32_bf16 v[2:5], v[198:201], v[230:233], v[2:5]
	s_setprio 0
	s_barrier
; #define PG8_STAGE(bufoff, gbase, voff) do { _Pragma("unroll") for (int _i = 0; _i < 2; ++_i) \
;         __builtin_amdgcn_global_load_lds((const unsigned*)((const char*)(gbase) + (voff)[_i]), (LAS unsigned*)(lds + (bufoff) + ldsw + _i * 8192), 16, 0, 0); } while (0)
; #define PG8_LDA(dst, b, h) do { _Pragma("unroll") for (int m = 0; m < 4; ++m) _Pragma("unroll") for (int k = 0; k < 2; ++k) dst[m][k] = *(const LAS bf16x8*)(lds + PG8_SA(b, h) + aoff + m * 2048 + k * 1024); } while (0)
; #define PG8_LDB(dst, b, h) do { _Pragma("unroll") for (int n = 0; n < 2; ++n) _Pragma("unroll") for (int k = 0; k < 2; ++k) dst[n][k] = *(const LAS bf16x8*)(lds + PG8_SB(b, h) + boff + n * 2048 + k * 1024); } while (0)
; #define PG8_MMA(ai, bj, At, Bt) do { __builtin_amdgcn_s_setprio(1); _Pragma("unroll") for (int m = 0; m < 4; ++m) _Pragma("unroll") for (int n = 0; n < 2; ++n) _Pragma("unroll") for (int k = 0; k < 2; ++k) \
;         acc[ai][bj][m][n] = __builtin_amdgcn_mfma_f32_16x16x32_bf16(Bt[n][k], At[m][k], acc[ai][bj][m][n], 0, 0, 0); __builtin_amdgcn_s_setprio(0); } while (0)
; #define PG8_WAIT_V(n) asm volatile("s_waitcnt vmcnt(" #n ")" ::: "memory")
; #define PG8_WAIT_L(n) asm volatile("s_waitcnt lgkmcnt(" #n ")" ::: "memory")
; #define PG8_BAR __builtin_amdgcn_s_barrier()
; #define PG8_SCHED __builtin_amdgcn_sched_barrier(0)
; template <class Epi, class Sched>
; DI void gemm_phase(LAS unsigned char* lds, const Gemm g, const Sched& S, const Epi& E) {
;     ...
;             PG8_LDB(B0, 1, 0); PG8_LDB(B1, 1, 1); PG8_SCHED; PG8_LDA(At, 1, 0); PG8_STAGE(PG8_SA(0, 1), a2 + hstepA, voffA);
;             PG8_WAIT_V(8); PG8_WAIT_L(0); PG8_BAR; PG8_MMA(0, 0, At, B0); PG8_MMA(0, 1, At, B1); PG8_BAR; PG8_SCHED;
;             PG8_LDA(At, 1, 1); PG8_STAGE(PG8_SB(1, 0), b3, voffB); PG8_STAGE(PG8_SB(1, 1), b3 + hstepB, voffB); PG8_STAGE(PG8_SA(1, 0), a3, voffA);
;             PG8_WAIT_V(8); PG8_WAIT_L(0); PG8_BAR; PG8_MMA(1, 0, At, B0); PG8_MMA(1, 1, At, B1); PG8_BAR; PG8_SCHED;
;         }
;         if (wr == 0) PG8_BAR;
	s_add_i32 s66, 0, 0x18000
	v_add_u32_e32 v167, s66, v158
	s_add_i32 s67, 0, 0x1c000
	ds_read_b128 v[168:171], v167
	ds_read_b128 v[172:175], v167 offset:1024
	ds_read_b128 v[176:179], v167 offset:2048
	ds_read_b128 v[180:183], v167 offset:3072
	v_add_u32_e32 v167, s67, v158
	ds_read_b128 v[186:189], v167
	ds_read_b128 v[190:193], v167 offset:1024
	ds_read_b128 v[194:197], v167 offset:2048
	ds_read_b128 v[198:201], v167 offset:3072
	s_add_u32 s44, s44, 0x40000
	s_addc_u32 s45, s45, 0
	s_mov_b32 m0, s51
	ds_read_b128 v[202:205], v160 offset:32768
	ds_read_b128 v[206:209], v160 offset:33792
	ds_read_b128 v[210:213], v160 offset:34816
	ds_read_b128 v[214:217], v160 offset:35840
	ds_read_b128 v[218:221], v160 offset:36864
	ds_read_b128 v[222:225], v160 offset:37888
	ds_read_b128 v[226:229], v160 offset:38912
	ds_read_b128 v[230:233], v160 offset:39936
	global_load_lds_dwordx4 v136, s[44:45]
	s_mov_b32 m0, s52
	s_nop 0
	global_load_lds_dwordx4 v132, s[44:45]
	s_waitcnt vmcnt(8)
	s_waitcnt lgkmcnt(0)
	s_barrier
	s_setprio 1
	v_mfma_f32_16x16x32_bf16 v[126:129], v[168:171], v[202:205], v[126:129]
	v_mfma_f32_16x16x32_bf16 v[118:121], v[176:179], v[202:205], v[118:121]
	v_mfma_f32_16x16x32_bf16 v[110:113], v[168:171], v[210:213], v[110:113]
	v_mfma_f32_16x16x32_bf16 v[102:105], v[176:179], v[210:213], v[102:105]
	v_mfma_f32_16x16x32_bf16 v[94:97], v[168:171], v[218:221], v[94:97]
	v_mfma_f32_16x16x32_bf16 v[86:89], v[176:179], v[218:221], v[86:89]
	v_mfma_f32_16x16x32_bf16 v[78:81], v[168:171], v[226:229], v[78:81]
	v_mfma_f32_16x16x32_bf16 v[70:73], v[176:179], v[226:229], v[70:73]
	v_mfma_f32_16x16x32_bf16 v[126:129], v[172:175], v[206:209], v[126:129]
	v_mfma_f32_16x16x32_bf16 v[118:121], v[180:183], v[206:209], v[118:121]
	v_mfma_f32_16x16x32_bf16 v[110:113], v[172:175], v[214:217], v[110:113]
	v_mfma_f32_16x16x32_bf16 v[102:105], v[180:183], v[214:217], v[102:105]
	v_mfma_f32_16x16x32_bf16 v[94:97], v[172:175], v[222:225], v[94:97]
	v_mfma_f32_16x16x32_bf16 v[86:89], v[180:183], v[222:225], v[86:89]
	v_mfma_f32_16x16x32_bf16 v[78:81], v[172:175], v[230:233], v[78:81]
	v_mfma_f32_16x16x32_bf16 v[70:73], v[180:183], v[230:233], v[70:73]
	v_mfma_f32_16x16x32_bf16 v[122:125], v[186:189], v[202:205], v[122:125]
	v_mfma_f32_16x16x32_bf16 v[114:117], v[194:197], v[202:205], v[114:117]
	v_mfma_f32_16x16x32_bf16 v[106:109], v[186:189], v[210:213], v[106:109]
	v_mfma_f32_16x16x32_bf16 v[98:101], v[194:197], v[210:213], v[98:101]
	v_mfma_f32_16x16x32_bf16 v[90:93], v[186:189], v[218:221], v[90:93]
	v_mfma_f32_16x16x32_bf16 v[82:85], v[194:197], v[218:221], v[82:85]
	v_mfma_f32_16x16x32_bf16 v[74:77], v[186:189], v[226:229], v[74:77]
	v_mfma_f32_16x16x32_bf16 v[66:69], v[194:197], v[226:229], v[66:69]
	v_mfma_f32_16x16x32_bf16 v[122:125], v[190:193], v[206:209], v[122:125]
	v_mfma_f32_16x16x32_bf16 v[114:117], v[198:201], v[206:209], v[114:117]
	v_mfma_f32_16x16x32_bf16 v[106:109], v[190:193], v[214:217], v[106:109]
	v_mfma_f32_16x16x32_bf16 v[98:101], v[198:201], v[214:217], v[98:101]
	v_mfma_f32_16x16x32_bf16 v[90:93], v[190:193], v[222:225], v[90:93]
	v_mfma_f32_16x16x32_bf16 v[82:85], v[198:201], v[222:225], v[82:85]
	v_mfma_f32_16x16x32_bf16 v[74:77], v[190:193], v[230:233], v[74:77]
	v_mfma_f32_16x16x32_bf16 v[66:69], v[198:201], v[230:233], v[66:69]
	s_setprio 0
	s_barrier
	s_add_i32 s44, s66, s46
	s_mov_b32 m0, s44
	ds_read_b128 v[202:205], v160 offset:49152
	ds_read_b128 v[206:209], v160 offset:50176
	ds_read_b128 v[210:213], v160 offset:51200
	ds_read_b128 v[214:217], v160 offset:52224
	ds_read_b128 v[218:221], v160 offset:53248
	ds_read_b128 v[222:225], v160 offset:54272
	ds_read_b128 v[226:229], v160 offset:55296
	ds_read_b128 v[230:233], v160 offset:56320
	global_load_lds_dwordx4 v134, s[88:89]
	s_add_i32 m0, s44, 0x2000
	s_add_u32 s42, s42, 0x40080
	s_addc_u32 s43, s43, 0
	s_add_i32 s44, s67, s46
	global_load_lds_dwordx4 v130, s[88:89]
	s_mov_b32 m0, s44
	s_nop 0
	global_load_lds_dwordx4 v134, s[42:43]
	s_add_i32 m0, s44, 0x2000
	s_nop 0
	global_load_lds_dwordx4 v130, s[42:43]
	s_mov_b32 m0, s54
	s_nop 0
	global_load_lds_dwordx4 v136, s[90:91]
	s_mov_b32 m0, s55
	s_nop 0
	global_load_lds_dwordx4 v132, s[90:91]
	s_waitcnt vmcnt(8)
	s_waitcnt lgkmcnt(0)
	s_barrier
	s_setprio 1
	v_mfma_f32_16x16x32_bf16 v[62:65], v[168:171], v[202:205], v[62:65]
	v_mfma_f32_16x16x32_bf16 v[54:57], v[176:179], v[202:205], v[54:57]
	v_mfma_f32_16x16x32_bf16 v[46:49], v[168:171], v[210:213], v[46:49]
	v_mfma_f32_16x16x32_bf16 v[38:41], v[176:179], v[210:213], v[38:41]
	v_mfma_f32_16x16x32_bf16 v[30:33], v[168:171], v[218:221], v[30:33]
	v_mfma_f32_16x16x32_bf16 v[22:25], v[176:179], v[218:221], v[22:25]
	v_mfma_f32_16x16x32_bf16 v[14:17], v[168:171], v[226:229], v[14:17]
	v_mfma_f32_16x16x32_bf16 v[6:9], v[176:179], v[226:229], v[6:9]
	v_mfma_f32_16x16x32_bf16 v[62:65], v[172:175], v[206:209], v[62:65]
	v_mfma_f32_16x16x32_bf16 v[54:57], v[180:183], v[206:209], v[54:57]
	v_mfma_f32_16x16x32_bf16 v[46:49], v[172:175], v[214:217], v[46:49]
	v_mfma_f32_16x16x32_bf16 v[38:41], v[180:183], v[214:217], v[38:41]
	v_mfma_f32_16x16x32_bf16 v[30:33], v[172:175], v[222:225], v[30:33]
	v_mfma_f32_16x16x32_bf16 v[22:25], v[180:183], v[222:225], v[22:25]
	v_mfma_f32_16x16x32_bf16 v[14:17], v[172:175], v[230:233], v[14:17]
	v_mfma_f32_16x16x32_bf16 v[6:9], v[180:183], v[230:233], v[6:9]
	v_mfma_f32_16x16x32_bf16 v[58:61], v[186:189], v[202:205], v[58:61]
	v_mfma_f32_16x16x32_bf16 v[50:53], v[194:197], v[202:205], v[50:53]
	v_mfma_f32_16x16x32_bf16 v[42:45], v[186:189], v[210:213], v[42:45]
	v_mfma_f32_16x16x32_bf16 v[34:37], v[194:197], v[210:213], v[34:37]
	v_mfma_f32_16x16x32_bf16 v[26:29], v[186:189], v[218:221], v[26:29]
	v_mfma_f32_16x16x32_bf16 v[18:21], v[194:197], v[218:221], v[18:21]
	v_mfma_f32_16x16x32_bf16 v[10:13], v[186:189], v[226:229], v[10:13]
	v_mfma_f32_16x16x32_bf16 v[2:5], v[194:197], v[226:229], v[2:5]
	v_mfma_f32_16x16x32_bf16 v[58:61], v[190:193], v[206:209], v[58:61]
	v_mfma_f32_16x16x32_bf16 v[50:53], v[198:201], v[206:209], v[50:53]
	v_mfma_f32_16x16x32_bf16 v[42:45], v[190:193], v[214:217], v[42:45]
	v_mfma_f32_16x16x32_bf16 v[34:37], v[198:201], v[214:217], v[34:37]
	v_mfma_f32_16x16x32_bf16 v[26:29], v[190:193], v[222:225], v[26:29]
	v_mfma_f32_16x16x32_bf16 v[18:21], v[198:201], v[222:225], v[18:21]
	v_mfma_f32_16x16x32_bf16 v[10:13], v[190:193], v[230:233], v[10:13]
	v_mfma_f32_16x16x32_bf16 v[2:5], v[198:201], v[230:233], v[2:5]
	s_setprio 0
	s_barrier
	s_add_i32 s65, s65, 2
	s_add_u32 s40, s40, 0x100
	s_addc_u32 s41, s41, 0
	s_add_u32 s63, s63, 0x100
	s_addc_u32 s64, s64, 0
	s_cmp_gt_u32 s65, 13
	s_cbranch_scc0 .LBB0_179
	s_mov_b32 s99, 1
	s_and_b64 vcc, exec, s[18:19]
	s_cbranch_vccz .LBB0_182
	s_barrier

; #define PG8_STAGE(bufoff, gbase, voff) do { _Pragma("unroll") for (int _i = 0; _i < 2; ++_i) \
;         __builtin_amdgcn_global_load_lds((const unsigned*)((const char*)(gbase) + (voff)[_i]), (LAS unsigned*)(lds + (bufoff) + ldsw + _i * 8192), 16, 0, 0); } while (0)
; #define PG8_LDA(dst, b, h) do { _Pragma("unroll") for (int m = 0; m < 4; ++m) _Pragma("unroll") for (int k = 0; k < 2; ++k) dst[m][k] = *(const LAS bf16x8*)(lds + PG8_SA(b, h) + aoff + m * 2048 + k * 1024); } while (0)
; #define PG8_LDB(dst, b, h) do { _Pragma("unroll") for (int n = 0; n < 2; ++n) _Pragma("unroll") for (int k = 0; k < 2; ++k) dst[n][k] = *(const LAS bf16x8*)(lds + PG8_SB(b, h) + boff + n * 2048 + k * 1024); } while (0)
; #define PG8_MMA(ai, bj, At, Bt) do { __builtin_amdgcn_s_setprio(1); _Pragma("unroll") for (int m = 0; m < 4; ++m) _Pragma("unroll") for (int n = 0; n < 2; ++n) _Pragma("unroll") for (int k = 0; k < 2; ++k) \
;         acc[ai][bj][m][n] = __builtin_amdgcn_mfma_f32_16x16x32_bf16(Bt[n][k], At[m][k], acc[ai][bj][m][n], 0, 0, 0); __builtin_amdgcn_s_setprio(0); } while (0)
; #define PG8_WAIT_V(n) asm volatile("s_waitcnt vmcnt(" #n ")" ::: "memory")
; #define PG8_WAIT_L(n) asm volatile("s_waitcnt lgkmcnt(" #n ")" ::: "memory")
; #define PG8_BAR __builtin_amdgcn_s_barrier()
; #define PG8_SCHED __builtin_amdgcn_sched_barrier(0)
; template <class Epi, class Sched>
; DI void gemm_phase(LAS unsigned char* lds, const Gemm g, const Sched& S, const Epi& E) {
;     ...
;             PG8_LDB(B0, 0, 0); PG8_LDB(B1, 0, 1); PG8_SCHED; PG8_LDA(At, 0, 0); PG8_STAGE(PG8_SA(1, 1), a1 + hstepA, voffA);
;             PG8_WAIT_V(8); PG8_WAIT_L(0); PG8_BAR; PG8_MMA(0, 0, At, B0); PG8_MMA(0, 1, At, B1); PG8_BAR; PG8_SCHED;
;             PG8_LDA(At, 0, 1); PG8_STAGE(PG8_SB(0, 0), b2, voffB); PG8_STAGE(PG8_SB(0, 1), b2 + hstepB, voffB); PG8_STAGE(PG8_SA(0, 0), a2, voffA);
;             PG8_WAIT_V(8); PG8_WAIT_L(0); PG8_BAR; PG8_MMA(1, 0, At, B0); PG8_MMA(1, 1, At, B1); PG8_BAR; PG8_SCHED;
.Lpk1_w1:
	s_waitcnt lgkmcnt(0)
	s_barrier
	s_setprio 1
	v_mfma_f32_16x16x32_bf16 v[126:129], v[148:151], v[190:193], 0
	v_mfma_f32_16x16x32_bf16 v[122:125], v[162:165], v[190:193], 0
	v_mfma_f32_16x16x32_bf16 v[110:113], v[148:151], v[198:201], 0
	v_mfma_f32_16x16x32_bf16 v[106:109], v[162:165], v[198:201], 0
	v_mfma_f32_16x16x32_bf16 v[94:97], v[148:151], v[206:209], 0
	v_mfma_f32_16x16x32_bf16 v[90:93], v[162:165], v[206:209], 0
	v_mfma_f32_16x16x32_bf16 v[78:81], v[148:151], v[214:217], 0
	v_mfma_f32_16x16x32_bf16 v[74:77], v[162:165], v[214:217], 0
	v_mfma_f32_16x16x32_bf16 v[126:129], v[158:161], v[194:197], v[126:129]
	v_mfma_f32_16x16x32_bf16 v[122:125], v[166:169], v[194:197], v[122:125]
	v_mfma_f32_16x16x32_bf16 v[110:113], v[158:161], v[202:205], v[110:113]
	v_mfma_f32_16x16x32_bf16 v[106:109], v[166:169], v[202:205], v[106:109]
	v_mfma_f32_16x16x32_bf16 v[94:97], v[158:161], v[210:213], v[94:97]
	v_mfma_f32_16x16x32_bf16 v[90:93], v[166:169], v[210:213], v[90:93]
	v_mfma_f32_16x16x32_bf16 v[78:81], v[158:161], v[218:221], v[78:81]
	v_mfma_f32_16x16x32_bf16 v[74:77], v[166:169], v[218:221], v[74:77]
	v_mfma_f32_16x16x32_bf16 v[118:121], v[170:173], v[190:193], 0
	v_mfma_f32_16x16x32_bf16 v[114:117], v[178:181], v[190:193], 0
	v_mfma_f32_16x16x32_bf16 v[102:105], v[170:173], v[198:201], 0
	v_mfma_f32_16x16x32_bf16 v[98:101], v[178:181], v[198:201], 0
	v_mfma_f32_16x16x32_bf16 v[86:89], v[170:173], v[206:209], 0
	v_mfma_f32_16x16x32_bf16 v[82:85], v[178:181], v[206:209], 0
	v_mfma_f32_16x16x32_bf16 v[70:73], v[170:173], v[214:217], 0
	v_mfma_f32_16x16x32_bf16 v[66:69], v[178:181], v[214:217], 0
	v_mfma_f32_16x16x32_bf16 v[118:121], v[174:177], v[194:197], v[118:121]
	v_mfma_f32_16x16x32_bf16 v[114:117], v[186:189], v[194:197], v[114:117]
	v_mfma_f32_16x16x32_bf16 v[102:105], v[174:177], v[202:205], v[102:105]
	v_mfma_f32_16x16x32_bf16 v[98:101], v[186:189], v[202:205], v[98:101]
	v_mfma_f32_16x16x32_bf16 v[86:89], v[174:177], v[210:213], v[86:89]
	v_mfma_f32_16x16x32_bf16 v[82:85], v[186:189], v[210:213], v[82:85]
	v_mfma_f32_16x16x32_bf16 v[70:73], v[174:177], v[218:221], v[70:73]
	v_mfma_f32_16x16x32_bf16 v[66:69], v[186:189], v[218:221], v[66:69]
	s_setprio 0
	s_barrier
	s_add_u32 s88, s38, s16
	s_addc_u32 s89, s39, s17
	s_add_u32 s90, s40, s16
	s_addc_u32 s91, s41, s17
	s_add_i32 s63, s54, s44
	s_mov_b32 m0, s63
	ds_read_b128 v[190:193], v156 offset:16384
	ds_read_b128 v[194:197], v156 offset:17408
	ds_read_b128 v[198:201], v156 offset:18432
	ds_read_b128 v[202:205], v156 offset:19456
	ds_read_b128 v[206:209], v156 offset:20480
	ds_read_b128 v[210:213], v156 offset:21504
	ds_read_b128 v[214:217], v156 offset:22528
	ds_read_b128 v[218:221], v156 offset:23552
	global_load_lds_dwordx4 v132, s[38:39]
	s_add_i32 m0, s63, 0x2000
	s_add_u32 s64, s38, 0xb0000
	s_addc_u32 s65, s39, 0
	s_add_i32 s63, s55, s44
	global_load_lds_dwordx4 v136, s[38:39]
	s_mov_b32 m0, s63
	s_nop 0
	global_load_lds_dwordx4 v132, s[64:65]
	s_add_i32 m0, s63, 0x2000
	s_nop 0
	global_load_lds_dwordx4 v136, s[64:65]
	s_mov_b32 m0, s45
	s_nop 0
	global_load_lds_dwordx4 v130, s[40:41]
	s_mov_b32 m0, s46
	s_nop 0
	global_load_lds_dwordx4 v134, s[40:41]
	s_cmp_lg_u32 s99, 0
	s_cbranch_scc1 .Lpk1_w2
	s_waitcnt vmcnt(8)
.Lpk1_w2:
	s_mov_b32 s99, 0
	s_waitcnt lgkmcnt(0)
	s_barrier
	s_setprio 1
	v_mfma_f32_16x16x32_bf16 v[62:65], v[148:151], v[190:193], 0
	v_mfma_f32_16x16x32_bf16 v[58:61], v[162:165], v[190:193], 0
	v_mfma_f32_16x16x32_bf16 v[46:49], v[148:151], v[198:201], 0
	v_mfma_f32_16x16x32_bf16 v[42:45], v[162:165], v[198:201], 0
	v_mfma_f32_16x16x32_bf16 v[30:33], v[148:151], v[206:209], 0
	v_mfma_f32_16x16x32_bf16 v[26:29], v[162:165], v[206:209], 0
	v_mfma_f32_16x16x32_bf16 v[14:17], v[148:151], v[214:217], 0
	v_mfma_f32_16x16x32_bf16 v[10:13], v[162:165], v[214:217], 0
	v_mfma_f32_16x16x32_bf16 v[62:65], v[158:161], v[194:197], v[62:65]
	v_mfma_f32_16x16x32_bf16 v[58:61], v[166:169], v[194:197], v[58:61]
	v_mfma_f32_16x16x32_bf16 v[46:49], v[158:161], v[202:205], v[46:49]
	v_mfma_f32_16x16x32_bf16 v[42:45], v[166:169], v[202:205], v[42:45]
	v_mfma_f32_16x16x32_bf16 v[30:33], v[158:161], v[210:213], v[30:33]
	v_mfma_f32_16x16x32_bf16 v[26:29], v[166:169], v[210:213], v[26:29]
	v_mfma_f32_16x16x32_bf16 v[14:17], v[158:161], v[218:221], v[14:17]
	v_mfma_f32_16x16x32_bf16 v[10:13], v[166:169], v[218:221], v[10:13]
	v_mfma_f32_16x16x32_bf16 v[54:57], v[170:173], v[190:193], 0
	v_mfma_f32_16x16x32_bf16 v[50:53], v[178:181], v[190:193], 0
	v_mfma_f32_16x16x32_bf16 v[38:41], v[170:173], v[198:201], 0
	v_mfma_f32_16x16x32_bf16 v[34:37], v[178:181], v[198:201], 0
	v_mfma_f32_16x16x32_bf16 v[22:25], v[170:173], v[206:209], 0
	v_mfma_f32_16x16x32_bf16 v[18:21], v[178:181], v[206:209], 0
	v_mfma_f32_16x16x32_bf16 v[6:9], v[170:173], v[214:217], 0
	v_mfma_f32_16x16x32_bf16 v[2:5], v[178:181], v[214:217], 0
	v_mfma_f32_16x16x32_bf16 v[54:57], v[174:177], v[194:197], v[54:57]
	v_mfma_f32_16x16x32_bf16 v[50:53], v[186:189], v[194:197], v[50:53]
	v_mfma_f32_16x16x32_bf16 v[38:41], v[174:177], v[202:205], v[38:41]
	v_mfma_f32_16x16x32_bf16 v[34:37], v[186:189], v[202:205], v[34:37]
	v_mfma_f32_16x16x32_bf16 v[22:25], v[174:177], v[210:213], v[22:25]
	v_mfma_f32_16x16x32_bf16 v[18:21], v[186:189], v[210:213], v[18:21]
	v_mfma_f32_16x16x32_bf16 v[6:9], v[174:177], v[218:221], v[6:9]
	v_mfma_f32_16x16x32_bf16 v[2:5], v[186:189], v[218:221], v[2:5]
	s_setprio 0
	s_barrier
; #define PG8_STAGE(bufoff, gbase, voff) do { _Pragma("unroll") for (int _i = 0; _i < 2; ++_i) \
;         __builtin_amdgcn_global_load_lds((const unsigned*)((const char*)(gbase) + (voff)[_i]), (LAS unsigned*)(lds + (bufoff) + ldsw + _i * 8192), 16, 0, 0); } while (0)
; #define PG8_LDA(dst, b, h) do { _Pragma("unroll") for (int m = 0; m < 4; ++m) _Pragma("unroll") for (int k = 0; k < 2; ++k) dst[m][k] = *(const LAS bf16x8*)(lds + PG8_SA(b, h) + aoff + m * 2048 + k * 1024); } while (0)
; #define PG8_LDB(dst, b, h) do { _Pragma("unroll") for (int n = 0; n < 2; ++n) _Pragma("unroll") for (int k = 0; k < 2; ++k) dst[n][k] = *(const LAS bf16x8*)(lds + PG8_SB(b, h) + boff + n * 2048 + k * 1024); } while (0)
; #define PG8_MMA(ai, bj, At, Bt) do { __builtin_amdgcn_s_setprio(1); _Pragma("unroll") for (int m = 0; m < 4; ++m) _Pragma("unroll") for (int n = 0; n < 2; ++n) _Pragma("unroll") for (int k = 0; k < 2; ++k) \
;         acc[ai][bj][m][n] = __builtin_amdgcn_mfma_f32_16x16x32_bf16(Bt[n][k], At[m][k], acc[ai][bj][m][n], 0, 0, 0); __builtin_amdgcn_s_setprio(0); } while (0)
; #define PG8_WAIT_V(n) asm volatile("s_waitcnt vmcnt(" #n ")" ::: "memory")
; #define PG8_WAIT_L(n) asm volatile("s_waitcnt lgkmcnt(" #n ")" ::: "memory")
; #define PG8_BAR __builtin_amdgcn_s_barrier()
; #define PG8_SCHED __builtin_amdgcn_sched_barrier(0)
; template <class Epi, class Sched>
; DI void gemm_phase(LAS unsigned char* lds, const Gemm g, const Sched& S, const Epi& E) {
;     ...
;             PG8_LDB(B0, 1, 0); PG8_LDB(B1, 1, 1); PG8_SCHED; PG8_LDA(At, 1, 0); PG8_STAGE(PG8_SA(0, 1), a2 + hstepA, voffA);
;             PG8_WAIT_V(8); PG8_WAIT_L(0); PG8_BAR; PG8_MMA(0, 0, At, B0); PG8_MMA(0, 1, At, B1); PG8_BAR; PG8_SCHED;
;             PG8_LDA(At, 1, 1); PG8_STAGE(PG8_SB(1, 0), b3, voffB); PG8_STAGE(PG8_SB(1, 1), b3 + hstepB, voffB); PG8_STAGE(PG8_SA(1, 0), a3, voffA);
;             PG8_WAIT_V(8); PG8_WAIT_L(0); PG8_BAR; PG8_MMA(1, 0, At, B0); PG8_MMA(1, 1, At, B1); PG8_BAR; PG8_SCHED;
;         }
	s_add_i32 s63, 0, 0x18000
	s_add_i32 s64, 0, 0x1c000
	v_add_u32_e32 v166, s63, v152
	v_add_u32_e32 v185, s64, v152
	ds_read_b128 v[148:151], v166
	ds_read_b128 v[158:161], v166 offset:1024
	ds_read_b128 v[162:165], v166 offset:2048
	ds_read_b128 v[166:169], v166 offset:3072
	ds_read_b128 v[170:173], v185
	ds_read_b128 v[174:177], v185 offset:1024
	ds_read_b128 v[178:181], v185 offset:2048
	ds_read_b128 v[186:189], v185 offset:3072
	s_add_u32 s40, s40, 0xb0000
	s_addc_u32 s41, s41, 0
	s_mov_b32 m0, s47
	ds_read_b128 v[190:193], v156 offset:32768
	ds_read_b128 v[194:197], v156 offset:33792
	ds_read_b128 v[198:201], v156 offset:34816
	ds_read_b128 v[202:205], v156 offset:35840
	ds_read_b128 v[206:209], v156 offset:36864
	ds_read_b128 v[210:213], v156 offset:37888
	ds_read_b128 v[214:217], v156 offset:38912
	ds_read_b128 v[218:221], v156 offset:39936
	global_load_lds_dwordx4 v130, s[40:41]
	s_mov_b32 m0, s48
	s_nop 0
	global_load_lds_dwordx4 v134, s[40:41]
	s_waitcnt vmcnt(8)
	s_waitcnt lgkmcnt(0)
	s_barrier
	s_setprio 1
	v_mfma_f32_16x16x32_bf16 v[126:129], v[148:151], v[190:193], v[126:129]
	v_mfma_f32_16x16x32_bf16 v[122:125], v[162:165], v[190:193], v[122:125]
	v_mfma_f32_16x16x32_bf16 v[110:113], v[148:151], v[198:201], v[110:113]
	v_mfma_f32_16x16x32_bf16 v[106:109], v[162:165], v[198:201], v[106:109]
	v_mfma_f32_16x16x32_bf16 v[94:97], v[148:151], v[206:209], v[94:97]
	v_mfma_f32_16x16x32_bf16 v[90:93], v[162:165], v[206:209], v[90:93]
	v_mfma_f32_16x16x32_bf16 v[78:81], v[148:151], v[214:217], v[78:81]
	v_mfma_f32_16x16x32_bf16 v[74:77], v[162:165], v[214:217], v[74:77]
	v_mfma_f32_16x16x32_bf16 v[126:129], v[158:161], v[194:197], v[126:129]
	v_mfma_f32_16x16x32_bf16 v[122:125], v[166:169], v[194:197], v[122:125]
	v_mfma_f32_16x16x32_bf16 v[110:113], v[158:161], v[202:205], v[110:113]
	v_mfma_f32_16x16x32_bf16 v[106:109], v[166:169], v[202:205], v[106:109]
	v_mfma_f32_16x16x32_bf16 v[94:97], v[158:161], v[210:213], v[94:97]
	v_mfma_f32_16x16x32_bf16 v[90:93], v[166:169], v[210:213], v[90:93]
	v_mfma_f32_16x16x32_bf16 v[78:81], v[158:161], v[218:221], v[78:81]
	v_mfma_f32_16x16x32_bf16 v[74:77], v[166:169], v[218:221], v[74:77]
	v_mfma_f32_16x16x32_bf16 v[118:121], v[170:173], v[190:193], v[118:121]
	v_mfma_f32_16x16x32_bf16 v[114:117], v[178:181], v[190:193], v[114:117]
	v_mfma_f32_16x16x32_bf16 v[102:105], v[170:173], v[198:201], v[102:105]
	v_mfma_f32_16x16x32_bf16 v[98:101], v[178:181], v[198:201], v[98:101]
	v_mfma_f32_16x16x32_bf16 v[86:89], v[170:173], v[206:209], v[86:89]
	v_mfma_f32_16x16x32_bf16 v[82:85], v[178:181], v[206:209], v[82:85]
	v_mfma_f32_16x16x32_bf16 v[70:73], v[170:173], v[214:217], v[70:73]
	v_mfma_f32_16x16x32_bf16 v[66:69], v[178:181], v[214:217], v[66:69]
	v_mfma_f32_16x16x32_bf16 v[118:121], v[174:177], v[194:197], v[118:121]
	v_mfma_f32_16x16x32_bf16 v[114:117], v[186:189], v[194:197], v[114:117]
	v_mfma_f32_16x16x32_bf16 v[102:105], v[174:177], v[202:205], v[102:105]
	v_mfma_f32_16x16x32_bf16 v[98:101], v[186:189], v[202:205], v[98:101]
	v_mfma_f32_16x16x32_bf16 v[86:89], v[174:177], v[210:213], v[86:89]
	v_mfma_f32_16x16x32_bf16 v[82:85], v[186:189], v[210:213], v[82:85]
	v_mfma_f32_16x16x32_bf16 v[70:73], v[174:177], v[218:221], v[70:73]
	v_mfma_f32_16x16x32_bf16 v[66:69], v[186:189], v[218:221], v[66:69]
	s_setprio 0
	s_barrier
	s_add_i32 s40, s63, s44
	s_mov_b32 m0, s40
	ds_read_b128 v[190:193], v156 offset:49152
	ds_read_b128 v[194:197], v156 offset:50176
	ds_read_b128 v[198:201], v156 offset:51200
	ds_read_b128 v[202:205], v156 offset:52224
	ds_read_b128 v[206:209], v156 offset:53248
	ds_read_b128 v[210:213], v156 offset:54272
	ds_read_b128 v[214:217], v156 offset:55296
	ds_read_b128 v[218:221], v156 offset:56320
	global_load_lds_dwordx4 v132, s[88:89]
	s_add_i32 m0, s40, 0x2000
	s_add_u32 s38, s38, 0xb0080
	s_addc_u32 s39, s39, 0
	s_add_i32 s40, s64, s44
	global_load_lds_dwordx4 v136, s[88:89]
	s_mov_b32 m0, s40
	s_nop 0
	global_load_lds_dwordx4 v132, s[38:39]
	s_add_i32 m0, s40, 0x2000
	s_nop 0
	global_load_lds_dwordx4 v136, s[38:39]
	s_mov_b32 m0, s50
	s_nop 0
	global_load_lds_dwordx4 v130, s[90:91]
	s_mov_b32 m0, s51
	s_nop 0
	global_load_lds_dwordx4 v134, s[90:91]
	s_waitcnt vmcnt(8)
	s_waitcnt lgkmcnt(0)
	s_barrier
	s_setprio 1
	v_mfma_f32_16x16x32_bf16 v[62:65], v[148:151], v[190:193], v[62:65]
	v_mfma_f32_16x16x32_bf16 v[58:61], v[162:165], v[190:193], v[58:61]
	v_mfma_f32_16x16x32_bf16 v[46:49], v[148:151], v[198:201], v[46:49]
	v_mfma_f32_16x16x32_bf16 v[42:45], v[162:165], v[198:201], v[42:45]
	v_mfma_f32_16x16x32_bf16 v[30:33], v[148:151], v[206:209], v[30:33]
	v_mfma_f32_16x16x32_bf16 v[26:29], v[162:165], v[206:209], v[26:29]
	v_mfma_f32_16x16x32_bf16 v[14:17], v[148:151], v[214:217], v[14:17]
	v_mfma_f32_16x16x32_bf16 v[10:13], v[162:165], v[214:217], v[10:13]
	v_mfma_f32_16x16x32_bf16 v[62:65], v[158:161], v[194:197], v[62:65]
	v_mfma_f32_16x16x32_bf16 v[58:61], v[166:169], v[194:197], v[58:61]
	v_mfma_f32_16x16x32_bf16 v[46:49], v[158:161], v[202:205], v[46:49]
	v_mfma_f32_16x16x32_bf16 v[42:45], v[166:169], v[202:205], v[42:45]
	v_mfma_f32_16x16x32_bf16 v[30:33], v[158:161], v[210:213], v[30:33]
	v_mfma_f32_16x16x32_bf16 v[26:29], v[166:169], v[210:213], v[26:29]
	v_mfma_f32_16x16x32_bf16 v[14:17], v[158:161], v[218:221], v[14:17]
	v_mfma_f32_16x16x32_bf16 v[10:13], v[166:169], v[218:221], v[10:13]
	v_mfma_f32_16x16x32_bf16 v[54:57], v[170:173], v[190:193], v[54:57]
	v_mfma_f32_16x16x32_bf16 v[50:53], v[178:181], v[190:193], v[50:53]
	v_mfma_f32_16x16x32_bf16 v[38:41], v[170:173], v[198:201], v[38:41]
	v_mfma_f32_16x16x32_bf16 v[34:37], v[178:181], v[198:201], v[34:37]
	v_mfma_f32_16x16x32_bf16 v[22:25], v[170:173], v[206:209], v[22:25]
	v_mfma_f32_16x16x32_bf16 v[18:21], v[178:181], v[206:209], v[18:21]
	v_mfma_f32_16x16x32_bf16 v[6:9], v[170:173], v[214:217], v[6:9]
	v_mfma_f32_16x16x32_bf16 v[2:5], v[178:181], v[214:217], v[2:5]
	v_mfma_f32_16x16x32_bf16 v[54:57], v[174:177], v[194:197], v[54:57]
	v_mfma_f32_16x16x32_bf16 v[50:53], v[186:189], v[194:197], v[50:53]
	v_mfma_f32_16x16x32_bf16 v[38:41], v[174:177], v[202:205], v[38:41]
	v_mfma_f32_16x16x32_bf16 v[34:37], v[186:189], v[202:205], v[34:37]
	v_mfma_f32_16x16x32_bf16 v[22:25], v[174:177], v[210:213], v[22:25]
	v_mfma_f32_16x16x32_bf16 v[18:21], v[186:189], v[210:213], v[18:21]
	v_mfma_f32_16x16x32_bf16 v[6:9], v[174:177], v[218:221], v[6:9]
	v_mfma_f32_16x16x32_bf16 v[2:5], v[186:189], v[218:221], v[2:5]
	s_setprio 0
	s_barrier
	s_add_i32 s62, s62, 2
	s_add_u32 s36, s36, 0x100
	s_addc_u32 s37, s37, 0
	s_add_u32 s60, s60, 0x100
	s_addc_u32 s61, s61, 0
	s_cmp_gt_u32 s62, 41
; #define PG8_STAGE(bufoff, gbase, voff) do { _Pragma("unroll") for (int _i = 0; _i < 2; ++_i) \
;         __builtin_amdgcn_global_load_lds((const unsigned*)((const char*)(gbase) + (voff)[_i]), (LAS unsigned*)(lds + (bufoff) + ldsw + _i * 8192), 16, 0, 0); } while (0)
; #define PG8_LDA(dst, b, h) do { _Pragma("unroll") for (int m = 0; m < 4; ++m) _Pragma("unroll") for (int k = 0; k < 2; ++k) dst[m][k] = *(const LAS bf16x8*)(lds + PG8_SA(b, h) + aoff + m * 2048 + k * 1024); } while (0)
; #define PG8_LDB(dst, b, h) do { _Pragma("unroll") for (int n = 0; n < 2; ++n) _Pragma("unroll") for (int k = 0; k < 2; ++k) dst[n][k] = *(const LAS bf16x8*)(lds + PG8_SB(b, h) + boff + n * 2048 + k * 1024); } while (0)
; #define PG8_MMA(ai, bj, At, Bt) do { __builtin_amdgcn_s_setprio(1); _Pragma("unroll") for (int m = 0; m < 4; ++m) _Pragma("unroll") for (int n = 0; n < 2; ++n) _Pragma("unroll") for (int k = 0; k < 2; ++k) \
;         acc[ai][bj][m][n] = __builtin_amdgcn_mfma_f32_16x16x32_bf16(Bt[n][k], At[m][k], acc[ai][bj][m][n], 0, 0, 0); __builtin_amdgcn_s_setprio(0); } while (0)
; #define PG8_WAIT_V(n) asm volatile("s_waitcnt vmcnt(" #n ")" ::: "memory")
; #define PG8_WAIT_L(n) asm volatile("s_waitcnt lgkmcnt(" #n ")" ::: "memory")
; #define PG8_BAR __builtin_amdgcn_s_barrier()
; #define PG8_SCHED __builtin_amdgcn_sched_barrier(0)
; template <class Epi, class Sched>
; DI void gemm_phase(LAS unsigned char* lds, const Gemm g, const Sched& S, const Epi& E) {
;     ...
;             PG8_LDB(B0, 0, 0); PG8_LDB(B1, 0, 1); PG8_SCHED; PG8_LDA(At, 0, 0); PG8_STAGE(PG8_SA(1, 1), a1 + hstepA, voffA);
;             PG8_WAIT_V(8); PG8_WAIT_L(0); PG8_BAR; PG8_MMA(0, 0, At, B0); PG8_MMA(0, 1, At, B1); PG8_BAR; PG8_SCHED;
;             PG8_LDA(At, 0, 1); PG8_STAGE(PG8_SB(0, 0), b2, voffB); PG8_STAGE(PG8_SB(0, 1), b2 + hstepB, voffB); PG8_STAGE(PG8_SA(0, 0), a2, voffA);
;             PG8_WAIT_V(8); PG8_WAIT_L(0); PG8_BAR; PG8_MMA(1, 0, At, B0); PG8_MMA(1, 1, At, B1); PG8_BAR; PG8_SCHED;
.LBB0_278:
	ds_read_b128 v[148:151], v154
	ds_read_b128 v[158:161], v154 offset:1024
	ds_read_b128 v[162:165], v154 offset:2048
	ds_read_b128 v[166:169], v154 offset:3072
	ds_read_b128 v[170:173], v155
	ds_read_b128 v[174:177], v155 offset:1024
	ds_read_b128 v[178:181], v155 offset:2048
	ds_read_b128 v[186:189], v155 offset:3072
	s_add_u32 s38, s36, 0xfff50080
	s_addc_u32 s39, s37, -1
	s_cmp_eq_u32 s62, 40
	s_cselect_b32 s41, s9, s39
	s_cselect_b32 s40, s8, s38
	s_cselect_b32 s39, s35, s61
	s_cselect_b32 s38, s34, s60
	s_add_i32 m0, s45, 0xc000
	ds_read_b128 v[190:193], v156
	ds_read_b128 v[194:197], v156 offset:1024
	ds_read_b128 v[198:201], v156 offset:2048
	ds_read_b128 v[202:205], v156 offset:3072
	ds_read_b128 v[206:209], v156 offset:4096
	ds_read_b128 v[210:213], v156 offset:5120
	ds_read_b128 v[214:217], v156 offset:6144
	ds_read_b128 v[218:221], v156 offset:7168
	global_load_lds_dwordx4 v138, s[36:37]
	s_add_i32 m0, s45, 0xe000
	s_nop 0
	global_load_lds_dwordx4 v140, s[36:37]
	s_waitcnt vmcnt(8)
	s_waitcnt lgkmcnt(0)
	s_barrier
	s_setprio 1
	v_mfma_f32_16x16x32_bf16 v[126:129], v[148:151], v[190:193], v[126:129]
	v_mfma_f32_16x16x32_bf16 v[122:125], v[162:165], v[190:193], v[122:125]
	v_mfma_f32_16x16x32_bf16 v[110:113], v[148:151], v[198:201], v[110:113]
	v_mfma_f32_16x16x32_bf16 v[106:109], v[162:165], v[198:201], v[106:109]
	v_mfma_f32_16x16x32_bf16 v[94:97], v[148:151], v[206:209], v[94:97]
	v_mfma_f32_16x16x32_bf16 v[90:93], v[162:165], v[206:209], v[90:93]
	v_mfma_f32_16x16x32_bf16 v[78:81], v[148:151], v[214:217], v[78:81]
	v_mfma_f32_16x16x32_bf16 v[74:77], v[162:165], v[214:217], v[74:77]
	v_mfma_f32_16x16x32_bf16 v[126:129], v[158:161], v[194:197], v[126:129]
	v_mfma_f32_16x16x32_bf16 v[122:125], v[166:169], v[194:197], v[122:125]
	v_mfma_f32_16x16x32_bf16 v[110:113], v[158:161], v[202:205], v[110:113]
	v_mfma_f32_16x16x32_bf16 v[106:109], v[166:169], v[202:205], v[106:109]
	v_mfma_f32_16x16x32_bf16 v[94:97], v[158:161], v[210:213], v[94:97]
	v_mfma_f32_16x16x32_bf16 v[90:93], v[166:169], v[210:213], v[90:93]
	v_mfma_f32_16x16x32_bf16 v[78:81], v[158:161], v[218:221], v[78:81]
	v_mfma_f32_16x16x32_bf16 v[74:77], v[166:169], v[218:221], v[74:77]
	v_mfma_f32_16x16x32_bf16 v[118:121], v[170:173], v[190:193], v[118:121]
	v_mfma_f32_16x16x32_bf16 v[114:117], v[178:181], v[190:193], v[114:117]
	v_mfma_f32_16x16x32_bf16 v[102:105], v[170:173], v[198:201], v[102:105]
	v_mfma_f32_16x16x32_bf16 v[98:101], v[178:181], v[198:201], v[98:101]
	v_mfma_f32_16x16x32_bf16 v[86:89], v[170:173], v[206:209], v[86:89]
	v_mfma_f32_16x16x32_bf16 v[82:85], v[178:181], v[206:209], v[82:85]
	v_mfma_f32_16x16x32_bf16 v[70:73], v[170:173], v[214:217], v[70:73]
	v_mfma_f32_16x16x32_bf16 v[66:69], v[178:181], v[214:217], v[66:69]
	v_mfma_f32_16x16x32_bf16 v[118:121], v[174:177], v[194:197], v[118:121]
	v_mfma_f32_16x16x32_bf16 v[114:117], v[186:189], v[194:197], v[114:117]
	v_mfma_f32_16x16x32_bf16 v[102:105], v[174:177], v[202:205], v[102:105]
	v_mfma_f32_16x16x32_bf16 v[98:101], v[186:189], v[202:205], v[98:101]
	v_mfma_f32_16x16x32_bf16 v[86:89], v[174:177], v[210:213], v[86:89]
	v_mfma_f32_16x16x32_bf16 v[82:85], v[186:189], v[210:213], v[82:85]
	v_mfma_f32_16x16x32_bf16 v[70:73], v[174:177], v[218:221], v[70:73]
	v_mfma_f32_16x16x32_bf16 v[66:69], v[186:189], v[218:221], v[66:69]
	s_setprio 0
	s_barrier
	s_add_u32 s88, s38, s16
	s_addc_u32 s89, s39, s17
	s_add_u32 s90, s40, s16
	s_addc_u32 s91, s41, s17
	s_add_i32 s63, s54, s44
	s_mov_b32 m0, s63
	ds_read_b128 v[190:193], v156 offset:16384
	ds_read_b128 v[194:197], v156 offset:17408
	ds_read_b128 v[198:201], v156 offset:18432
	ds_read_b128 v[202:205], v156 offset:19456
	ds_read_b128 v[206:209], v156 offset:20480
	ds_read_b128 v[210:213], v156 offset:21504
	ds_read_b128 v[214:217], v156 offset:22528
	ds_read_b128 v[218:221], v156 offset:23552
	global_load_lds_dwordx4 v132, s[38:39]
	s_add_i32 m0, s63, 0x2000
	s_add_u32 s64, s38, 0xb0000
	s_addc_u32 s65, s39, 0
	s_add_i32 s63, s55, s44
	global_load_lds_dwordx4 v136, s[38:39]
	s_mov_b32 m0, s63
	s_nop 0
	global_load_lds_dwordx4 v132, s[64:65]
	s_add_i32 m0, s63, 0x2000
	s_nop 0
	global_load_lds_dwordx4 v136, s[64:65]
	s_mov_b32 m0, s45
	s_nop 0
	global_load_lds_dwordx4 v130, s[40:41]
	s_mov_b32 m0, s46
	s_nop 0
	global_load_lds_dwordx4 v134, s[40:41]
	s_waitcnt vmcnt(8)
	s_waitcnt lgkmcnt(0)
	s_barrier
	s_setprio 1
	v_mfma_f32_16x16x32_bf16 v[62:65], v[148:151], v[190:193], v[62:65]
	v_mfma_f32_16x16x32_bf16 v[58:61], v[162:165], v[190:193], v[58:61]
	v_mfma_f32_16x16x32_bf16 v[46:49], v[148:151], v[198:201], v[46:49]
	v_mfma_f32_16x16x32_bf16 v[42:45], v[162:165], v[198:201], v[42:45]
	v_mfma_f32_16x16x32_bf16 v[30:33], v[148:151], v[206:209], v[30:33]
	v_mfma_f32_16x16x32_bf16 v[26:29], v[162:165], v[206:209], v[26:29]
	v_mfma_f32_16x16x32_bf16 v[14:17], v[148:151], v[214:217], v[14:17]
	v_mfma_f32_16x16x32_bf16 v[10:13], v[162:165], v[214:217], v[10:13]
	v_mfma_f32_16x16x32_bf16 v[62:65], v[158:161], v[194:197], v[62:65]
	v_mfma_f32_16x16x32_bf16 v[58:61], v[166:169], v[194:197], v[58:61]
	v_mfma_f32_16x16x32_bf16 v[46:49], v[158:161], v[202:205], v[46:49]
	v_mfma_f32_16x16x32_bf16 v[42:45], v[166:169], v[202:205], v[42:45]
	v_mfma_f32_16x16x32_bf16 v[30:33], v[158:161], v[210:213], v[30:33]
	v_mfma_f32_16x16x32_bf16 v[26:29], v[166:169], v[210:213], v[26:29]
	v_mfma_f32_16x16x32_bf16 v[14:17], v[158:161], v[218:221], v[14:17]
	v_mfma_f32_16x16x32_bf16 v[10:13], v[166:169], v[218:221], v[10:13]
	v_mfma_f32_16x16x32_bf16 v[54:57], v[170:173], v[190:193], v[54:57]
	v_mfma_f32_16x16x32_bf16 v[50:53], v[178:181], v[190:193], v[50:53]
	v_mfma_f32_16x16x32_bf16 v[38:41], v[170:173], v[198:201], v[38:41]
	v_mfma_f32_16x16x32_bf16 v[34:37], v[178:181], v[198:201], v[34:37]
	v_mfma_f32_16x16x32_bf16 v[22:25], v[170:173], v[206:209], v[22:25]
	v_mfma_f32_16x16x32_bf16 v[18:21], v[178:181], v[206:209], v[18:21]
	v_mfma_f32_16x16x32_bf16 v[6:9], v[170:173], v[214:217], v[6:9]
	v_mfma_f32_16x16x32_bf16 v[2:5], v[178:181], v[214:217], v[2:5]
	v_mfma_f32_16x16x32_bf16 v[54:57], v[174:177], v[194:197], v[54:57]
	v_mfma_f32_16x16x32_bf16 v[50:53], v[186:189], v[194:197], v[50:53]
	v_mfma_f32_16x16x32_bf16 v[38:41], v[174:177], v[202:205], v[38:41]
	v_mfma_f32_16x16x32_bf16 v[34:37], v[186:189], v[202:205], v[34:37]
	v_mfma_f32_16x16x32_bf16 v[22:25], v[174:177], v[210:213], v[22:25]
	v_mfma_f32_16x16x32_bf16 v[18:21], v[186:189], v[210:213], v[18:21]
	v_mfma_f32_16x16x32_bf16 v[6:9], v[174:177], v[218:221], v[6:9]
	v_mfma_f32_16x16x32_bf16 v[2:5], v[186:189], v[218:221], v[2:5]
	s_setprio 0
	s_barrier
; #define PG8_STAGE(bufoff, gbase, voff) do { _Pragma("unroll") for (int _i = 0; _i < 2; ++_i) \
;         __builtin_amdgcn_global_load_lds((const unsigned*)((const char*)(gbase) + (voff)[_i]), (LAS unsigned*)(lds + (bufoff) + ldsw + _i * 8192), 16, 0, 0); } while (0)
; #define PG8_LDA(dst, b, h) do { _Pragma("unroll") for (int m = 0; m < 4; ++m) _Pragma("unroll") for (int k = 0; k < 2; ++k) dst[m][k] = *(const LAS bf16x8*)(lds + PG8_SA(b, h) + aoff + m * 2048 + k * 1024); } while (0)
; #define PG8_LDB(dst, b, h) do { _Pragma("unroll") for (int n = 0; n < 2; ++n) _Pragma("unroll") for (int k = 0; k < 2; ++k) dst[n][k] = *(const LAS bf16x8*)(lds + PG8_SB(b, h) + boff + n * 2048 + k * 1024); } while (0)
; #define PG8_MMA(ai, bj, At, Bt) do { __builtin_amdgcn_s_setprio(1); _Pragma("unroll") for (int m = 0; m < 4; ++m) _Pragma("unroll") for (int n = 0; n < 2; ++n) _Pragma("unroll") for (int k = 0; k < 2; ++k) \
;         acc[ai][bj][m][n] = __builtin_amdgcn_mfma_f32_16x16x32_bf16(Bt[n][k], At[m][k], acc[ai][bj][m][n], 0, 0, 0); __builtin_amdgcn_s_setprio(0); } while (0)
; #define PG8_WAIT_V(n) asm volatile("s_waitcnt vmcnt(" #n ")" ::: "memory")
; #define PG8_WAIT_L(n) asm volatile("s_waitcnt lgkmcnt(" #n ")" ::: "memory")
; #define PG8_BAR __builtin_amdgcn_s_barrier()
; #define PG8_SCHED __builtin_amdgcn_sched_barrier(0)
; template <class Epi, class Sched>
; DI void gemm_phase(LAS unsigned char* lds, const Gemm g, const Sched& S, const Epi& E) {
;     ...
;             PG8_LDB(B0, 1, 0); PG8_LDB(B1, 1, 1); PG8_SCHED; PG8_LDA(At, 1, 0); PG8_STAGE(PG8_SA(0, 1), a2 + hstepA, voffA);
;             PG8_WAIT_V(8); PG8_WAIT_L(0); PG8_BAR; PG8_MMA(0, 0, At, B0); PG8_MMA(0, 1, At, B1); PG8_BAR; PG8_SCHED;
;             PG8_LDA(At, 1, 1); PG8_STAGE(PG8_SB(1, 0), b3, voffB); PG8_STAGE(PG8_SB(1, 1), b3 + hstepB, voffB); PG8_STAGE(PG8_SA(1, 0), a3, voffA);
;             PG8_WAIT_V(8); PG8_WAIT_L(0); PG8_BAR; PG8_MMA(1, 0, At, B0); PG8_MMA(1, 1, At, B1); PG8_BAR; PG8_SCHED;
;         }
;         if (wr == 0) PG8_BAR;
	s_add_i32 s63, 0, 0x18000
	s_add_i32 s64, 0, 0x1c000
	v_add_u32_e32 v166, s63, v152
	v_add_u32_e32 v185, s64, v152
	ds_read_b128 v[148:151], v166
	ds_read_b128 v[158:161], v166 offset:1024
	ds_read_b128 v[162:165], v166 offset:2048
	ds_read_b128 v[166:169], v166 offset:3072
	ds_read_b128 v[170:173], v185
	ds_read_b128 v[174:177], v185 offset:1024
	ds_read_b128 v[178:181], v185 offset:2048
	ds_read_b128 v[186:189], v185 offset:3072
	s_add_u32 s40, s40, 0xb0000
	s_addc_u32 s41, s41, 0
	s_mov_b32 m0, s47
	ds_read_b128 v[190:193], v156 offset:32768
	ds_read_b128 v[194:197], v156 offset:33792
	ds_read_b128 v[198:201], v156 offset:34816
	ds_read_b128 v[202:205], v156 offset:35840
	ds_read_b128 v[206:209], v156 offset:36864
	ds_read_b128 v[210:213], v156 offset:37888
	ds_read_b128 v[214:217], v156 offset:38912
	ds_read_b128 v[218:221], v156 offset:39936
	global_load_lds_dwordx4 v130, s[40:41]
	s_mov_b32 m0, s48
	s_nop 0
	global_load_lds_dwordx4 v134, s[40:41]
	s_waitcnt vmcnt(8)
	s_waitcnt lgkmcnt(0)
	s_barrier
	s_setprio 1
	v_mfma_f32_16x16x32_bf16 v[126:129], v[148:151], v[190:193], v[126:129]
	v_mfma_f32_16x16x32_bf16 v[122:125], v[162:165], v[190:193], v[122:125]
	v_mfma_f32_16x16x32_bf16 v[110:113], v[148:151], v[198:201], v[110:113]
	v_mfma_f32_16x16x32_bf16 v[106:109], v[162:165], v[198:201], v[106:109]
	v_mfma_f32_16x16x32_bf16 v[94:97], v[148:151], v[206:209], v[94:97]
	v_mfma_f32_16x16x32_bf16 v[90:93], v[162:165], v[206:209], v[90:93]
	v_mfma_f32_16x16x32_bf16 v[78:81], v[148:151], v[214:217], v[78:81]
	v_mfma_f32_16x16x32_bf16 v[74:77], v[162:165], v[214:217], v[74:77]
	v_mfma_f32_16x16x32_bf16 v[126:129], v[158:161], v[194:197], v[126:129]
	v_mfma_f32_16x16x32_bf16 v[122:125], v[166:169], v[194:197], v[122:125]
	v_mfma_f32_16x16x32_bf16 v[110:113], v[158:161], v[202:205], v[110:113]
	v_mfma_f32_16x16x32_bf16 v[106:109], v[166:169], v[202:205], v[106:109]
	v_mfma_f32_16x16x32_bf16 v[94:97], v[158:161], v[210:213], v[94:97]
	v_mfma_f32_16x16x32_bf16 v[90:93], v[166:169], v[210:213], v[90:93]
	v_mfma_f32_16x16x32_bf16 v[78:81], v[158:161], v[218:221], v[78:81]
	v_mfma_f32_16x16x32_bf16 v[74:77], v[166:169], v[218:221], v[74:77]
	v_mfma_f32_16x16x32_bf16 v[118:121], v[170:173], v[190:193], v[118:121]
	v_mfma_f32_16x16x32_bf16 v[114:117], v[178:181], v[190:193], v[114:117]
	v_mfma_f32_16x16x32_bf16 v[102:105], v[170:173], v[198:201], v[102:105]
	v_mfma_f32_16x16x32_bf16 v[98:101], v[178:181], v[198:201], v[98:101]
	v_mfma_f32_16x16x32_bf16 v[86:89], v[170:173], v[206:209], v[86:89]
	v_mfma_f32_16x16x32_bf16 v[82:85], v[178:181], v[206:209], v[82:85]
	v_mfma_f32_16x16x32_bf16 v[70:73], v[170:173], v[214:217], v[70:73]
	v_mfma_f32_16x16x32_bf16 v[66:69], v[178:181], v[214:217], v[66:69]
	v_mfma_f32_16x16x32_bf16 v[118:121], v[174:177], v[194:197], v[118:121]
	v_mfma_f32_16x16x32_bf16 v[114:117], v[186:189], v[194:197], v[114:117]
	v_mfma_f32_16x16x32_bf16 v[102:105], v[174:177], v[202:205], v[102:105]
	v_mfma_f32_16x16x32_bf16 v[98:101], v[186:189], v[202:205], v[98:101]
	v_mfma_f32_16x16x32_bf16 v[86:89], v[174:177], v[210:213], v[86:89]
	v_mfma_f32_16x16x32_bf16 v[82:85], v[186:189], v[210:213], v[82:85]
	v_mfma_f32_16x16x32_bf16 v[70:73], v[174:177], v[218:221], v[70:73]
	v_mfma_f32_16x16x32_bf16 v[66:69], v[186:189], v[218:221], v[66:69]
	s_setprio 0
	s_barrier
	s_add_i32 s40, s63, s44
	s_mov_b32 m0, s40
	ds_read_b128 v[190:193], v156 offset:49152
	ds_read_b128 v[194:197], v156 offset:50176
	ds_read_b128 v[198:201], v156 offset:51200
	ds_read_b128 v[202:205], v156 offset:52224
	ds_read_b128 v[206:209], v156 offset:53248
	ds_read_b128 v[210:213], v156 offset:54272
	ds_read_b128 v[214:217], v156 offset:55296
	ds_read_b128 v[218:221], v156 offset:56320
	global_load_lds_dwordx4 v132, s[88:89]
	s_add_i32 m0, s40, 0x2000
	s_add_u32 s38, s38, 0xb0080
	s_addc_u32 s39, s39, 0
	s_add_i32 s40, s64, s44
	global_load_lds_dwordx4 v136, s[88:89]
	s_mov_b32 m0, s40
	s_nop 0
	global_load_lds_dwordx4 v132, s[38:39]
	s_add_i32 m0, s40, 0x2000
	s_nop 0
	global_load_lds_dwordx4 v136, s[38:39]
	s_mov_b32 m0, s50
	s_nop 0
	global_load_lds_dwordx4 v130, s[90:91]
	s_mov_b32 m0, s51
	s_nop 0
	global_load_lds_dwordx4 v134, s[90:91]
	s_waitcnt vmcnt(8)
	s_waitcnt lgkmcnt(0)
	s_barrier
	s_setprio 1
	v_mfma_f32_16x16x32_bf16 v[62:65], v[148:151], v[190:193], v[62:65]
	v_mfma_f32_16x16x32_bf16 v[58:61], v[162:165], v[190:193], v[58:61]
	v_mfma_f32_16x16x32_bf16 v[46:49], v[148:151], v[198:201], v[46:49]
	v_mfma_f32_16x16x32_bf16 v[42:45], v[162:165], v[198:201], v[42:45]
	v_mfma_f32_16x16x32_bf16 v[30:33], v[148:151], v[206:209], v[30:33]
	v_mfma_f32_16x16x32_bf16 v[26:29], v[162:165], v[206:209], v[26:29]
	v_mfma_f32_16x16x32_bf16 v[14:17], v[148:151], v[214:217], v[14:17]
	v_mfma_f32_16x16x32_bf16 v[10:13], v[162:165], v[214:217], v[10:13]
	v_mfma_f32_16x16x32_bf16 v[62:65], v[158:161], v[194:197], v[62:65]
	v_mfma_f32_16x16x32_bf16 v[58:61], v[166:169], v[194:197], v[58:61]
	v_mfma_f32_16x16x32_bf16 v[46:49], v[158:161], v[202:205], v[46:49]
	v_mfma_f32_16x16x32_bf16 v[42:45], v[166:169], v[202:205], v[42:45]
	v_mfma_f32_16x16x32_bf16 v[30:33], v[158:161], v[210:213], v[30:33]
	v_mfma_f32_16x16x32_bf16 v[26:29], v[166:169], v[210:213], v[26:29]
	v_mfma_f32_16x16x32_bf16 v[14:17], v[158:161], v[218:221], v[14:17]
	v_mfma_f32_16x16x32_bf16 v[10:13], v[166:169], v[218:221], v[10:13]
	v_mfma_f32_16x16x32_bf16 v[54:57], v[170:173], v[190:193], v[54:57]
	v_mfma_f32_16x16x32_bf16 v[50:53], v[178:181], v[190:193], v[50:53]
	v_mfma_f32_16x16x32_bf16 v[38:41], v[170:173], v[198:201], v[38:41]
	v_mfma_f32_16x16x32_bf16 v[34:37], v[178:181], v[198:201], v[34:37]
	v_mfma_f32_16x16x32_bf16 v[22:25], v[170:173], v[206:209], v[22:25]
	v_mfma_f32_16x16x32_bf16 v[18:21], v[178:181], v[206:209], v[18:21]
	v_mfma_f32_16x16x32_bf16 v[6:9], v[170:173], v[214:217], v[6:9]
	v_mfma_f32_16x16x32_bf16 v[2:5], v[178:181], v[214:217], v[2:5]
	v_mfma_f32_16x16x32_bf16 v[54:57], v[174:177], v[194:197], v[54:57]
	v_mfma_f32_16x16x32_bf16 v[50:53], v[186:189], v[194:197], v[50:53]
	v_mfma_f32_16x16x32_bf16 v[38:41], v[174:177], v[202:205], v[38:41]
	v_mfma_f32_16x16x32_bf16 v[34:37], v[186:189], v[202:205], v[34:37]
	v_mfma_f32_16x16x32_bf16 v[22:25], v[174:177], v[210:213], v[22:25]
	v_mfma_f32_16x16x32_bf16 v[18:21], v[186:189], v[210:213], v[18:21]
	v_mfma_f32_16x16x32_bf16 v[6:9], v[174:177], v[218:221], v[6:9]
	v_mfma_f32_16x16x32_bf16 v[2:5], v[186:189], v[218:221], v[2:5]
	s_setprio 0
	s_barrier
	s_add_i32 s62, s62, 2
	s_add_u32 s36, s36, 0x100
	s_addc_u32 s37, s37, 0
	s_add_u32 s60, s60, 0x100
	s_addc_u32 s61, s61, 0
	s_cmp_gt_u32 s62, 41
	s_cbranch_scc0 .LBB0_278
	s_mov_b32 s99, 1
	s_and_b64 vcc, exec, s[18:19]
	s_cbranch_vccz .LBB0_281
	s_barrier

; #define PG8_STAGE(bufoff, gbase, voff) do { _Pragma("unroll") for (int _i = 0; _i < 2; ++_i) \
;         __builtin_amdgcn_global_load_lds((const unsigned*)((const char*)(gbase) + (voff)[_i]), (LAS unsigned*)(lds + (bufoff) + ldsw + _i * 8192), 16, 0, 0); } while (0)
; #define PG8_LDA(dst, b, h) do { _Pragma("unroll") for (int m = 0; m < 4; ++m) _Pragma("unroll") for (int k = 0; k < 2; ++k) dst[m][k] = *(const LAS bf16x8*)(lds + PG8_SA(b, h) + aoff + m * 2048 + k * 1024); } while (0)
; #define PG8_LDB(dst, b, h) do { _Pragma("unroll") for (int n = 0; n < 2; ++n) _Pragma("unroll") for (int k = 0; k < 2; ++k) dst[n][k] = *(const LAS bf16x8*)(lds + PG8_SB(b, h) + boff + n * 2048 + k * 1024); } while (0)
; #define PG8_MMA(ai, bj, At, Bt) do { __builtin_amdgcn_s_setprio(1); _Pragma("unroll") for (int m = 0; m < 4; ++m) _Pragma("unroll") for (int n = 0; n < 2; ++n) _Pragma("unroll") for (int k = 0; k < 2; ++k) \
;         acc[ai][bj][m][n] = __builtin_amdgcn_mfma_f32_16x16x32_bf16(Bt[n][k], At[m][k], acc[ai][bj][m][n], 0, 0, 0); __builtin_amdgcn_s_setprio(0); } while (0)
; #define PG8_WAIT_V(n) asm volatile("s_waitcnt vmcnt(" #n ")" ::: "memory")
; #define PG8_WAIT_L(n) asm volatile("s_waitcnt lgkmcnt(" #n ")" ::: "memory")
; #define PG8_BAR __builtin_amdgcn_s_barrier()
; #define PG8_SCHED __builtin_amdgcn_sched_barrier(0)
; template <class Epi, class Sched>
; DI void gemm_phase(LAS unsigned char* lds, const Gemm g, const Sched& S, const Epi& E) {
;     ...
;             PG8_LDB(B0, 0, 0); PG8_LDB(B1, 0, 1); PG8_SCHED; PG8_LDA(At, 0, 0); PG8_STAGE(PG8_SA(1, 1), a1 + hstepA, voffA);
;             PG8_WAIT_V(8); PG8_WAIT_L(0); PG8_BAR; PG8_MMA(0, 0, At, B0); PG8_MMA(0, 1, At, B1); PG8_BAR; PG8_SCHED;
;             PG8_LDA(At, 0, 1); PG8_STAGE(PG8_SB(0, 0), b2, voffB); PG8_STAGE(PG8_SB(0, 1), b2 + hstepB, voffB); PG8_STAGE(PG8_SA(0, 0), a2, voffA);
;             PG8_WAIT_V(8); PG8_WAIT_L(0); PG8_BAR; PG8_MMA(1, 0, At, B0); PG8_MMA(1, 1, At, B1); PG8_BAR; PG8_SCHED;
.Lpk4_w1:
	s_waitcnt lgkmcnt(0)
	s_barrier
	s_setprio 1
	v_mfma_f32_16x16x32_bf16 v[126:129], v[146:149], v[186:189], 0
	v_mfma_f32_16x16x32_bf16 v[122:125], v[160:163], v[186:189], 0
	v_mfma_f32_16x16x32_bf16 v[110:113], v[146:149], v[194:197], 0
	v_mfma_f32_16x16x32_bf16 v[106:109], v[160:163], v[194:197], 0
	v_mfma_f32_16x16x32_bf16 v[94:97], v[146:149], v[202:205], 0
	v_mfma_f32_16x16x32_bf16 v[90:93], v[160:163], v[202:205], 0
	v_mfma_f32_16x16x32_bf16 v[78:81], v[146:149], v[210:213], 0
	v_mfma_f32_16x16x32_bf16 v[74:77], v[160:163], v[210:213], 0
	v_mfma_f32_16x16x32_bf16 v[126:129], v[156:159], v[190:193], v[126:129]
	v_mfma_f32_16x16x32_bf16 v[122:125], v[164:167], v[190:193], v[122:125]
	v_mfma_f32_16x16x32_bf16 v[110:113], v[156:159], v[198:201], v[110:113]
	v_mfma_f32_16x16x32_bf16 v[106:109], v[164:167], v[198:201], v[106:109]
	v_mfma_f32_16x16x32_bf16 v[94:97], v[156:159], v[206:209], v[94:97]
	v_mfma_f32_16x16x32_bf16 v[90:93], v[164:167], v[206:209], v[90:93]
	v_mfma_f32_16x16x32_bf16 v[78:81], v[156:159], v[214:217], v[78:81]
	v_mfma_f32_16x16x32_bf16 v[74:77], v[164:167], v[214:217], v[74:77]
	v_mfma_f32_16x16x32_bf16 v[118:121], v[168:171], v[186:189], 0
	v_mfma_f32_16x16x32_bf16 v[114:117], v[176:179], v[186:189], 0
	v_mfma_f32_16x16x32_bf16 v[102:105], v[168:171], v[194:197], 0
	v_mfma_f32_16x16x32_bf16 v[98:101], v[176:179], v[194:197], 0
	v_mfma_f32_16x16x32_bf16 v[86:89], v[168:171], v[202:205], 0
	v_mfma_f32_16x16x32_bf16 v[82:85], v[176:179], v[202:205], 0
	v_mfma_f32_16x16x32_bf16 v[70:73], v[168:171], v[210:213], 0
	v_mfma_f32_16x16x32_bf16 v[66:69], v[176:179], v[210:213], 0
	v_mfma_f32_16x16x32_bf16 v[118:121], v[172:175], v[190:193], v[118:121]
	v_mfma_f32_16x16x32_bf16 v[114:117], v[180:183], v[190:193], v[114:117]
	v_mfma_f32_16x16x32_bf16 v[102:105], v[172:175], v[198:201], v[102:105]
	v_mfma_f32_16x16x32_bf16 v[98:101], v[180:183], v[198:201], v[98:101]
	v_mfma_f32_16x16x32_bf16 v[86:89], v[172:175], v[206:209], v[86:89]
	v_mfma_f32_16x16x32_bf16 v[82:85], v[180:183], v[206:209], v[82:85]
	v_mfma_f32_16x16x32_bf16 v[70:73], v[172:175], v[214:217], v[70:73]
	v_mfma_f32_16x16x32_bf16 v[66:69], v[180:183], v[214:217], v[66:69]
	s_setprio 0
	s_barrier
	s_add_u32 s88, s46, s16
	s_addc_u32 s89, s47, s17
	s_add_u32 s90, s48, s16
	s_addc_u32 s91, s49, s17
	s_add_i32 s67, s61, s52
	s_mov_b32 m0, s67
	ds_read_b128 v[186:189], v154 offset:16384
	ds_read_b128 v[190:193], v154 offset:17408
	ds_read_b128 v[194:197], v154 offset:18432
	ds_read_b128 v[198:201], v154 offset:19456
	ds_read_b128 v[202:205], v154 offset:20480
	ds_read_b128 v[206:209], v154 offset:21504
	ds_read_b128 v[210:213], v154 offset:22528
	ds_read_b128 v[214:217], v154 offset:23552
	global_load_lds_dwordx4 v132, s[46:47]
	s_add_i32 m0, s67, 0x2000
	s_add_u32 s68, s46, 0x40000
	s_addc_u32 s69, s47, 0
	s_add_i32 s67, s62, s52
	global_load_lds_dwordx4 v136, s[46:47]
	s_mov_b32 m0, s67
	s_nop 0
	global_load_lds_dwordx4 v132, s[68:69]
	s_add_i32 m0, s67, 0x2000
	s_nop 0
	global_load_lds_dwordx4 v136, s[68:69]
	s_mov_b32 m0, s43
	s_nop 0
	global_load_lds_dwordx4 v130, s[48:49]
	s_mov_b32 m0, s53
	s_nop 0
	global_load_lds_dwordx4 v134, s[48:49]
	s_cmp_lg_u32 s99, 0
	s_cbranch_scc1 .Lpk4_w2
	s_waitcnt vmcnt(8)
.Lpk4_w2:
	s_mov_b32 s99, 0
	s_waitcnt lgkmcnt(0)
	s_barrier
	s_setprio 1
	v_mfma_f32_16x16x32_bf16 v[62:65], v[146:149], v[186:189], 0
	v_mfma_f32_16x16x32_bf16 v[58:61], v[160:163], v[186:189], 0
	v_mfma_f32_16x16x32_bf16 v[46:49], v[146:149], v[194:197], 0
	v_mfma_f32_16x16x32_bf16 v[42:45], v[160:163], v[194:197], 0
	v_mfma_f32_16x16x32_bf16 v[30:33], v[146:149], v[202:205], 0
	v_mfma_f32_16x16x32_bf16 v[26:29], v[160:163], v[202:205], 0
	v_mfma_f32_16x16x32_bf16 v[14:17], v[146:149], v[210:213], 0
	v_mfma_f32_16x16x32_bf16 v[10:13], v[160:163], v[210:213], 0
	v_mfma_f32_16x16x32_bf16 v[62:65], v[156:159], v[190:193], v[62:65]
	v_mfma_f32_16x16x32_bf16 v[58:61], v[164:167], v[190:193], v[58:61]
	v_mfma_f32_16x16x32_bf16 v[46:49], v[156:159], v[198:201], v[46:49]
	v_mfma_f32_16x16x32_bf16 v[42:45], v[164:167], v[198:201], v[42:45]
	v_mfma_f32_16x16x32_bf16 v[30:33], v[156:159], v[206:209], v[30:33]
	v_mfma_f32_16x16x32_bf16 v[26:29], v[164:167], v[206:209], v[26:29]
	v_mfma_f32_16x16x32_bf16 v[14:17], v[156:159], v[214:217], v[14:17]
	v_mfma_f32_16x16x32_bf16 v[10:13], v[164:167], v[214:217], v[10:13]
	v_mfma_f32_16x16x32_bf16 v[54:57], v[168:171], v[186:189], 0
	v_mfma_f32_16x16x32_bf16 v[50:53], v[176:179], v[186:189], 0
	v_mfma_f32_16x16x32_bf16 v[38:41], v[168:171], v[194:197], 0
	v_mfma_f32_16x16x32_bf16 v[34:37], v[176:179], v[194:197], 0
	v_mfma_f32_16x16x32_bf16 v[22:25], v[168:171], v[202:205], 0
	v_mfma_f32_16x16x32_bf16 v[18:21], v[176:179], v[202:205], 0
	v_mfma_f32_16x16x32_bf16 v[6:9], v[168:171], v[210:213], 0
	v_mfma_f32_16x16x32_bf16 v[2:5], v[176:179], v[210:213], 0
	v_mfma_f32_16x16x32_bf16 v[54:57], v[172:175], v[190:193], v[54:57]
	v_mfma_f32_16x16x32_bf16 v[50:53], v[180:183], v[190:193], v[50:53]
	v_mfma_f32_16x16x32_bf16 v[38:41], v[172:175], v[198:201], v[38:41]
	v_mfma_f32_16x16x32_bf16 v[34:37], v[180:183], v[198:201], v[34:37]
	v_mfma_f32_16x16x32_bf16 v[22:25], v[172:175], v[206:209], v[22:25]
	v_mfma_f32_16x16x32_bf16 v[18:21], v[180:183], v[206:209], v[18:21]
	v_mfma_f32_16x16x32_bf16 v[6:9], v[172:175], v[214:217], v[6:9]
	v_mfma_f32_16x16x32_bf16 v[2:5], v[180:183], v[214:217], v[2:5]
	s_setprio 0
	s_barrier
; #define PG8_STAGE(bufoff, gbase, voff) do { _Pragma("unroll") for (int _i = 0; _i < 2; ++_i) \
;         __builtin_amdgcn_global_load_lds((const unsigned*)((const char*)(gbase) + (voff)[_i]), (LAS unsigned*)(lds + (bufoff) + ldsw + _i * 8192), 16, 0, 0); } while (0)
; #define PG8_LDA(dst, b, h) do { _Pragma("unroll") for (int m = 0; m < 4; ++m) _Pragma("unroll") for (int k = 0; k < 2; ++k) dst[m][k] = *(const LAS bf16x8*)(lds + PG8_SA(b, h) + aoff + m * 2048 + k * 1024); } while (0)
; #define PG8_LDB(dst, b, h) do { _Pragma("unroll") for (int n = 0; n < 2; ++n) _Pragma("unroll") for (int k = 0; k < 2; ++k) dst[n][k] = *(const LAS bf16x8*)(lds + PG8_SB(b, h) + boff + n * 2048 + k * 1024); } while (0)
; #define PG8_MMA(ai, bj, At, Bt) do { __builtin_amdgcn_s_setprio(1); _Pragma("unroll") for (int m = 0; m < 4; ++m) _Pragma("unroll") for (int n = 0; n < 2; ++n) _Pragma("unroll") for (int k = 0; k < 2; ++k) \
;         acc[ai][bj][m][n] = __builtin_amdgcn_mfma_f32_16x16x32_bf16(Bt[n][k], At[m][k], acc[ai][bj][m][n], 0, 0, 0); __builtin_amdgcn_s_setprio(0); } while (0)
; #define PG8_WAIT_V(n) asm volatile("s_waitcnt vmcnt(" #n ")" ::: "memory")
; #define PG8_WAIT_L(n) asm volatile("s_waitcnt lgkmcnt(" #n ")" ::: "memory")
; #define PG8_BAR __builtin_amdgcn_s_barrier()
; #define PG8_SCHED __builtin_amdgcn_sched_barrier(0)
; template <class Epi, class Sched>
; DI void gemm_phase(LAS unsigned char* lds, const Gemm g, const Sched& S, const Epi& E) {
;     ...
;             PG8_LDB(B0, 1, 0); PG8_LDB(B1, 1, 1); PG8_SCHED; PG8_LDA(At, 1, 0); PG8_STAGE(PG8_SA(0, 1), a2 + hstepA, voffA);
;             PG8_WAIT_V(8); PG8_WAIT_L(0); PG8_BAR; PG8_MMA(0, 0, At, B0); PG8_MMA(0, 1, At, B1); PG8_BAR; PG8_SCHED;
;             PG8_LDA(At, 1, 1); PG8_STAGE(PG8_SB(1, 0), b3, voffB); PG8_STAGE(PG8_SB(1, 1), b3 + hstepB, voffB); PG8_STAGE(PG8_SA(1, 0), a3, voffA);
;             PG8_WAIT_V(8); PG8_WAIT_L(0); PG8_BAR; PG8_MMA(1, 0, At, B0); PG8_MMA(1, 1, At, B1); PG8_BAR; PG8_SCHED;
;         }
	s_add_i32 s67, 0, 0x18000
	s_add_i32 s68, 0, 0x1c000
	v_add_u32_e32 v164, s67, v150
	v_add_u32_e32 v180, s68, v150
	ds_read_b128 v[146:149], v164
	ds_read_b128 v[156:159], v164 offset:1024
	ds_read_b128 v[160:163], v164 offset:2048
	ds_read_b128 v[164:167], v164 offset:3072
	ds_read_b128 v[168:171], v180
	ds_read_b128 v[172:175], v180 offset:1024
	ds_read_b128 v[176:179], v180 offset:2048
	ds_read_b128 v[180:183], v180 offset:3072
	s_add_u32 s48, s48, 0x40000
	s_addc_u32 s49, s49, 0
	s_mov_b32 m0, s54
	ds_read_b128 v[186:189], v154 offset:32768
	ds_read_b128 v[190:193], v154 offset:33792
	ds_read_b128 v[194:197], v154 offset:34816
	ds_read_b128 v[198:201], v154 offset:35840
	ds_read_b128 v[202:205], v154 offset:36864
	ds_read_b128 v[206:209], v154 offset:37888
	ds_read_b128 v[210:213], v154 offset:38912
	ds_read_b128 v[214:217], v154 offset:39936
	global_load_lds_dwordx4 v130, s[48:49]
	s_mov_b32 m0, s55
	s_nop 0
	global_load_lds_dwordx4 v134, s[48:49]
	s_waitcnt vmcnt(8)
	s_waitcnt lgkmcnt(0)
	s_barrier
	s_setprio 1
	v_mfma_f32_16x16x32_bf16 v[126:129], v[146:149], v[186:189], v[126:129]
	v_mfma_f32_16x16x32_bf16 v[122:125], v[160:163], v[186:189], v[122:125]
	v_mfma_f32_16x16x32_bf16 v[110:113], v[146:149], v[194:197], v[110:113]
	v_mfma_f32_16x16x32_bf16 v[106:109], v[160:163], v[194:197], v[106:109]
	v_mfma_f32_16x16x32_bf16 v[94:97], v[146:149], v[202:205], v[94:97]
	v_mfma_f32_16x16x32_bf16 v[90:93], v[160:163], v[202:205], v[90:93]
	v_mfma_f32_16x16x32_bf16 v[78:81], v[146:149], v[210:213], v[78:81]
	v_mfma_f32_16x16x32_bf16 v[74:77], v[160:163], v[210:213], v[74:77]
	v_mfma_f32_16x16x32_bf16 v[126:129], v[156:159], v[190:193], v[126:129]
	v_mfma_f32_16x16x32_bf16 v[122:125], v[164:167], v[190:193], v[122:125]
	v_mfma_f32_16x16x32_bf16 v[110:113], v[156:159], v[198:201], v[110:113]
	v_mfma_f32_16x16x32_bf16 v[106:109], v[164:167], v[198:201], v[106:109]
	v_mfma_f32_16x16x32_bf16 v[94:97], v[156:159], v[206:209], v[94:97]
	v_mfma_f32_16x16x32_bf16 v[90:93], v[164:167], v[206:209], v[90:93]
	v_mfma_f32_16x16x32_bf16 v[78:81], v[156:159], v[214:217], v[78:81]
	v_mfma_f32_16x16x32_bf16 v[74:77], v[164:167], v[214:217], v[74:77]
	v_mfma_f32_16x16x32_bf16 v[118:121], v[168:171], v[186:189], v[118:121]
	v_mfma_f32_16x16x32_bf16 v[114:117], v[176:179], v[186:189], v[114:117]
	v_mfma_f32_16x16x32_bf16 v[102:105], v[168:171], v[194:197], v[102:105]
	v_mfma_f32_16x16x32_bf16 v[98:101], v[176:179], v[194:197], v[98:101]
	v_mfma_f32_16x16x32_bf16 v[86:89], v[168:171], v[202:205], v[86:89]
	v_mfma_f32_16x16x32_bf16 v[82:85], v[176:179], v[202:205], v[82:85]
	v_mfma_f32_16x16x32_bf16 v[70:73], v[168:171], v[210:213], v[70:73]
	v_mfma_f32_16x16x32_bf16 v[66:69], v[176:179], v[210:213], v[66:69]
	v_mfma_f32_16x16x32_bf16 v[118:121], v[172:175], v[190:193], v[118:121]
	v_mfma_f32_16x16x32_bf16 v[114:117], v[180:183], v[190:193], v[114:117]
	v_mfma_f32_16x16x32_bf16 v[102:105], v[172:175], v[198:201], v[102:105]
	v_mfma_f32_16x16x32_bf16 v[98:101], v[180:183], v[198:201], v[98:101]
	v_mfma_f32_16x16x32_bf16 v[86:89], v[172:175], v[206:209], v[86:89]
	v_mfma_f32_16x16x32_bf16 v[82:85], v[180:183], v[206:209], v[82:85]
	v_mfma_f32_16x16x32_bf16 v[70:73], v[172:175], v[214:217], v[70:73]
	v_mfma_f32_16x16x32_bf16 v[66:69], v[180:183], v[214:217], v[66:69]
	s_setprio 0
	s_barrier
	s_add_i32 s48, s67, s52
	s_mov_b32 m0, s48
	ds_read_b128 v[186:189], v154 offset:49152
	ds_read_b128 v[190:193], v154 offset:50176
	ds_read_b128 v[194:197], v154 offset:51200
	ds_read_b128 v[198:201], v154 offset:52224
	ds_read_b128 v[202:205], v154 offset:53248
	ds_read_b128 v[206:209], v154 offset:54272
	ds_read_b128 v[210:213], v154 offset:55296
	ds_read_b128 v[214:217], v154 offset:56320
	global_load_lds_dwordx4 v132, s[88:89]
	s_add_i32 m0, s48, 0x2000
	s_add_u32 s46, s46, 0x40080
	s_addc_u32 s47, s47, 0
	s_add_i32 s48, s68, s52
	global_load_lds_dwordx4 v136, s[88:89]
	s_mov_b32 m0, s48
	s_nop 0
	global_load_lds_dwordx4 v132, s[46:47]
	s_add_i32 m0, s48, 0x2000
	s_nop 0
	global_load_lds_dwordx4 v136, s[46:47]
	s_mov_b32 m0, s57
	s_nop 0
	global_load_lds_dwordx4 v130, s[90:91]
	s_mov_b32 m0, s58
	s_nop 0
	global_load_lds_dwordx4 v134, s[90:91]
	s_waitcnt vmcnt(8)
	s_waitcnt lgkmcnt(0)
	s_barrier
	s_setprio 1
	v_mfma_f32_16x16x32_bf16 v[62:65], v[146:149], v[186:189], v[62:65]
	v_mfma_f32_16x16x32_bf16 v[58:61], v[160:163], v[186:189], v[58:61]
	v_mfma_f32_16x16x32_bf16 v[46:49], v[146:149], v[194:197], v[46:49]
	v_mfma_f32_16x16x32_bf16 v[42:45], v[160:163], v[194:197], v[42:45]
	v_mfma_f32_16x16x32_bf16 v[30:33], v[146:149], v[202:205], v[30:33]
	v_mfma_f32_16x16x32_bf16 v[26:29], v[160:163], v[202:205], v[26:29]
	v_mfma_f32_16x16x32_bf16 v[14:17], v[146:149], v[210:213], v[14:17]
	v_mfma_f32_16x16x32_bf16 v[10:13], v[160:163], v[210:213], v[10:13]
	v_mfma_f32_16x16x32_bf16 v[62:65], v[156:159], v[190:193], v[62:65]
	v_mfma_f32_16x16x32_bf16 v[58:61], v[164:167], v[190:193], v[58:61]
	v_mfma_f32_16x16x32_bf16 v[46:49], v[156:159], v[198:201], v[46:49]
	v_mfma_f32_16x16x32_bf16 v[42:45], v[164:167], v[198:201], v[42:45]
	v_mfma_f32_16x16x32_bf16 v[30:33], v[156:159], v[206:209], v[30:33]
	v_mfma_f32_16x16x32_bf16 v[26:29], v[164:167], v[206:209], v[26:29]
	v_mfma_f32_16x16x32_bf16 v[14:17], v[156:159], v[214:217], v[14:17]
	v_mfma_f32_16x16x32_bf16 v[10:13], v[164:167], v[214:217], v[10:13]
	v_mfma_f32_16x16x32_bf16 v[54:57], v[168:171], v[186:189], v[54:57]
	v_mfma_f32_16x16x32_bf16 v[50:53], v[176:179], v[186:189], v[50:53]
	v_mfma_f32_16x16x32_bf16 v[38:41], v[168:171], v[194:197], v[38:41]
	v_mfma_f32_16x16x32_bf16 v[34:37], v[176:179], v[194:197], v[34:37]
	v_mfma_f32_16x16x32_bf16 v[22:25], v[168:171], v[202:205], v[22:25]
	v_mfma_f32_16x16x32_bf16 v[18:21], v[176:179], v[202:205], v[18:21]
	v_mfma_f32_16x16x32_bf16 v[6:9], v[168:171], v[210:213], v[6:9]
	v_mfma_f32_16x16x32_bf16 v[2:5], v[176:179], v[210:213], v[2:5]
	v_mfma_f32_16x16x32_bf16 v[54:57], v[172:175], v[190:193], v[54:57]
	v_mfma_f32_16x16x32_bf16 v[50:53], v[180:183], v[190:193], v[50:53]
	v_mfma_f32_16x16x32_bf16 v[38:41], v[172:175], v[198:201], v[38:41]
	v_mfma_f32_16x16x32_bf16 v[34:37], v[180:183], v[198:201], v[34:37]
	v_mfma_f32_16x16x32_bf16 v[22:25], v[172:175], v[206:209], v[22:25]
	v_mfma_f32_16x16x32_bf16 v[18:21], v[180:183], v[206:209], v[18:21]
	v_mfma_f32_16x16x32_bf16 v[6:9], v[172:175], v[214:217], v[6:9]
	v_mfma_f32_16x16x32_bf16 v[2:5], v[180:183], v[214:217], v[2:5]
	s_setprio 0
	s_barrier
	s_add_i32 s66, s66, 2
	s_add_u32 s44, s44, 0x100
	s_addc_u32 s45, s45, 0
	s_add_u32 s64, s64, 0x100
	s_addc_u32 s65, s65, 0
	s_cmp_gt_u32 s66, 13
; #define PG8_STAGE(bufoff, gbase, voff) do { _Pragma("unroll") for (int _i = 0; _i < 2; ++_i) \
;         __builtin_amdgcn_global_load_lds((const unsigned*)((const char*)(gbase) + (voff)[_i]), (LAS unsigned*)(lds + (bufoff) + ldsw + _i * 8192), 16, 0, 0); } while (0)
; #define PG8_LDA(dst, b, h) do { _Pragma("unroll") for (int m = 0; m < 4; ++m) _Pragma("unroll") for (int k = 0; k < 2; ++k) dst[m][k] = *(const LAS bf16x8*)(lds + PG8_SA(b, h) + aoff + m * 2048 + k * 1024); } while (0)
; #define PG8_LDB(dst, b, h) do { _Pragma("unroll") for (int n = 0; n < 2; ++n) _Pragma("unroll") for (int k = 0; k < 2; ++k) dst[n][k] = *(const LAS bf16x8*)(lds + PG8_SB(b, h) + boff + n * 2048 + k * 1024); } while (0)
; #define PG8_MMA(ai, bj, At, Bt) do { __builtin_amdgcn_s_setprio(1); _Pragma("unroll") for (int m = 0; m < 4; ++m) _Pragma("unroll") for (int n = 0; n < 2; ++n) _Pragma("unroll") for (int k = 0; k < 2; ++k) \
;         acc[ai][bj][m][n] = __builtin_amdgcn_mfma_f32_16x16x32_bf16(Bt[n][k], At[m][k], acc[ai][bj][m][n], 0, 0, 0); __builtin_amdgcn_s_setprio(0); } while (0)
; #define PG8_WAIT_V(n) asm volatile("s_waitcnt vmcnt(" #n ")" ::: "memory")
; #define PG8_WAIT_L(n) asm volatile("s_waitcnt lgkmcnt(" #n ")" ::: "memory")
; #define PG8_BAR __builtin_amdgcn_s_barrier()
; #define PG8_SCHED __builtin_amdgcn_sched_barrier(0)
; template <class Epi, class Sched>
; DI void gemm_phase(LAS unsigned char* lds, const Gemm g, const Sched& S, const Epi& E) {
;     ...
;             PG8_LDB(B0, 0, 0); PG8_LDB(B1, 0, 1); PG8_SCHED; PG8_LDA(At, 0, 0); PG8_STAGE(PG8_SA(1, 1), a1 + hstepA, voffA);
;             PG8_WAIT_V(8); PG8_WAIT_L(0); PG8_BAR; PG8_MMA(0, 0, At, B0); PG8_MMA(0, 1, At, B1); PG8_BAR; PG8_SCHED;
;             PG8_LDA(At, 0, 1); PG8_STAGE(PG8_SB(0, 0), b2, voffB); PG8_STAGE(PG8_SB(0, 1), b2 + hstepB, voffB); PG8_STAGE(PG8_SA(0, 0), a2, voffA);
;             PG8_WAIT_V(8); PG8_WAIT_L(0); PG8_BAR; PG8_MMA(1, 0, At, B0); PG8_MMA(1, 1, At, B1); PG8_BAR; PG8_SCHED;
.LBB0_1133:
	ds_read_b128 v[146:149], v152
	ds_read_b128 v[156:159], v152 offset:1024
	ds_read_b128 v[160:163], v152 offset:2048
	ds_read_b128 v[164:167], v152 offset:3072
	ds_read_b128 v[168:171], v153
	ds_read_b128 v[172:175], v153 offset:1024
	ds_read_b128 v[176:179], v153 offset:2048
	ds_read_b128 v[180:183], v153 offset:3072
	s_add_u32 s46, s44, 0xfffc0080
	s_addc_u32 s47, s45, -1
	s_cmp_eq_u32 s66, 12
	s_cselect_b32 s49, s35, s47
	s_cselect_b32 s48, s41, s46
	s_cselect_b32 s47, s21, s65
	s_cselect_b32 s46, s63, s64
	s_add_i32 m0, s43, 0xc000
	ds_read_b128 v[186:189], v154
	ds_read_b128 v[190:193], v154 offset:1024
	ds_read_b128 v[194:197], v154 offset:2048
	ds_read_b128 v[198:201], v154 offset:3072
	ds_read_b128 v[202:205], v154 offset:4096
	ds_read_b128 v[206:209], v154 offset:5120
	ds_read_b128 v[210:213], v154 offset:6144
	ds_read_b128 v[214:217], v154 offset:7168
	global_load_lds_dwordx4 v138, s[44:45]
	s_add_i32 m0, s43, 0xe000
	s_nop 0
	global_load_lds_dwordx4 v140, s[44:45]
	s_waitcnt vmcnt(8)
	s_waitcnt lgkmcnt(0)
	s_barrier
	s_setprio 1
	v_mfma_f32_16x16x32_bf16 v[126:129], v[146:149], v[186:189], v[126:129]
	v_mfma_f32_16x16x32_bf16 v[122:125], v[160:163], v[186:189], v[122:125]
	v_mfma_f32_16x16x32_bf16 v[110:113], v[146:149], v[194:197], v[110:113]
	v_mfma_f32_16x16x32_bf16 v[106:109], v[160:163], v[194:197], v[106:109]
	v_mfma_f32_16x16x32_bf16 v[94:97], v[146:149], v[202:205], v[94:97]
	v_mfma_f32_16x16x32_bf16 v[90:93], v[160:163], v[202:205], v[90:93]
	v_mfma_f32_16x16x32_bf16 v[78:81], v[146:149], v[210:213], v[78:81]
	v_mfma_f32_16x16x32_bf16 v[74:77], v[160:163], v[210:213], v[74:77]
	v_mfma_f32_16x16x32_bf16 v[126:129], v[156:159], v[190:193], v[126:129]
	v_mfma_f32_16x16x32_bf16 v[122:125], v[164:167], v[190:193], v[122:125]
	v_mfma_f32_16x16x32_bf16 v[110:113], v[156:159], v[198:201], v[110:113]
	v_mfma_f32_16x16x32_bf16 v[106:109], v[164:167], v[198:201], v[106:109]
	v_mfma_f32_16x16x32_bf16 v[94:97], v[156:159], v[206:209], v[94:97]
	v_mfma_f32_16x16x32_bf16 v[90:93], v[164:167], v[206:209], v[90:93]
	v_mfma_f32_16x16x32_bf16 v[78:81], v[156:159], v[214:217], v[78:81]
	v_mfma_f32_16x16x32_bf16 v[74:77], v[164:167], v[214:217], v[74:77]
	v_mfma_f32_16x16x32_bf16 v[118:121], v[168:171], v[186:189], v[118:121]
	v_mfma_f32_16x16x32_bf16 v[114:117], v[176:179], v[186:189], v[114:117]
	v_mfma_f32_16x16x32_bf16 v[102:105], v[168:171], v[194:197], v[102:105]
	v_mfma_f32_16x16x32_bf16 v[98:101], v[176:179], v[194:197], v[98:101]
	v_mfma_f32_16x16x32_bf16 v[86:89], v[168:171], v[202:205], v[86:89]
	v_mfma_f32_16x16x32_bf16 v[82:85], v[176:179], v[202:205], v[82:85]
	v_mfma_f32_16x16x32_bf16 v[70:73], v[168:171], v[210:213], v[70:73]
	v_mfma_f32_16x16x32_bf16 v[66:69], v[176:179], v[210:213], v[66:69]
	v_mfma_f32_16x16x32_bf16 v[118:121], v[172:175], v[190:193], v[118:121]
	v_mfma_f32_16x16x32_bf16 v[114:117], v[180:183], v[190:193], v[114:117]
	v_mfma_f32_16x16x32_bf16 v[102:105], v[172:175], v[198:201], v[102:105]
	v_mfma_f32_16x16x32_bf16 v[98:101], v[180:183], v[198:201], v[98:101]
	v_mfma_f32_16x16x32_bf16 v[86:89], v[172:175], v[206:209], v[86:89]
	v_mfma_f32_16x16x32_bf16 v[82:85], v[180:183], v[206:209], v[82:85]
	v_mfma_f32_16x16x32_bf16 v[70:73], v[172:175], v[214:217], v[70:73]
	v_mfma_f32_16x16x32_bf16 v[66:69], v[180:183], v[214:217], v[66:69]
	s_setprio 0
	s_barrier
	s_add_u32 s88, s46, s16
	s_addc_u32 s89, s47, s17
	s_add_u32 s90, s48, s16
	s_addc_u32 s91, s49, s17
	s_add_i32 s67, s61, s52
	s_mov_b32 m0, s67
	ds_read_b128 v[186:189], v154 offset:16384
	ds_read_b128 v[190:193], v154 offset:17408
	ds_read_b128 v[194:197], v154 offset:18432
	ds_read_b128 v[198:201], v154 offset:19456
	ds_read_b128 v[202:205], v154 offset:20480
	ds_read_b128 v[206:209], v154 offset:21504
	ds_read_b128 v[210:213], v154 offset:22528
	ds_read_b128 v[214:217], v154 offset:23552
	global_load_lds_dwordx4 v132, s[46:47]
	s_add_i32 m0, s67, 0x2000
	s_add_u32 s68, s46, 0x40000
	s_addc_u32 s69, s47, 0
	s_add_i32 s67, s62, s52
	global_load_lds_dwordx4 v136, s[46:47]
	s_mov_b32 m0, s67
	s_nop 0
	global_load_lds_dwordx4 v132, s[68:69]
	s_add_i32 m0, s67, 0x2000
	s_nop 0
	global_load_lds_dwordx4 v136, s[68:69]
	s_mov_b32 m0, s43
	s_nop 0
	global_load_lds_dwordx4 v130, s[48:49]
	s_mov_b32 m0, s53
	s_nop 0
	global_load_lds_dwordx4 v134, s[48:49]
	s_waitcnt vmcnt(8)
	s_waitcnt lgkmcnt(0)
	s_barrier
	s_setprio 1
	v_mfma_f32_16x16x32_bf16 v[62:65], v[146:149], v[186:189], v[62:65]
	v_mfma_f32_16x16x32_bf16 v[58:61], v[160:163], v[186:189], v[58:61]
	v_mfma_f32_16x16x32_bf16 v[46:49], v[146:149], v[194:197], v[46:49]
	v_mfma_f32_16x16x32_bf16 v[42:45], v[160:163], v[194:197], v[42:45]
	v_mfma_f32_16x16x32_bf16 v[30:33], v[146:149], v[202:205], v[30:33]
	v_mfma_f32_16x16x32_bf16 v[26:29], v[160:163], v[202:205], v[26:29]
	v_mfma_f32_16x16x32_bf16 v[14:17], v[146:149], v[210:213], v[14:17]
	v_mfma_f32_16x16x32_bf16 v[10:13], v[160:163], v[210:213], v[10:13]
	v_mfma_f32_16x16x32_bf16 v[62:65], v[156:159], v[190:193], v[62:65]
	v_mfma_f32_16x16x32_bf16 v[58:61], v[164:167], v[190:193], v[58:61]
	v_mfma_f32_16x16x32_bf16 v[46:49], v[156:159], v[198:201], v[46:49]
	v_mfma_f32_16x16x32_bf16 v[42:45], v[164:167], v[198:201], v[42:45]
	v_mfma_f32_16x16x32_bf16 v[30:33], v[156:159], v[206:209], v[30:33]
	v_mfma_f32_16x16x32_bf16 v[26:29], v[164:167], v[206:209], v[26:29]
	v_mfma_f32_16x16x32_bf16 v[14:17], v[156:159], v[214:217], v[14:17]
	v_mfma_f32_16x16x32_bf16 v[10:13], v[164:167], v[214:217], v[10:13]
	v_mfma_f32_16x16x32_bf16 v[54:57], v[168:171], v[186:189], v[54:57]
	v_mfma_f32_16x16x32_bf16 v[50:53], v[176:179], v[186:189], v[50:53]
	v_mfma_f32_16x16x32_bf16 v[38:41], v[168:171], v[194:197], v[38:41]
	v_mfma_f32_16x16x32_bf16 v[34:37], v[176:179], v[194:197], v[34:37]
	v_mfma_f32_16x16x32_bf16 v[22:25], v[168:171], v[202:205], v[22:25]
	v_mfma_f32_16x16x32_bf16 v[18:21], v[176:179], v[202:205], v[18:21]
	v_mfma_f32_16x16x32_bf16 v[6:9], v[168:171], v[210:213], v[6:9]
	v_mfma_f32_16x16x32_bf16 v[2:5], v[176:179], v[210:213], v[2:5]
	v_mfma_f32_16x16x32_bf16 v[54:57], v[172:175], v[190:193], v[54:57]
	v_mfma_f32_16x16x32_bf16 v[50:53], v[180:183], v[190:193], v[50:53]
	v_mfma_f32_16x16x32_bf16 v[38:41], v[172:175], v[198:201], v[38:41]
	v_mfma_f32_16x16x32_bf16 v[34:37], v[180:183], v[198:201], v[34:37]
	v_mfma_f32_16x16x32_bf16 v[22:25], v[172:175], v[206:209], v[22:25]
	v_mfma_f32_16x16x32_bf16 v[18:21], v[180:183], v[206:209], v[18:21]
	v_mfma_f32_16x16x32_bf16 v[6:9], v[172:175], v[214:217], v[6:9]
	v_mfma_f32_16x16x32_bf16 v[2:5], v[180:183], v[214:217], v[2:5]
	s_setprio 0
	s_barrier
; #define PG8_STAGE(bufoff, gbase, voff) do { _Pragma("unroll") for (int _i = 0; _i < 2; ++_i) \
;         __builtin_amdgcn_global_load_lds((const unsigned*)((const char*)(gbase) + (voff)[_i]), (LAS unsigned*)(lds + (bufoff) + ldsw + _i * 8192), 16, 0, 0); } while (0)
; #define PG8_LDA(dst, b, h) do { _Pragma("unroll") for (int m = 0; m < 4; ++m) _Pragma("unroll") for (int k = 0; k < 2; ++k) dst[m][k] = *(const LAS bf16x8*)(lds + PG8_SA(b, h) + aoff + m * 2048 + k * 1024); } while (0)
; #define PG8_LDB(dst, b, h) do { _Pragma("unroll") for (int n = 0; n < 2; ++n) _Pragma("unroll") for (int k = 0; k < 2; ++k) dst[n][k] = *(const LAS bf16x8*)(lds + PG8_SB(b, h) + boff + n * 2048 + k * 1024); } while (0)
; #define PG8_MMA(ai, bj, At, Bt) do { __builtin_amdgcn_s_setprio(1); _Pragma("unroll") for (int m = 0; m < 4; ++m) _Pragma("unroll") for (int n = 0; n < 2; ++n) _Pragma("unroll") for (int k = 0; k < 2; ++k) \
;         acc[ai][bj][m][n] = __builtin_amdgcn_mfma_f32_16x16x32_bf16(Bt[n][k], At[m][k], acc[ai][bj][m][n], 0, 0, 0); __builtin_amdgcn_s_setprio(0); } while (0)
; #define PG8_WAIT_V(n) asm volatile("s_waitcnt vmcnt(" #n ")" ::: "memory")
; #define PG8_WAIT_L(n) asm volatile("s_waitcnt lgkmcnt(" #n ")" ::: "memory")
; #define PG8_BAR __builtin_amdgcn_s_barrier()
; #define PG8_SCHED __builtin_amdgcn_sched_barrier(0)
; template <class Epi, class Sched>
; DI void gemm_phase(LAS unsigned char* lds, const Gemm g, const Sched& S, const Epi& E) {
;     ...
;             PG8_LDB(B0, 1, 0); PG8_LDB(B1, 1, 1); PG8_SCHED; PG8_LDA(At, 1, 0); PG8_STAGE(PG8_SA(0, 1), a2 + hstepA, voffA);
;             PG8_WAIT_V(8); PG8_WAIT_L(0); PG8_BAR; PG8_MMA(0, 0, At, B0); PG8_MMA(0, 1, At, B1); PG8_BAR; PG8_SCHED;
;             PG8_LDA(At, 1, 1); PG8_STAGE(PG8_SB(1, 0), b3, voffB); PG8_STAGE(PG8_SB(1, 1), b3 + hstepB, voffB); PG8_STAGE(PG8_SA(1, 0), a3, voffA);
;             PG8_WAIT_V(8); PG8_WAIT_L(0); PG8_BAR; PG8_MMA(1, 0, At, B0); PG8_MMA(1, 1, At, B1); PG8_BAR; PG8_SCHED;
;         }
	s_add_i32 s67, 0, 0x18000
	s_add_i32 s68, 0, 0x1c000
	v_add_u32_e32 v164, s67, v150
	v_add_u32_e32 v180, s68, v150
	ds_read_b128 v[146:149], v164
	ds_read_b128 v[156:159], v164 offset:1024
	ds_read_b128 v[160:163], v164 offset:2048
	ds_read_b128 v[164:167], v164 offset:3072
	ds_read_b128 v[168:171], v180
	ds_read_b128 v[172:175], v180 offset:1024
	ds_read_b128 v[176:179], v180 offset:2048
	ds_read_b128 v[180:183], v180 offset:3072
	s_add_u32 s48, s48, 0x40000
	s_addc_u32 s49, s49, 0
	s_mov_b32 m0, s54
	ds_read_b128 v[186:189], v154 offset:32768
	ds_read_b128 v[190:193], v154 offset:33792
	ds_read_b128 v[194:197], v154 offset:34816
	ds_read_b128 v[198:201], v154 offset:35840
	ds_read_b128 v[202:205], v154 offset:36864
	ds_read_b128 v[206:209], v154 offset:37888
	ds_read_b128 v[210:213], v154 offset:38912
	ds_read_b128 v[214:217], v154 offset:39936
	global_load_lds_dwordx4 v130, s[48:49]
	s_mov_b32 m0, s55
	s_nop 0
	global_load_lds_dwordx4 v134, s[48:49]
	s_waitcnt vmcnt(8)
	s_waitcnt lgkmcnt(0)
	s_barrier
	s_setprio 1
	v_mfma_f32_16x16x32_bf16 v[126:129], v[146:149], v[186:189], v[126:129]
	v_mfma_f32_16x16x32_bf16 v[122:125], v[160:163], v[186:189], v[122:125]
	v_mfma_f32_16x16x32_bf16 v[110:113], v[146:149], v[194:197], v[110:113]
	v_mfma_f32_16x16x32_bf16 v[106:109], v[160:163], v[194:197], v[106:109]
	v_mfma_f32_16x16x32_bf16 v[94:97], v[146:149], v[202:205], v[94:97]
	v_mfma_f32_16x16x32_bf16 v[90:93], v[160:163], v[202:205], v[90:93]
	v_mfma_f32_16x16x32_bf16 v[78:81], v[146:149], v[210:213], v[78:81]
	v_mfma_f32_16x16x32_bf16 v[74:77], v[160:163], v[210:213], v[74:77]
	v_mfma_f32_16x16x32_bf16 v[126:129], v[156:159], v[190:193], v[126:129]
	v_mfma_f32_16x16x32_bf16 v[122:125], v[164:167], v[190:193], v[122:125]
	v_mfma_f32_16x16x32_bf16 v[110:113], v[156:159], v[198:201], v[110:113]
	v_mfma_f32_16x16x32_bf16 v[106:109], v[164:167], v[198:201], v[106:109]
	v_mfma_f32_16x16x32_bf16 v[94:97], v[156:159], v[206:209], v[94:97]
	v_mfma_f32_16x16x32_bf16 v[90:93], v[164:167], v[206:209], v[90:93]
	v_mfma_f32_16x16x32_bf16 v[78:81], v[156:159], v[214:217], v[78:81]
	v_mfma_f32_16x16x32_bf16 v[74:77], v[164:167], v[214:217], v[74:77]
	v_mfma_f32_16x16x32_bf16 v[118:121], v[168:171], v[186:189], v[118:121]
	v_mfma_f32_16x16x32_bf16 v[114:117], v[176:179], v[186:189], v[114:117]
	v_mfma_f32_16x16x32_bf16 v[102:105], v[168:171], v[194:197], v[102:105]
	v_mfma_f32_16x16x32_bf16 v[98:101], v[176:179], v[194:197], v[98:101]
	v_mfma_f32_16x16x32_bf16 v[86:89], v[168:171], v[202:205], v[86:89]
	v_mfma_f32_16x16x32_bf16 v[82:85], v[176:179], v[202:205], v[82:85]
	v_mfma_f32_16x16x32_bf16 v[70:73], v[168:171], v[210:213], v[70:73]
	v_mfma_f32_16x16x32_bf16 v[66:69], v[176:179], v[210:213], v[66:69]
	v_mfma_f32_16x16x32_bf16 v[118:121], v[172:175], v[190:193], v[118:121]
	v_mfma_f32_16x16x32_bf16 v[114:117], v[180:183], v[190:193], v[114:117]
	v_mfma_f32_16x16x32_bf16 v[102:105], v[172:175], v[198:201], v[102:105]
	v_mfma_f32_16x16x32_bf16 v[98:101], v[180:183], v[198:201], v[98:101]
	v_mfma_f32_16x16x32_bf16 v[86:89], v[172:175], v[206:209], v[86:89]
	v_mfma_f32_16x16x32_bf16 v[82:85], v[180:183], v[206:209], v[82:85]
	v_mfma_f32_16x16x32_bf16 v[70:73], v[172:175], v[214:217], v[70:73]
	v_mfma_f32_16x16x32_bf16 v[66:69], v[180:183], v[214:217], v[66:69]
	s_setprio 0
	s_barrier
	s_add_i32 s48, s67, s52
	s_mov_b32 m0, s48
	ds_read_b128 v[186:189], v154 offset:49152
	ds_read_b128 v[190:193], v154 offset:50176
	ds_read_b128 v[194:197], v154 offset:51200
	ds_read_b128 v[198:201], v154 offset:52224
	ds_read_b128 v[202:205], v154 offset:53248
	ds_read_b128 v[206:209], v154 offset:54272
	ds_read_b128 v[210:213], v154 offset:55296
	ds_read_b128 v[214:217], v154 offset:56320
	global_load_lds_dwordx4 v132, s[88:89]
	s_add_i32 m0, s48, 0x2000
	s_add_u32 s46, s46, 0x40080
	s_addc_u32 s47, s47, 0
	s_add_i32 s48, s68, s52
	global_load_lds_dwordx4 v136, s[88:89]
	s_mov_b32 m0, s48
	s_nop 0
	global_load_lds_dwordx4 v132, s[46:47]
	s_add_i32 m0, s48, 0x2000
	s_nop 0
	global_load_lds_dwordx4 v136, s[46:47]
	s_mov_b32 m0, s57
	s_nop 0
	global_load_lds_dwordx4 v130, s[90:91]
	s_mov_b32 m0, s58
	s_nop 0
	global_load_lds_dwordx4 v134, s[90:91]
	s_waitcnt vmcnt(8)
	s_waitcnt lgkmcnt(0)
	s_barrier
	s_setprio 1
	v_mfma_f32_16x16x32_bf16 v[62:65], v[146:149], v[186:189], v[62:65]
	v_mfma_f32_16x16x32_bf16 v[58:61], v[160:163], v[186:189], v[58:61]
	v_mfma_f32_16x16x32_bf16 v[46:49], v[146:149], v[194:197], v[46:49]
	v_mfma_f32_16x16x32_bf16 v[42:45], v[160:163], v[194:197], v[42:45]
	v_mfma_f32_16x16x32_bf16 v[30:33], v[146:149], v[202:205], v[30:33]
	v_mfma_f32_16x16x32_bf16 v[26:29], v[160:163], v[202:205], v[26:29]
	v_mfma_f32_16x16x32_bf16 v[14:17], v[146:149], v[210:213], v[14:17]
	v_mfma_f32_16x16x32_bf16 v[10:13], v[160:163], v[210:213], v[10:13]
	v_mfma_f32_16x16x32_bf16 v[62:65], v[156:159], v[190:193], v[62:65]
	v_mfma_f32_16x16x32_bf16 v[58:61], v[164:167], v[190:193], v[58:61]
	v_mfma_f32_16x16x32_bf16 v[46:49], v[156:159], v[198:201], v[46:49]
	v_mfma_f32_16x16x32_bf16 v[42:45], v[164:167], v[198:201], v[42:45]
	v_mfma_f32_16x16x32_bf16 v[30:33], v[156:159], v[206:209], v[30:33]
	v_mfma_f32_16x16x32_bf16 v[26:29], v[164:167], v[206:209], v[26:29]
	v_mfma_f32_16x16x32_bf16 v[14:17], v[156:159], v[214:217], v[14:17]
	v_mfma_f32_16x16x32_bf16 v[10:13], v[164:167], v[214:217], v[10:13]
	v_mfma_f32_16x16x32_bf16 v[54:57], v[168:171], v[186:189], v[54:57]
	v_mfma_f32_16x16x32_bf16 v[50:53], v[176:179], v[186:189], v[50:53]
	v_mfma_f32_16x16x32_bf16 v[38:41], v[168:171], v[194:197], v[38:41]
	v_mfma_f32_16x16x32_bf16 v[34:37], v[176:179], v[194:197], v[34:37]
	v_mfma_f32_16x16x32_bf16 v[22:25], v[168:171], v[202:205], v[22:25]
	v_mfma_f32_16x16x32_bf16 v[18:21], v[176:179], v[202:205], v[18:21]
	v_mfma_f32_16x16x32_bf16 v[6:9], v[168:171], v[210:213], v[6:9]
	v_mfma_f32_16x16x32_bf16 v[2:5], v[176:179], v[210:213], v[2:5]
	v_mfma_f32_16x16x32_bf16 v[54:57], v[172:175], v[190:193], v[54:57]
	v_mfma_f32_16x16x32_bf16 v[50:53], v[180:183], v[190:193], v[50:53]
	v_mfma_f32_16x16x32_bf16 v[38:41], v[172:175], v[198:201], v[38:41]
	v_mfma_f32_16x16x32_bf16 v[34:37], v[180:183], v[198:201], v[34:37]
	v_mfma_f32_16x16x32_bf16 v[22:25], v[172:175], v[206:209], v[22:25]
	v_mfma_f32_16x16x32_bf16 v[18:21], v[180:183], v[206:209], v[18:21]
	v_mfma_f32_16x16x32_bf16 v[6:9], v[172:175], v[214:217], v[6:9]
	v_mfma_f32_16x16x32_bf16 v[2:5], v[180:183], v[214:217], v[2:5]
	s_setprio 0
	s_barrier
	s_add_i32 s66, s66, 2
	s_add_u32 s44, s44, 0x100
	s_addc_u32 s45, s45, 0
	s_add_u32 s64, s64, 0x100
	s_addc_u32 s65, s65, 0
	s_cmp_gt_u32 s66, 13
	s_cbranch_scc0 .LBB0_1133
	s_mov_b32 s99, 1
	s_and_b64 vcc, exec, s[18:19]
	s_cbranch_vccz .LBB0_1136
	s_barrier

; #define PG8_STAGE(bufoff, gbase, voff) do { _Pragma("unroll") for (int _i = 0; _i < 2; ++_i) \
;         __builtin_amdgcn_global_load_lds((const unsigned*)((const char*)(gbase) + (voff)[_i]), (LAS unsigned*)(lds + (bufoff) + ldsw + _i * 8192), 16, 0, 0); } while (0)
; #define PG8_LDA(dst, b, h) do { _Pragma("unroll") for (int m = 0; m < 4; ++m) _Pragma("unroll") for (int k = 0; k < 2; ++k) dst[m][k] = *(const LAS bf16x8*)(lds + PG8_SA(b, h) + aoff + m * 2048 + k * 1024); } while (0)
; #define PG8_MMA(ai, bj, At, Bt) do { __builtin_amdgcn_s_setprio(1); _Pragma("unroll") for (int m = 0; m < 4; ++m) _Pragma("unroll") for (int n = 0; n < 2; ++n) _Pragma("unroll") for (int k = 0; k < 2; ++k) \
;         acc[ai][bj][m][n] = __builtin_amdgcn_mfma_f32_16x16x32_bf16(Bt[n][k], At[m][k], acc[ai][bj][m][n], 0, 0, 0); __builtin_amdgcn_s_setprio(0); } while (0)
; #define PG8_WAIT_V(n) asm volatile("s_waitcnt vmcnt(" #n ")" ::: "memory")
; #define PG8_WAIT_L(n) asm volatile("s_waitcnt lgkmcnt(" #n ")" ::: "memory")
; #define PG8_BAR __builtin_amdgcn_s_barrier()
; #define PG8_SCHED __builtin_amdgcn_sched_barrier(0)
; template <class Epi, class Sched>
; DI void gemm_phase(LAS unsigned char* lds, const Gemm g, const Sched& S, const Epi& E) {
;     ...
;             PG8_WAIT_V(8); PG8_WAIT_L(0); PG8_BAR; PG8_MMA(0, 0, At, B0); PG8_MMA(0, 1, At, B1); PG8_BAR; PG8_SCHED;
;             PG8_LDA(At, 0, 1); PG8_STAGE(PG8_SB(0, 0), b2, voffB); PG8_STAGE(PG8_SB(0, 1), b2 + hstepB, voffB); PG8_STAGE(PG8_SA(0, 0), a2, voffA);
;             PG8_WAIT_V(8); PG8_WAIT_L(0); PG8_BAR; PG8_MMA(1, 0, At, B0); PG8_MMA(1, 1, At, B1); PG8_BAR; PG8_SCHED;
.Lpk5_w1:
	s_waitcnt lgkmcnt(0)
	s_barrier
	s_setprio 1
	v_mfma_f32_16x16x32_bf16 v[126:129], v[166:169], v[202:205], 0
	v_mfma_f32_16x16x32_bf16 v[118:121], v[174:177], v[202:205], 0
	v_mfma_f32_16x16x32_bf16 v[110:113], v[166:169], v[210:213], 0
	v_mfma_f32_16x16x32_bf16 v[102:105], v[174:177], v[210:213], 0
	v_mfma_f32_16x16x32_bf16 v[94:97], v[166:169], v[218:221], 0
	v_mfma_f32_16x16x32_bf16 v[86:89], v[174:177], v[218:221], 0
	v_mfma_f32_16x16x32_bf16 v[78:81], v[166:169], v[226:229], 0
	v_mfma_f32_16x16x32_bf16 v[70:73], v[174:177], v[226:229], 0
	v_mfma_f32_16x16x32_bf16 v[126:129], v[170:173], v[206:209], v[126:129]
	v_mfma_f32_16x16x32_bf16 v[118:121], v[178:181], v[206:209], v[118:121]
	v_mfma_f32_16x16x32_bf16 v[110:113], v[170:173], v[214:217], v[110:113]
	v_mfma_f32_16x16x32_bf16 v[102:105], v[178:181], v[214:217], v[102:105]
	v_mfma_f32_16x16x32_bf16 v[94:97], v[170:173], v[222:225], v[94:97]
	v_mfma_f32_16x16x32_bf16 v[86:89], v[178:181], v[222:225], v[86:89]
	v_mfma_f32_16x16x32_bf16 v[78:81], v[170:173], v[230:233], v[78:81]
	v_mfma_f32_16x16x32_bf16 v[70:73], v[178:181], v[230:233], v[70:73]
	v_mfma_f32_16x16x32_bf16 v[122:125], v[186:189], v[202:205], 0
	v_mfma_f32_16x16x32_bf16 v[114:117], v[194:197], v[202:205], 0
	v_mfma_f32_16x16x32_bf16 v[106:109], v[186:189], v[210:213], 0
	v_mfma_f32_16x16x32_bf16 v[98:101], v[194:197], v[210:213], 0
	v_mfma_f32_16x16x32_bf16 v[90:93], v[186:189], v[218:221], 0
	v_mfma_f32_16x16x32_bf16 v[82:85], v[194:197], v[218:221], 0
	v_mfma_f32_16x16x32_bf16 v[74:77], v[186:189], v[226:229], 0
	v_mfma_f32_16x16x32_bf16 v[66:69], v[194:197], v[226:229], 0
	v_mfma_f32_16x16x32_bf16 v[122:125], v[190:193], v[206:209], v[122:125]
	v_mfma_f32_16x16x32_bf16 v[114:117], v[198:201], v[206:209], v[114:117]
	v_mfma_f32_16x16x32_bf16 v[106:109], v[190:193], v[214:217], v[106:109]
	v_mfma_f32_16x16x32_bf16 v[98:101], v[198:201], v[214:217], v[98:101]
	v_mfma_f32_16x16x32_bf16 v[90:93], v[190:193], v[222:225], v[90:93]
	v_mfma_f32_16x16x32_bf16 v[82:85], v[198:201], v[222:225], v[82:85]
	v_mfma_f32_16x16x32_bf16 v[74:77], v[190:193], v[230:233], v[74:77]
	v_mfma_f32_16x16x32_bf16 v[66:69], v[198:201], v[230:233], v[66:69]
	s_setprio 0
	s_barrier
	s_add_u32 s88, s42, s16
	s_addc_u32 s89, s43, s17
	s_add_u32 s90, s44, s16
	s_addc_u32 s91, s45, s17
	s_add_i32 s66, s57, s46
	s_mov_b32 m0, s66
	ds_read_b128 v[202:205], v158 offset:16384
	ds_read_b128 v[206:209], v158 offset:17408
	ds_read_b128 v[210:213], v158 offset:18432
	ds_read_b128 v[214:217], v158 offset:19456
	ds_read_b128 v[218:221], v158 offset:20480
	ds_read_b128 v[222:225], v158 offset:21504
	ds_read_b128 v[226:229], v158 offset:22528
	ds_read_b128 v[230:233], v158 offset:23552
	global_load_lds_dwordx4 v134, s[42:43]
	s_add_i32 m0, s66, 0x2000
	s_add_u32 s66, s42, 0x40000
	s_addc_u32 s67, s43, 0
	s_add_i32 s68, s58, s46
	global_load_lds_dwordx4 v130, s[42:43]
	s_mov_b32 m0, s68
	s_nop 0
	global_load_lds_dwordx4 v134, s[66:67]
	s_add_i32 m0, s68, 0x2000
	s_nop 0
	global_load_lds_dwordx4 v130, s[66:67]
	s_mov_b32 m0, s49
	s_nop 0
	global_load_lds_dwordx4 v136, s[44:45]
	s_mov_b32 m0, s50
	s_nop 0
	global_load_lds_dwordx4 v132, s[44:45]
	s_cmp_lg_u32 s99, 0
	s_cbranch_scc1 .Lpk5_w2
	s_waitcnt vmcnt(8)
.Lpk5_w2:
	s_mov_b32 s99, 0
	s_waitcnt lgkmcnt(0)
	s_barrier
	s_setprio 1
	v_mfma_f32_16x16x32_bf16 v[62:65], v[166:169], v[202:205], 0
	v_mfma_f32_16x16x32_bf16 v[54:57], v[174:177], v[202:205], 0
	v_mfma_f32_16x16x32_bf16 v[46:49], v[166:169], v[210:213], 0
	v_mfma_f32_16x16x32_bf16 v[38:41], v[174:177], v[210:213], 0
	v_mfma_f32_16x16x32_bf16 v[30:33], v[166:169], v[218:221], 0
	v_mfma_f32_16x16x32_bf16 v[22:25], v[174:177], v[218:221], 0
	v_mfma_f32_16x16x32_bf16 v[14:17], v[166:169], v[226:229], 0
	v_mfma_f32_16x16x32_bf16 v[6:9], v[174:177], v[226:229], 0
	v_mfma_f32_16x16x32_bf16 v[62:65], v[170:173], v[206:209], v[62:65]
	v_mfma_f32_16x16x32_bf16 v[54:57], v[178:181], v[206:209], v[54:57]
	v_mfma_f32_16x16x32_bf16 v[46:49], v[170:173], v[214:217], v[46:49]
	v_mfma_f32_16x16x32_bf16 v[38:41], v[178:181], v[214:217], v[38:41]
	v_mfma_f32_16x16x32_bf16 v[30:33], v[170:173], v[222:225], v[30:33]
	v_mfma_f32_16x16x32_bf16 v[22:25], v[178:181], v[222:225], v[22:25]
	v_mfma_f32_16x16x32_bf16 v[14:17], v[170:173], v[230:233], v[14:17]
	v_mfma_f32_16x16x32_bf16 v[6:9], v[178:181], v[230:233], v[6:9]
	v_mfma_f32_16x16x32_bf16 v[58:61], v[186:189], v[202:205], 0
	v_mfma_f32_16x16x32_bf16 v[50:53], v[194:197], v[202:205], 0
	v_mfma_f32_16x16x32_bf16 v[42:45], v[186:189], v[210:213], 0
	v_mfma_f32_16x16x32_bf16 v[34:37], v[194:197], v[210:213], 0
	v_mfma_f32_16x16x32_bf16 v[26:29], v[186:189], v[218:221], 0
	v_mfma_f32_16x16x32_bf16 v[18:21], v[194:197], v[218:221], 0
	v_mfma_f32_16x16x32_bf16 v[10:13], v[186:189], v[226:229], 0
	v_mfma_f32_16x16x32_bf16 v[2:5], v[194:197], v[226:229], 0
	v_mfma_f32_16x16x32_bf16 v[58:61], v[190:193], v[206:209], v[58:61]
	v_mfma_f32_16x16x32_bf16 v[50:53], v[198:201], v[206:209], v[50:53]
	v_mfma_f32_16x16x32_bf16 v[42:45], v[190:193], v[214:217], v[42:45]
	v_mfma_f32_16x16x32_bf16 v[34:37], v[198:201], v[214:217], v[34:37]
	v_mfma_f32_16x16x32_bf16 v[26:29], v[190:193], v[222:225], v[26:29]
	v_mfma_f32_16x16x32_bf16 v[18:21], v[198:201], v[222:225], v[18:21]
	v_mfma_f32_16x16x32_bf16 v[10:13], v[190:193], v[230:233], v[10:13]
	v_mfma_f32_16x16x32_bf16 v[2:5], v[198:201], v[230:233], v[2:5]
	s_setprio 0
	s_barrier
; #define PG8_STAGE(bufoff, gbase, voff) do { _Pragma("unroll") for (int _i = 0; _i < 2; ++_i) \
;         __builtin_amdgcn_global_load_lds((const unsigned*)((const char*)(gbase) + (voff)[_i]), (LAS unsigned*)(lds + (bufoff) + ldsw + _i * 8192), 16, 0, 0); } while (0)
; #define PG8_LDA(dst, b, h) do { _Pragma("unroll") for (int m = 0; m < 4; ++m) _Pragma("unroll") for (int k = 0; k < 2; ++k) dst[m][k] = *(const LAS bf16x8*)(lds + PG8_SA(b, h) + aoff + m * 2048 + k * 1024); } while (0)
; #define PG8_LDB(dst, b, h) do { _Pragma("unroll") for (int n = 0; n < 2; ++n) _Pragma("unroll") for (int k = 0; k < 2; ++k) dst[n][k] = *(const LAS bf16x8*)(lds + PG8_SB(b, h) + boff + n * 2048 + k * 1024); } while (0)
; #define PG8_MMA(ai, bj, At, Bt) do { __builtin_amdgcn_s_setprio(1); _Pragma("unroll") for (int m = 0; m < 4; ++m) _Pragma("unroll") for (int n = 0; n < 2; ++n) _Pragma("unroll") for (int k = 0; k < 2; ++k) \
;         acc[ai][bj][m][n] = __builtin_amdgcn_mfma_f32_16x16x32_bf16(Bt[n][k], At[m][k], acc[ai][bj][m][n], 0, 0, 0); __builtin_amdgcn_s_setprio(0); } while (0)
; #define PG8_WAIT_V(n) asm volatile("s_waitcnt vmcnt(" #n ")" ::: "memory")
; #define PG8_WAIT_L(n) asm volatile("s_waitcnt lgkmcnt(" #n ")" ::: "memory")
; #define PG8_BAR __builtin_amdgcn_s_barrier()
; #define PG8_SCHED __builtin_amdgcn_sched_barrier(0)
; template <class Epi, class Sched>
; DI void gemm_phase(LAS unsigned char* lds, const Gemm g, const Sched& S, const Epi& E) {
;     ...
;             PG8_LDB(B0, 1, 0); PG8_LDB(B1, 1, 1); PG8_SCHED; PG8_LDA(At, 1, 0); PG8_STAGE(PG8_SA(0, 1), a2 + hstepA, voffA);
;             PG8_WAIT_V(8); PG8_WAIT_L(0); PG8_BAR; PG8_MMA(0, 0, At, B0); PG8_MMA(0, 1, At, B1); PG8_BAR; PG8_SCHED;
;             PG8_LDA(At, 1, 1); PG8_STAGE(PG8_SB(1, 0), b3, voffB); PG8_STAGE(PG8_SB(1, 1), b3 + hstepB, voffB); PG8_STAGE(PG8_SA(1, 0), a3, voffA);
;             PG8_WAIT_V(8); PG8_WAIT_L(0); PG8_BAR; PG8_MMA(1, 0, At, B0); PG8_MMA(1, 1, At, B1); PG8_BAR; PG8_SCHED;
	s_add_i32 s66, 0, 0x18000
	v_add_u32_e32 v165, s66, v156
	s_add_i32 s67, 0, 0x1c000
	ds_read_b128 v[166:169], v165
	ds_read_b128 v[170:173], v165 offset:1024
	ds_read_b128 v[174:177], v165 offset:2048
	ds_read_b128 v[178:181], v165 offset:3072
	v_add_u32_e32 v165, s67, v156
	ds_read_b128 v[186:189], v165
	ds_read_b128 v[190:193], v165 offset:1024
	ds_read_b128 v[194:197], v165 offset:2048
	ds_read_b128 v[198:201], v165 offset:3072
	s_add_u32 s44, s44, 0x40000
	s_addc_u32 s45, s45, 0
	s_mov_b32 m0, s51
	ds_read_b128 v[202:205], v158 offset:32768
	ds_read_b128 v[206:209], v158 offset:33792
	ds_read_b128 v[210:213], v158 offset:34816
	ds_read_b128 v[214:217], v158 offset:35840
	ds_read_b128 v[218:221], v158 offset:36864
	ds_read_b128 v[222:225], v158 offset:37888
	ds_read_b128 v[226:229], v158 offset:38912
	ds_read_b128 v[230:233], v158 offset:39936
	global_load_lds_dwordx4 v136, s[44:45]
	s_mov_b32 m0, s52
	s_nop 0
	global_load_lds_dwordx4 v132, s[44:45]
	s_waitcnt vmcnt(8)
	s_waitcnt lgkmcnt(0)
	s_barrier
	s_setprio 1
	v_mfma_f32_16x16x32_bf16 v[126:129], v[166:169], v[202:205], v[126:129]
	v_mfma_f32_16x16x32_bf16 v[118:121], v[174:177], v[202:205], v[118:121]
	v_mfma_f32_16x16x32_bf16 v[110:113], v[166:169], v[210:213], v[110:113]
	v_mfma_f32_16x16x32_bf16 v[102:105], v[174:177], v[210:213], v[102:105]
	v_mfma_f32_16x16x32_bf16 v[94:97], v[166:169], v[218:221], v[94:97]
	v_mfma_f32_16x16x32_bf16 v[86:89], v[174:177], v[218:221], v[86:89]
	v_mfma_f32_16x16x32_bf16 v[78:81], v[166:169], v[226:229], v[78:81]
	v_mfma_f32_16x16x32_bf16 v[70:73], v[174:177], v[226:229], v[70:73]
	v_mfma_f32_16x16x32_bf16 v[126:129], v[170:173], v[206:209], v[126:129]
	v_mfma_f32_16x16x32_bf16 v[118:121], v[178:181], v[206:209], v[118:121]
	v_mfma_f32_16x16x32_bf16 v[110:113], v[170:173], v[214:217], v[110:113]
	v_mfma_f32_16x16x32_bf16 v[102:105], v[178:181], v[214:217], v[102:105]
	v_mfma_f32_16x16x32_bf16 v[94:97], v[170:173], v[222:225], v[94:97]
	v_mfma_f32_16x16x32_bf16 v[86:89], v[178:181], v[222:225], v[86:89]
	v_mfma_f32_16x16x32_bf16 v[78:81], v[170:173], v[230:233], v[78:81]
	v_mfma_f32_16x16x32_bf16 v[70:73], v[178:181], v[230:233], v[70:73]
	v_mfma_f32_16x16x32_bf16 v[122:125], v[186:189], v[202:205], v[122:125]
	v_mfma_f32_16x16x32_bf16 v[114:117], v[194:197], v[202:205], v[114:117]
	v_mfma_f32_16x16x32_bf16 v[106:109], v[186:189], v[210:213], v[106:109]
	v_mfma_f32_16x16x32_bf16 v[98:101], v[194:197], v[210:213], v[98:101]
	v_mfma_f32_16x16x32_bf16 v[90:93], v[186:189], v[218:221], v[90:93]
	v_mfma_f32_16x16x32_bf16 v[82:85], v[194:197], v[218:221], v[82:85]
	v_mfma_f32_16x16x32_bf16 v[74:77], v[186:189], v[226:229], v[74:77]
	v_mfma_f32_16x16x32_bf16 v[66:69], v[194:197], v[226:229], v[66:69]
	v_mfma_f32_16x16x32_bf16 v[122:125], v[190:193], v[206:209], v[122:125]
	v_mfma_f32_16x16x32_bf16 v[114:117], v[198:201], v[206:209], v[114:117]
	v_mfma_f32_16x16x32_bf16 v[106:109], v[190:193], v[214:217], v[106:109]
	v_mfma_f32_16x16x32_bf16 v[98:101], v[198:201], v[214:217], v[98:101]
	v_mfma_f32_16x16x32_bf16 v[90:93], v[190:193], v[222:225], v[90:93]
	v_mfma_f32_16x16x32_bf16 v[82:85], v[198:201], v[222:225], v[82:85]
	v_mfma_f32_16x16x32_bf16 v[74:77], v[190:193], v[230:233], v[74:77]
	v_mfma_f32_16x16x32_bf16 v[66:69], v[198:201], v[230:233], v[66:69]
	s_setprio 0
	s_barrier
	s_add_i32 s44, s66, s46
	s_mov_b32 m0, s44
	ds_read_b128 v[202:205], v158 offset:49152
	ds_read_b128 v[206:209], v158 offset:50176
	ds_read_b128 v[210:213], v158 offset:51200
	ds_read_b128 v[214:217], v158 offset:52224
	ds_read_b128 v[218:221], v158 offset:53248
	ds_read_b128 v[222:225], v158 offset:54272
	ds_read_b128 v[226:229], v158 offset:55296
	ds_read_b128 v[230:233], v158 offset:56320
	global_load_lds_dwordx4 v134, s[88:89]
	s_add_i32 m0, s44, 0x2000
	s_add_u32 s42, s42, 0x40080
	s_addc_u32 s43, s43, 0
	s_add_i32 s44, s67, s46
	global_load_lds_dwordx4 v130, s[88:89]
	s_mov_b32 m0, s44
	s_nop 0
	global_load_lds_dwordx4 v134, s[42:43]
	s_add_i32 m0, s44, 0x2000
	s_nop 0
	global_load_lds_dwordx4 v130, s[42:43]
	s_mov_b32 m0, s54
	s_nop 0
	global_load_lds_dwordx4 v136, s[90:91]
	s_mov_b32 m0, s55
	s_nop 0
	global_load_lds_dwordx4 v132, s[90:91]
	s_waitcnt vmcnt(8)
	s_waitcnt lgkmcnt(0)
	s_barrier
	s_setprio 1
	v_mfma_f32_16x16x32_bf16 v[62:65], v[166:169], v[202:205], v[62:65]
	v_mfma_f32_16x16x32_bf16 v[54:57], v[174:177], v[202:205], v[54:57]
	v_mfma_f32_16x16x32_bf16 v[46:49], v[166:169], v[210:213], v[46:49]
	v_mfma_f32_16x16x32_bf16 v[38:41], v[174:177], v[210:213], v[38:41]
	v_mfma_f32_16x16x32_bf16 v[30:33], v[166:169], v[218:221], v[30:33]
	v_mfma_f32_16x16x32_bf16 v[22:25], v[174:177], v[218:221], v[22:25]
	v_mfma_f32_16x16x32_bf16 v[14:17], v[166:169], v[226:229], v[14:17]
	v_mfma_f32_16x16x32_bf16 v[6:9], v[174:177], v[226:229], v[6:9]
	v_mfma_f32_16x16x32_bf16 v[62:65], v[170:173], v[206:209], v[62:65]
	v_mfma_f32_16x16x32_bf16 v[54:57], v[178:181], v[206:209], v[54:57]
	v_mfma_f32_16x16x32_bf16 v[46:49], v[170:173], v[214:217], v[46:49]
	v_mfma_f32_16x16x32_bf16 v[38:41], v[178:181], v[214:217], v[38:41]
	v_mfma_f32_16x16x32_bf16 v[30:33], v[170:173], v[222:225], v[30:33]
	v_mfma_f32_16x16x32_bf16 v[22:25], v[178:181], v[222:225], v[22:25]
	v_mfma_f32_16x16x32_bf16 v[14:17], v[170:173], v[230:233], v[14:17]
	v_mfma_f32_16x16x32_bf16 v[6:9], v[178:181], v[230:233], v[6:9]
	v_mfma_f32_16x16x32_bf16 v[58:61], v[186:189], v[202:205], v[58:61]
	v_mfma_f32_16x16x32_bf16 v[50:53], v[194:197], v[202:205], v[50:53]
	v_mfma_f32_16x16x32_bf16 v[42:45], v[186:189], v[210:213], v[42:45]
	v_mfma_f32_16x16x32_bf16 v[34:37], v[194:197], v[210:213], v[34:37]
	v_mfma_f32_16x16x32_bf16 v[26:29], v[186:189], v[218:221], v[26:29]
	v_mfma_f32_16x16x32_bf16 v[18:21], v[194:197], v[218:221], v[18:21]
	v_mfma_f32_16x16x32_bf16 v[10:13], v[186:189], v[226:229], v[10:13]
	v_mfma_f32_16x16x32_bf16 v[2:5], v[194:197], v[226:229], v[2:5]
	v_mfma_f32_16x16x32_bf16 v[58:61], v[190:193], v[206:209], v[58:61]
	v_mfma_f32_16x16x32_bf16 v[50:53], v[198:201], v[206:209], v[50:53]
	v_mfma_f32_16x16x32_bf16 v[42:45], v[190:193], v[214:217], v[42:45]
	v_mfma_f32_16x16x32_bf16 v[34:37], v[198:201], v[214:217], v[34:37]
	v_mfma_f32_16x16x32_bf16 v[26:29], v[190:193], v[222:225], v[26:29]
	v_mfma_f32_16x16x32_bf16 v[18:21], v[198:201], v[222:225], v[18:21]
	v_mfma_f32_16x16x32_bf16 v[10:13], v[190:193], v[230:233], v[10:13]
	v_mfma_f32_16x16x32_bf16 v[2:5], v[198:201], v[230:233], v[2:5]
	s_setprio 0
	s_barrier
	s_add_i32 s65, s65, 2
	s_add_u32 s40, s40, 0x100
	s_addc_u32 s41, s41, 0
	s_add_u32 s63, s63, 0x100
	s_addc_u32 s64, s64, 0
	s_cmp_gt_u32 s65, 13
; #define PG8_STAGE(bufoff, gbase, voff) do { _Pragma("unroll") for (int _i = 0; _i < 2; ++_i) \
;         __builtin_amdgcn_global_load_lds((const unsigned*)((const char*)(gbase) + (voff)[_i]), (LAS unsigned*)(lds + (bufoff) + ldsw + _i * 8192), 16, 0, 0); } while (0)
; #define PG8_LDA(dst, b, h) do { _Pragma("unroll") for (int m = 0; m < 4; ++m) _Pragma("unroll") for (int k = 0; k < 2; ++k) dst[m][k] = *(const LAS bf16x8*)(lds + PG8_SA(b, h) + aoff + m * 2048 + k * 1024); } while (0)
; #define PG8_LDB(dst, b, h) do { _Pragma("unroll") for (int n = 0; n < 2; ++n) _Pragma("unroll") for (int k = 0; k < 2; ++k) dst[n][k] = *(const LAS bf16x8*)(lds + PG8_SB(b, h) + boff + n * 2048 + k * 1024); } while (0)
; #define PG8_MMA(ai, bj, At, Bt) do { __builtin_amdgcn_s_setprio(1); _Pragma("unroll") for (int m = 0; m < 4; ++m) _Pragma("unroll") for (int n = 0; n < 2; ++n) _Pragma("unroll") for (int k = 0; k < 2; ++k) \
;         acc[ai][bj][m][n] = __builtin_amdgcn_mfma_f32_16x16x32_bf16(Bt[n][k], At[m][k], acc[ai][bj][m][n], 0, 0, 0); __builtin_amdgcn_s_setprio(0); } while (0)
; #define PG8_WAIT_V(n) asm volatile("s_waitcnt vmcnt(" #n ")" ::: "memory")
; #define PG8_WAIT_L(n) asm volatile("s_waitcnt lgkmcnt(" #n ")" ::: "memory")
; #define PG8_BAR __builtin_amdgcn_s_barrier()
; #define PG8_SCHED __builtin_amdgcn_sched_barrier(0)
; template <class Epi, class Sched>
; DI void gemm_phase(LAS unsigned char* lds, const Gemm g, const Sched& S, const Epi& E) {
;     ...
;             const bool last = (t == nt - 2);
;             const char* a1 = cA + (size_t)(t + 1) * kstep;
;             const char* a2 = last ? nA : cA + (size_t)(t + 2) * kstep; const char* b2 = last ? nB : cB + (size_t)(t + 2) * kstep;
;             const char* a3 = a2 + kstep; const char* b3 = b2 + kstep;
;             PG8_LDB(B0, 0, 0); PG8_LDB(B1, 0, 1); PG8_SCHED; PG8_LDA(At, 0, 0); PG8_STAGE(PG8_SA(1, 1), a1 + hstepA, voffA);
;             PG8_WAIT_V(8); PG8_WAIT_L(0); PG8_BAR; PG8_MMA(0, 0, At, B0); PG8_MMA(0, 1, At, B1); PG8_BAR; PG8_SCHED;
;             PG8_LDA(At, 0, 1); PG8_STAGE(PG8_SB(0, 0), b2, voffB); PG8_STAGE(PG8_SB(0, 1), b2 + hstepB, voffB); PG8_STAGE(PG8_SA(0, 0), a2, voffA);
;             PG8_WAIT_V(8); PG8_WAIT_L(0); PG8_BAR; PG8_MMA(1, 0, At, B0); PG8_MMA(1, 1, At, B1); PG8_BAR; PG8_SCHED;
.LBB0_1234:
	ds_read_b128 v[166:169], v160
	ds_read_b128 v[170:173], v160 offset:1024
	ds_read_b128 v[174:177], v160 offset:2048
	ds_read_b128 v[178:181], v160 offset:3072
	ds_read_b128 v[186:189], v161
	ds_read_b128 v[190:193], v161 offset:1024
	ds_read_b128 v[194:197], v161 offset:2048
	ds_read_b128 v[198:201], v161 offset:3072
	s_add_u32 s42, s40, 0xfffc0080
	s_addc_u32 s43, s41, -1
	s_cmp_eq_u32 s65, 12
	s_cselect_b32 s45, s35, s43
	s_cselect_b32 s44, s61, s42
	s_cselect_b32 s43, s21, s64
	s_cselect_b32 s42, s62, s63
	s_add_i32 m0, s49, 0xc000
	ds_read_b128 v[202:205], v158
	ds_read_b128 v[206:209], v158 offset:1024
	ds_read_b128 v[210:213], v158 offset:2048
	ds_read_b128 v[214:217], v158 offset:3072
	ds_read_b128 v[218:221], v158 offset:4096
	ds_read_b128 v[222:225], v158 offset:5120
	ds_read_b128 v[226:229], v158 offset:6144
	ds_read_b128 v[230:233], v158 offset:7168
	global_load_lds_dwordx4 v138, s[40:41]
	s_add_i32 m0, s49, 0xe000
	s_nop 0
	global_load_lds_dwordx4 v140, s[40:41]
	s_waitcnt vmcnt(8)
	s_waitcnt lgkmcnt(0)
	s_barrier
	s_setprio 1
	v_mfma_f32_16x16x32_bf16 v[126:129], v[166:169], v[202:205], v[126:129]
	v_mfma_f32_16x16x32_bf16 v[118:121], v[174:177], v[202:205], v[118:121]
	v_mfma_f32_16x16x32_bf16 v[110:113], v[166:169], v[210:213], v[110:113]
	v_mfma_f32_16x16x32_bf16 v[102:105], v[174:177], v[210:213], v[102:105]
	v_mfma_f32_16x16x32_bf16 v[94:97], v[166:169], v[218:221], v[94:97]
	v_mfma_f32_16x16x32_bf16 v[86:89], v[174:177], v[218:221], v[86:89]
	v_mfma_f32_16x16x32_bf16 v[78:81], v[166:169], v[226:229], v[78:81]
	v_mfma_f32_16x16x32_bf16 v[70:73], v[174:177], v[226:229], v[70:73]
	v_mfma_f32_16x16x32_bf16 v[126:129], v[170:173], v[206:209], v[126:129]
	v_mfma_f32_16x16x32_bf16 v[118:121], v[178:181], v[206:209], v[118:121]
	v_mfma_f32_16x16x32_bf16 v[110:113], v[170:173], v[214:217], v[110:113]
	v_mfma_f32_16x16x32_bf16 v[102:105], v[178:181], v[214:217], v[102:105]
	v_mfma_f32_16x16x32_bf16 v[94:97], v[170:173], v[222:225], v[94:97]
	v_mfma_f32_16x16x32_bf16 v[86:89], v[178:181], v[222:225], v[86:89]
	v_mfma_f32_16x16x32_bf16 v[78:81], v[170:173], v[230:233], v[78:81]
	v_mfma_f32_16x16x32_bf16 v[70:73], v[178:181], v[230:233], v[70:73]
	v_mfma_f32_16x16x32_bf16 v[122:125], v[186:189], v[202:205], v[122:125]
	v_mfma_f32_16x16x32_bf16 v[114:117], v[194:197], v[202:205], v[114:117]
	v_mfma_f32_16x16x32_bf16 v[106:109], v[186:189], v[210:213], v[106:109]
	v_mfma_f32_16x16x32_bf16 v[98:101], v[194:197], v[210:213], v[98:101]
	v_mfma_f32_16x16x32_bf16 v[90:93], v[186:189], v[218:221], v[90:93]
	v_mfma_f32_16x16x32_bf16 v[82:85], v[194:197], v[218:221], v[82:85]
	v_mfma_f32_16x16x32_bf16 v[74:77], v[186:189], v[226:229], v[74:77]
	v_mfma_f32_16x16x32_bf16 v[66:69], v[194:197], v[226:229], v[66:69]
	v_mfma_f32_16x16x32_bf16 v[122:125], v[190:193], v[206:209], v[122:125]
	v_mfma_f32_16x16x32_bf16 v[114:117], v[198:201], v[206:209], v[114:117]
	v_mfma_f32_16x16x32_bf16 v[106:109], v[190:193], v[214:217], v[106:109]
	v_mfma_f32_16x16x32_bf16 v[98:101], v[198:201], v[214:217], v[98:101]
	v_mfma_f32_16x16x32_bf16 v[90:93], v[190:193], v[222:225], v[90:93]
	v_mfma_f32_16x16x32_bf16 v[82:85], v[198:201], v[222:225], v[82:85]
	v_mfma_f32_16x16x32_bf16 v[74:77], v[190:193], v[230:233], v[74:77]
	v_mfma_f32_16x16x32_bf16 v[66:69], v[198:201], v[230:233], v[66:69]
	s_setprio 0
	s_barrier
	s_add_u32 s88, s42, s16
	s_addc_u32 s89, s43, s17
	s_add_u32 s90, s44, s16
	s_addc_u32 s91, s45, s17
	s_add_i32 s66, s57, s46
	s_mov_b32 m0, s66
	ds_read_b128 v[202:205], v158 offset:16384
	ds_read_b128 v[206:209], v158 offset:17408
	ds_read_b128 v[210:213], v158 offset:18432
	ds_read_b128 v[214:217], v158 offset:19456
	ds_read_b128 v[218:221], v158 offset:20480
	ds_read_b128 v[222:225], v158 offset:21504
	ds_read_b128 v[226:229], v158 offset:22528
	ds_read_b128 v[230:233], v158 offset:23552
	global_load_lds_dwordx4 v134, s[42:43]
	s_add_i32 m0, s66, 0x2000
	s_add_u32 s66, s42, 0x40000
	s_addc_u32 s67, s43, 0
	s_add_i32 s68, s58, s46
	global_load_lds_dwordx4 v130, s[42:43]
	s_mov_b32 m0, s68
	s_nop 0
	global_load_lds_dwordx4 v134, s[66:67]
	s_add_i32 m0, s68, 0x2000
	s_nop 0
	global_load_lds_dwordx4 v130, s[66:67]
	s_mov_b32 m0, s49
	s_nop 0
	global_load_lds_dwordx4 v136, s[44:45]
	s_mov_b32 m0, s50
	s_nop 0
	global_load_lds_dwordx4 v132, s[44:45]
	s_waitcnt vmcnt(8)
	s_waitcnt lgkmcnt(0)
	s_barrier
	s_setprio 1
	v_mfma_f32_16x16x32_bf16 v[62:65], v[166:169], v[202:205], v[62:65]
	v_mfma_f32_16x16x32_bf16 v[54:57], v[174:177], v[202:205], v[54:57]
	v_mfma_f32_16x16x32_bf16 v[46:49], v[166:169], v[210:213], v[46:49]
	v_mfma_f32_16x16x32_bf16 v[38:41], v[174:177], v[210:213], v[38:41]
	v_mfma_f32_16x16x32_bf16 v[30:33], v[166:169], v[218:221], v[30:33]
	v_mfma_f32_16x16x32_bf16 v[22:25], v[174:177], v[218:221], v[22:25]
	v_mfma_f32_16x16x32_bf16 v[14:17], v[166:169], v[226:229], v[14:17]
	v_mfma_f32_16x16x32_bf16 v[6:9], v[174:177], v[226:229], v[6:9]
	v_mfma_f32_16x16x32_bf16 v[62:65], v[170:173], v[206:209], v[62:65]
	v_mfma_f32_16x16x32_bf16 v[54:57], v[178:181], v[206:209], v[54:57]
	v_mfma_f32_16x16x32_bf16 v[46:49], v[170:173], v[214:217], v[46:49]
	v_mfma_f32_16x16x32_bf16 v[38:41], v[178:181], v[214:217], v[38:41]
	v_mfma_f32_16x16x32_bf16 v[30:33], v[170:173], v[222:225], v[30:33]
	v_mfma_f32_16x16x32_bf16 v[22:25], v[178:181], v[222:225], v[22:25]
	v_mfma_f32_16x16x32_bf16 v[14:17], v[170:173], v[230:233], v[14:17]
	v_mfma_f32_16x16x32_bf16 v[6:9], v[178:181], v[230:233], v[6:9]
	v_mfma_f32_16x16x32_bf16 v[58:61], v[186:189], v[202:205], v[58:61]
	v_mfma_f32_16x16x32_bf16 v[50:53], v[194:197], v[202:205], v[50:53]
	v_mfma_f32_16x16x32_bf16 v[42:45], v[186:189], v[210:213], v[42:45]
	v_mfma_f32_16x16x32_bf16 v[34:37], v[194:197], v[210:213], v[34:37]
	v_mfma_f32_16x16x32_bf16 v[26:29], v[186:189], v[218:221], v[26:29]
	v_mfma_f32_16x16x32_bf16 v[18:21], v[194:197], v[218:221], v[18:21]
	v_mfma_f32_16x16x32_bf16 v[10:13], v[186:189], v[226:229], v[10:13]
	v_mfma_f32_16x16x32_bf16 v[2:5], v[194:197], v[226:229], v[2:5]
	v_mfma_f32_16x16x32_bf16 v[58:61], v[190:193], v[206:209], v[58:61]
	v_mfma_f32_16x16x32_bf16 v[50:53], v[198:201], v[206:209], v[50:53]
	v_mfma_f32_16x16x32_bf16 v[42:45], v[190:193], v[214:217], v[42:45]
	v_mfma_f32_16x16x32_bf16 v[34:37], v[198:201], v[214:217], v[34:37]
	v_mfma_f32_16x16x32_bf16 v[26:29], v[190:193], v[222:225], v[26:29]
	v_mfma_f32_16x16x32_bf16 v[18:21], v[198:201], v[222:225], v[18:21]
	v_mfma_f32_16x16x32_bf16 v[10:13], v[190:193], v[230:233], v[10:13]
	v_mfma_f32_16x16x32_bf16 v[2:5], v[198:201], v[230:233], v[2:5]
	s_setprio 0
	s_barrier
; #define PG8_STAGE(bufoff, gbase, voff) do { _Pragma("unroll") for (int _i = 0; _i < 2; ++_i) \
;         __builtin_amdgcn_global_load_lds((const unsigned*)((const char*)(gbase) + (voff)[_i]), (LAS unsigned*)(lds + (bufoff) + ldsw + _i * 8192), 16, 0, 0); } while (0)
; #define PG8_LDA(dst, b, h) do { _Pragma("unroll") for (int m = 0; m < 4; ++m) _Pragma("unroll") for (int k = 0; k < 2; ++k) dst[m][k] = *(const LAS bf16x8*)(lds + PG8_SA(b, h) + aoff + m * 2048 + k * 1024); } while (0)
; #define PG8_LDB(dst, b, h) do { _Pragma("unroll") for (int n = 0; n < 2; ++n) _Pragma("unroll") for (int k = 0; k < 2; ++k) dst[n][k] = *(const LAS bf16x8*)(lds + PG8_SB(b, h) + boff + n * 2048 + k * 1024); } while (0)
; #define PG8_MMA(ai, bj, At, Bt) do { __builtin_amdgcn_s_setprio(1); _Pragma("unroll") for (int m = 0; m < 4; ++m) _Pragma("unroll") for (int n = 0; n < 2; ++n) _Pragma("unroll") for (int k = 0; k < 2; ++k) \
;         acc[ai][bj][m][n] = __builtin_amdgcn_mfma_f32_16x16x32_bf16(Bt[n][k], At[m][k], acc[ai][bj][m][n], 0, 0, 0); __builtin_amdgcn_s_setprio(0); } while (0)
; #define PG8_WAIT_V(n) asm volatile("s_waitcnt vmcnt(" #n ")" ::: "memory")
; #define PG8_WAIT_L(n) asm volatile("s_waitcnt lgkmcnt(" #n ")" ::: "memory")
; #define PG8_BAR __builtin_amdgcn_s_barrier()
; #define PG8_SCHED __builtin_amdgcn_sched_barrier(0)
; template <class Epi, class Sched>
; DI void gemm_phase(LAS unsigned char* lds, const Gemm g, const Sched& S, const Epi& E) {
;     ...
;             PG8_LDB(B0, 1, 0); PG8_LDB(B1, 1, 1); PG8_SCHED; PG8_LDA(At, 1, 0); PG8_STAGE(PG8_SA(0, 1), a2 + hstepA, voffA);
;             PG8_WAIT_V(8); PG8_WAIT_L(0); PG8_BAR; PG8_MMA(0, 0, At, B0); PG8_MMA(0, 1, At, B1); PG8_BAR; PG8_SCHED;
;             PG8_LDA(At, 1, 1); PG8_STAGE(PG8_SB(1, 0), b3, voffB); PG8_STAGE(PG8_SB(1, 1), b3 + hstepB, voffB); PG8_STAGE(PG8_SA(1, 0), a3, voffA);
;             PG8_WAIT_V(8); PG8_WAIT_L(0); PG8_BAR; PG8_MMA(1, 0, At, B0); PG8_MMA(1, 1, At, B1); PG8_BAR; PG8_SCHED;
;         }
	s_add_i32 s66, 0, 0x18000
	v_add_u32_e32 v165, s66, v156
	s_add_i32 s67, 0, 0x1c000
	ds_read_b128 v[166:169], v165
	ds_read_b128 v[170:173], v165 offset:1024
	ds_read_b128 v[174:177], v165 offset:2048
	ds_read_b128 v[178:181], v165 offset:3072
	v_add_u32_e32 v165, s67, v156
	ds_read_b128 v[186:189], v165
	ds_read_b128 v[190:193], v165 offset:1024
	ds_read_b128 v[194:197], v165 offset:2048
	ds_read_b128 v[198:201], v165 offset:3072
	s_add_u32 s44, s44, 0x40000
	s_addc_u32 s45, s45, 0
	s_mov_b32 m0, s51
	ds_read_b128 v[202:205], v158 offset:32768
	ds_read_b128 v[206:209], v158 offset:33792
	ds_read_b128 v[210:213], v158 offset:34816
	ds_read_b128 v[214:217], v158 offset:35840
	ds_read_b128 v[218:221], v158 offset:36864
	ds_read_b128 v[222:225], v158 offset:37888
	ds_read_b128 v[226:229], v158 offset:38912
	ds_read_b128 v[230:233], v158 offset:39936
	global_load_lds_dwordx4 v136, s[44:45]
	s_mov_b32 m0, s52
	s_nop 0
	global_load_lds_dwordx4 v132, s[44:45]
	s_waitcnt vmcnt(8)
	s_waitcnt lgkmcnt(0)
	s_barrier
	s_setprio 1
	v_mfma_f32_16x16x32_bf16 v[126:129], v[166:169], v[202:205], v[126:129]
	v_mfma_f32_16x16x32_bf16 v[118:121], v[174:177], v[202:205], v[118:121]
	v_mfma_f32_16x16x32_bf16 v[110:113], v[166:169], v[210:213], v[110:113]
	v_mfma_f32_16x16x32_bf16 v[102:105], v[174:177], v[210:213], v[102:105]
	v_mfma_f32_16x16x32_bf16 v[94:97], v[166:169], v[218:221], v[94:97]
	v_mfma_f32_16x16x32_bf16 v[86:89], v[174:177], v[218:221], v[86:89]
	v_mfma_f32_16x16x32_bf16 v[78:81], v[166:169], v[226:229], v[78:81]
	v_mfma_f32_16x16x32_bf16 v[70:73], v[174:177], v[226:229], v[70:73]
	v_mfma_f32_16x16x32_bf16 v[126:129], v[170:173], v[206:209], v[126:129]
	v_mfma_f32_16x16x32_bf16 v[118:121], v[178:181], v[206:209], v[118:121]
	v_mfma_f32_16x16x32_bf16 v[110:113], v[170:173], v[214:217], v[110:113]
	v_mfma_f32_16x16x32_bf16 v[102:105], v[178:181], v[214:217], v[102:105]
	v_mfma_f32_16x16x32_bf16 v[94:97], v[170:173], v[222:225], v[94:97]
	v_mfma_f32_16x16x32_bf16 v[86:89], v[178:181], v[222:225], v[86:89]
	v_mfma_f32_16x16x32_bf16 v[78:81], v[170:173], v[230:233], v[78:81]
	v_mfma_f32_16x16x32_bf16 v[70:73], v[178:181], v[230:233], v[70:73]
	v_mfma_f32_16x16x32_bf16 v[122:125], v[186:189], v[202:205], v[122:125]
	v_mfma_f32_16x16x32_bf16 v[114:117], v[194:197], v[202:205], v[114:117]
	v_mfma_f32_16x16x32_bf16 v[106:109], v[186:189], v[210:213], v[106:109]
	v_mfma_f32_16x16x32_bf16 v[98:101], v[194:197], v[210:213], v[98:101]
	v_mfma_f32_16x16x32_bf16 v[90:93], v[186:189], v[218:221], v[90:93]
	v_mfma_f32_16x16x32_bf16 v[82:85], v[194:197], v[218:221], v[82:85]
	v_mfma_f32_16x16x32_bf16 v[74:77], v[186:189], v[226:229], v[74:77]
	v_mfma_f32_16x16x32_bf16 v[66:69], v[194:197], v[226:229], v[66:69]
	v_mfma_f32_16x16x32_bf16 v[122:125], v[190:193], v[206:209], v[122:125]
	v_mfma_f32_16x16x32_bf16 v[114:117], v[198:201], v[206:209], v[114:117]
	v_mfma_f32_16x16x32_bf16 v[106:109], v[190:193], v[214:217], v[106:109]
	v_mfma_f32_16x16x32_bf16 v[98:101], v[198:201], v[214:217], v[98:101]
	v_mfma_f32_16x16x32_bf16 v[90:93], v[190:193], v[222:225], v[90:93]
	v_mfma_f32_16x16x32_bf16 v[82:85], v[198:201], v[222:225], v[82:85]
	v_mfma_f32_16x16x32_bf16 v[74:77], v[190:193], v[230:233], v[74:77]
	v_mfma_f32_16x16x32_bf16 v[66:69], v[198:201], v[230:233], v[66:69]
	s_setprio 0
	s_barrier
	s_add_i32 s44, s66, s46
	s_mov_b32 m0, s44
	ds_read_b128 v[202:205], v158 offset:49152
	ds_read_b128 v[206:209], v158 offset:50176
	ds_read_b128 v[210:213], v158 offset:51200
	ds_read_b128 v[214:217], v158 offset:52224
	ds_read_b128 v[218:221], v158 offset:53248
	ds_read_b128 v[222:225], v158 offset:54272
	ds_read_b128 v[226:229], v158 offset:55296
	ds_read_b128 v[230:233], v158 offset:56320
	global_load_lds_dwordx4 v134, s[88:89]
	s_add_i32 m0, s44, 0x2000
	s_add_u32 s42, s42, 0x40080
	s_addc_u32 s43, s43, 0
	s_add_i32 s44, s67, s46
	global_load_lds_dwordx4 v130, s[88:89]
	s_mov_b32 m0, s44
	s_nop 0
	global_load_lds_dwordx4 v134, s[42:43]
	s_add_i32 m0, s44, 0x2000
	s_nop 0
	global_load_lds_dwordx4 v130, s[42:43]
	s_mov_b32 m0, s54
	s_nop 0
	global_load_lds_dwordx4 v136, s[90:91]
	s_mov_b32 m0, s55
	s_nop 0
	global_load_lds_dwordx4 v132, s[90:91]
	s_waitcnt vmcnt(8)
	s_waitcnt lgkmcnt(0)
	s_barrier
	s_setprio 1
	v_mfma_f32_16x16x32_bf16 v[62:65], v[166:169], v[202:205], v[62:65]
	v_mfma_f32_16x16x32_bf16 v[54:57], v[174:177], v[202:205], v[54:57]
	v_mfma_f32_16x16x32_bf16 v[46:49], v[166:169], v[210:213], v[46:49]
	v_mfma_f32_16x16x32_bf16 v[38:41], v[174:177], v[210:213], v[38:41]
	v_mfma_f32_16x16x32_bf16 v[30:33], v[166:169], v[218:221], v[30:33]
	v_mfma_f32_16x16x32_bf16 v[22:25], v[174:177], v[218:221], v[22:25]
	v_mfma_f32_16x16x32_bf16 v[14:17], v[166:169], v[226:229], v[14:17]
	v_mfma_f32_16x16x32_bf16 v[6:9], v[174:177], v[226:229], v[6:9]
	v_mfma_f32_16x16x32_bf16 v[62:65], v[170:173], v[206:209], v[62:65]
	v_mfma_f32_16x16x32_bf16 v[54:57], v[178:181], v[206:209], v[54:57]
	v_mfma_f32_16x16x32_bf16 v[46:49], v[170:173], v[214:217], v[46:49]
	v_mfma_f32_16x16x32_bf16 v[38:41], v[178:181], v[214:217], v[38:41]
	v_mfma_f32_16x16x32_bf16 v[30:33], v[170:173], v[222:225], v[30:33]
	v_mfma_f32_16x16x32_bf16 v[22:25], v[178:181], v[222:225], v[22:25]
	v_mfma_f32_16x16x32_bf16 v[14:17], v[170:173], v[230:233], v[14:17]
	v_mfma_f32_16x16x32_bf16 v[6:9], v[178:181], v[230:233], v[6:9]
	v_mfma_f32_16x16x32_bf16 v[58:61], v[186:189], v[202:205], v[58:61]
	v_mfma_f32_16x16x32_bf16 v[50:53], v[194:197], v[202:205], v[50:53]
	v_mfma_f32_16x16x32_bf16 v[42:45], v[186:189], v[210:213], v[42:45]
	v_mfma_f32_16x16x32_bf16 v[34:37], v[194:197], v[210:213], v[34:37]
	v_mfma_f32_16x16x32_bf16 v[26:29], v[186:189], v[218:221], v[26:29]
	v_mfma_f32_16x16x32_bf16 v[18:21], v[194:197], v[218:221], v[18:21]
	v_mfma_f32_16x16x32_bf16 v[10:13], v[186:189], v[226:229], v[10:13]
	v_mfma_f32_16x16x32_bf16 v[2:5], v[194:197], v[226:229], v[2:5]
	v_mfma_f32_16x16x32_bf16 v[58:61], v[190:193], v[206:209], v[58:61]
	v_mfma_f32_16x16x32_bf16 v[50:53], v[198:201], v[206:209], v[50:53]
	v_mfma_f32_16x16x32_bf16 v[42:45], v[190:193], v[214:217], v[42:45]
	v_mfma_f32_16x16x32_bf16 v[34:37], v[198:201], v[214:217], v[34:37]
	v_mfma_f32_16x16x32_bf16 v[26:29], v[190:193], v[222:225], v[26:29]
	v_mfma_f32_16x16x32_bf16 v[18:21], v[198:201], v[222:225], v[18:21]
	v_mfma_f32_16x16x32_bf16 v[10:13], v[190:193], v[230:233], v[10:13]
	v_mfma_f32_16x16x32_bf16 v[2:5], v[198:201], v[230:233], v[2:5]
	s_setprio 0
	s_barrier
	s_add_i32 s65, s65, 2
	s_add_u32 s40, s40, 0x100
	s_addc_u32 s41, s41, 0
	s_add_u32 s63, s63, 0x100
	s_addc_u32 s64, s64, 0
	s_cmp_gt_u32 s65, 13
	s_cbranch_scc0 .LBB0_1234
	s_mov_b32 s99, 1
	s_and_b64 vcc, exec, s[18:19]
	s_cbranch_vccz .LBB0_1237
	s_barrier

; #define PG8_STAGE(bufoff, gbase, voff) do { _Pragma("unroll") for (int _i = 0; _i < 2; ++_i) \
;         __builtin_amdgcn_global_load_lds((const unsigned*)((const char*)(gbase) + (voff)[_i]), (LAS unsigned*)(lds + (bufoff) + ldsw + _i * 8192), 16, 0, 0); } while (0)
; #define PG8_LDA(dst, b, h) do { _Pragma("unroll") for (int m = 0; m < 4; ++m) _Pragma("unroll") for (int k = 0; k < 2; ++k) dst[m][k] = *(const LAS bf16x8*)(lds + PG8_SA(b, h) + aoff + m * 2048 + k * 1024); } while (0)
; #define PG8_MMA(ai, bj, At, Bt) do { __builtin_amdgcn_s_setprio(1); _Pragma("unroll") for (int m = 0; m < 4; ++m) _Pragma("unroll") for (int n = 0; n < 2; ++n) _Pragma("unroll") for (int k = 0; k < 2; ++k) \
;         acc[ai][bj][m][n] = __builtin_amdgcn_mfma_f32_16x16x32_bf16(Bt[n][k], At[m][k], acc[ai][bj][m][n], 0, 0, 0); __builtin_amdgcn_s_setprio(0); } while (0)
; #define PG8_WAIT_V(n) asm volatile("s_waitcnt vmcnt(" #n ")" ::: "memory")
; #define PG8_WAIT_L(n) asm volatile("s_waitcnt lgkmcnt(" #n ")" ::: "memory")
; #define PG8_BAR __builtin_amdgcn_s_barrier()
; #define PG8_SCHED __builtin_amdgcn_sched_barrier(0)
; template <class Epi, class Sched>
; DI void gemm_phase(LAS unsigned char* lds, const Gemm g, const Sched& S, const Epi& E) {
;     ...
;             PG8_WAIT_V(8); PG8_WAIT_L(0); PG8_BAR; PG8_MMA(0, 0, At, B0); PG8_MMA(0, 1, At, B1); PG8_BAR; PG8_SCHED;
;             PG8_LDA(At, 0, 1); PG8_STAGE(PG8_SB(0, 0), b2, voffB); PG8_STAGE(PG8_SB(0, 1), b2 + hstepB, voffB); PG8_STAGE(PG8_SA(0, 0), a2, voffA);
;             PG8_WAIT_V(8); PG8_WAIT_L(0); PG8_BAR; PG8_MMA(1, 0, At, B0); PG8_MMA(1, 1, At, B1); PG8_BAR; PG8_SCHED;
.Lpk6_w1:
	s_waitcnt lgkmcnt(0)
	s_barrier
	s_setprio 1
	v_mfma_f32_16x16x32_bf16 v[124:127], v[144:147], v[182:185], 0
	v_mfma_f32_16x16x32_bf16 v[120:123], v[158:161], v[182:185], 0
	v_mfma_f32_16x16x32_bf16 v[108:111], v[144:147], v[190:193], 0
	v_mfma_f32_16x16x32_bf16 v[104:107], v[158:161], v[190:193], 0
	v_mfma_f32_16x16x32_bf16 v[92:95], v[144:147], v[198:201], 0
	v_mfma_f32_16x16x32_bf16 v[88:91], v[158:161], v[198:201], 0
	v_mfma_f32_16x16x32_bf16 v[76:79], v[144:147], v[206:209], 0
	v_mfma_f32_16x16x32_bf16 v[72:75], v[158:161], v[206:209], 0
	v_mfma_f32_16x16x32_bf16 v[124:127], v[154:157], v[186:189], v[124:127]
	v_mfma_f32_16x16x32_bf16 v[120:123], v[162:165], v[186:189], v[120:123]
	v_mfma_f32_16x16x32_bf16 v[108:111], v[154:157], v[194:197], v[108:111]
	v_mfma_f32_16x16x32_bf16 v[104:107], v[162:165], v[194:197], v[104:107]
	v_mfma_f32_16x16x32_bf16 v[92:95], v[154:157], v[202:205], v[92:95]
	v_mfma_f32_16x16x32_bf16 v[88:91], v[162:165], v[202:205], v[88:91]
	v_mfma_f32_16x16x32_bf16 v[76:79], v[154:157], v[210:213], v[76:79]
	v_mfma_f32_16x16x32_bf16 v[72:75], v[162:165], v[210:213], v[72:75]
	v_mfma_f32_16x16x32_bf16 v[116:119], v[166:169], v[182:185], 0
	v_mfma_f32_16x16x32_bf16 v[112:115], v[174:177], v[182:185], 0
	v_mfma_f32_16x16x32_bf16 v[100:103], v[166:169], v[190:193], 0
	v_mfma_f32_16x16x32_bf16 v[96:99], v[174:177], v[190:193], 0
	v_mfma_f32_16x16x32_bf16 v[84:87], v[166:169], v[198:201], 0
	v_mfma_f32_16x16x32_bf16 v[80:83], v[174:177], v[198:201], 0
	v_mfma_f32_16x16x32_bf16 v[68:71], v[166:169], v[206:209], 0
	v_mfma_f32_16x16x32_bf16 v[64:67], v[174:177], v[206:209], 0
	v_mfma_f32_16x16x32_bf16 v[116:119], v[170:173], v[186:189], v[116:119]
	v_mfma_f32_16x16x32_bf16 v[112:115], v[178:181], v[186:189], v[112:115]
	v_mfma_f32_16x16x32_bf16 v[100:103], v[170:173], v[194:197], v[100:103]
	v_mfma_f32_16x16x32_bf16 v[96:99], v[178:181], v[194:197], v[96:99]
	v_mfma_f32_16x16x32_bf16 v[84:87], v[170:173], v[202:205], v[84:87]
	v_mfma_f32_16x16x32_bf16 v[80:83], v[178:181], v[202:205], v[80:83]
	v_mfma_f32_16x16x32_bf16 v[68:71], v[170:173], v[210:213], v[68:71]
	v_mfma_f32_16x16x32_bf16 v[64:67], v[178:181], v[210:213], v[64:67]
	s_setprio 0
	s_barrier
	s_add_u32 s88, s18, s10
	s_addc_u32 s89, s19, s11
	s_add_u32 s90, s20, s10
	s_addc_u32 s91, s21, s11
	s_add_i32 s48, s39, s27
	s_mov_b32 m0, s48
	ds_read_b128 v[182:185], v153 offset:16384
	ds_read_b128 v[186:189], v153 offset:17408
	ds_read_b128 v[190:193], v153 offset:18432
	ds_read_b128 v[194:197], v153 offset:19456
	ds_read_b128 v[198:201], v153 offset:20480
	ds_read_b128 v[202:205], v153 offset:21504
	ds_read_b128 v[206:209], v153 offset:22528
	ds_read_b128 v[210:213], v153 offset:23552
	global_load_lds_dwordx4 v130, s[18:19]
	s_add_i32 m0, s48, 0x2000
	s_add_u32 s48, s18, 0xb0000
	s_addc_u32 s49, s19, 0
	s_add_i32 s50, s40, s27
	global_load_lds_dwordx4 v134, s[18:19]
	s_mov_b32 m0, s50
	s_nop 0
	global_load_lds_dwordx4 v130, s[48:49]
	s_add_i32 m0, s50, 0x2000
	s_nop 0
	global_load_lds_dwordx4 v134, s[48:49]
	s_mov_b32 m0, s28
	s_nop 0
	global_load_lds_dwordx4 v128, s[20:21]
	s_mov_b32 m0, s29
	s_nop 0
	global_load_lds_dwordx4 v132, s[20:21]
	s_cmp_lg_u32 s99, 0
	s_cbranch_scc1 .Lpk6_w2
	s_waitcnt vmcnt(8)
.Lpk6_w2:
	s_mov_b32 s99, 0
	s_waitcnt lgkmcnt(0)
	s_barrier
	s_setprio 1
	v_mfma_f32_16x16x32_bf16 v[60:63], v[144:147], v[182:185], 0
	v_mfma_f32_16x16x32_bf16 v[56:59], v[158:161], v[182:185], 0
	v_mfma_f32_16x16x32_bf16 v[44:47], v[144:147], v[190:193], 0
	v_mfma_f32_16x16x32_bf16 v[40:43], v[158:161], v[190:193], 0
	v_mfma_f32_16x16x32_bf16 v[28:31], v[144:147], v[198:201], 0
	v_mfma_f32_16x16x32_bf16 v[24:27], v[158:161], v[198:201], 0
	v_mfma_f32_16x16x32_bf16 v[12:15], v[144:147], v[206:209], 0
	v_mfma_f32_16x16x32_bf16 v[8:11], v[158:161], v[206:209], 0
	v_mfma_f32_16x16x32_bf16 v[60:63], v[154:157], v[186:189], v[60:63]
	v_mfma_f32_16x16x32_bf16 v[56:59], v[162:165], v[186:189], v[56:59]
	v_mfma_f32_16x16x32_bf16 v[44:47], v[154:157], v[194:197], v[44:47]
	v_mfma_f32_16x16x32_bf16 v[40:43], v[162:165], v[194:197], v[40:43]
	v_mfma_f32_16x16x32_bf16 v[28:31], v[154:157], v[202:205], v[28:31]
	v_mfma_f32_16x16x32_bf16 v[24:27], v[162:165], v[202:205], v[24:27]
	v_mfma_f32_16x16x32_bf16 v[12:15], v[154:157], v[210:213], v[12:15]
	v_mfma_f32_16x16x32_bf16 v[8:11], v[162:165], v[210:213], v[8:11]
	v_mfma_f32_16x16x32_bf16 v[52:55], v[166:169], v[182:185], 0
	v_mfma_f32_16x16x32_bf16 v[48:51], v[174:177], v[182:185], 0
	v_mfma_f32_16x16x32_bf16 v[36:39], v[166:169], v[190:193], 0
	v_mfma_f32_16x16x32_bf16 v[32:35], v[174:177], v[190:193], 0
	v_mfma_f32_16x16x32_bf16 v[20:23], v[166:169], v[198:201], 0
	v_mfma_f32_16x16x32_bf16 v[16:19], v[174:177], v[198:201], 0
	v_mfma_f32_16x16x32_bf16 v[4:7], v[166:169], v[206:209], 0
	v_mfma_f32_16x16x32_bf16 v[0:3], v[174:177], v[206:209], 0
	v_mfma_f32_16x16x32_bf16 v[52:55], v[170:173], v[186:189], v[52:55]
	v_mfma_f32_16x16x32_bf16 v[48:51], v[178:181], v[186:189], v[48:51]
	v_mfma_f32_16x16x32_bf16 v[36:39], v[170:173], v[194:197], v[36:39]
	v_mfma_f32_16x16x32_bf16 v[32:35], v[178:181], v[194:197], v[32:35]
	v_mfma_f32_16x16x32_bf16 v[20:23], v[170:173], v[202:205], v[20:23]
	v_mfma_f32_16x16x32_bf16 v[16:19], v[178:181], v[202:205], v[16:19]
	v_mfma_f32_16x16x32_bf16 v[4:7], v[170:173], v[210:213], v[4:7]
	v_mfma_f32_16x16x32_bf16 v[0:3], v[178:181], v[210:213], v[0:3]
	s_setprio 0
	s_barrier
; #define PG8_STAGE(bufoff, gbase, voff) do { _Pragma("unroll") for (int _i = 0; _i < 2; ++_i) \
;         __builtin_amdgcn_global_load_lds((const unsigned*)((const char*)(gbase) + (voff)[_i]), (LAS unsigned*)(lds + (bufoff) + ldsw + _i * 8192), 16, 0, 0); } while (0)
; #define PG8_LDA(dst, b, h) do { _Pragma("unroll") for (int m = 0; m < 4; ++m) _Pragma("unroll") for (int k = 0; k < 2; ++k) dst[m][k] = *(const LAS bf16x8*)(lds + PG8_SA(b, h) + aoff + m * 2048 + k * 1024); } while (0)
; #define PG8_LDB(dst, b, h) do { _Pragma("unroll") for (int n = 0; n < 2; ++n) _Pragma("unroll") for (int k = 0; k < 2; ++k) dst[n][k] = *(const LAS bf16x8*)(lds + PG8_SB(b, h) + boff + n * 2048 + k * 1024); } while (0)
; #define PG8_MMA(ai, bj, At, Bt) do { __builtin_amdgcn_s_setprio(1); _Pragma("unroll") for (int m = 0; m < 4; ++m) _Pragma("unroll") for (int n = 0; n < 2; ++n) _Pragma("unroll") for (int k = 0; k < 2; ++k) \
;         acc[ai][bj][m][n] = __builtin_amdgcn_mfma_f32_16x16x32_bf16(Bt[n][k], At[m][k], acc[ai][bj][m][n], 0, 0, 0); __builtin_amdgcn_s_setprio(0); } while (0)
; #define PG8_WAIT_V(n) asm volatile("s_waitcnt vmcnt(" #n ")" ::: "memory")
; #define PG8_WAIT_L(n) asm volatile("s_waitcnt lgkmcnt(" #n ")" ::: "memory")
; #define PG8_BAR __builtin_amdgcn_s_barrier()
; #define PG8_SCHED __builtin_amdgcn_sched_barrier(0)
; template <class Epi, class Sched>
; DI void gemm_phase(LAS unsigned char* lds, const Gemm g, const Sched& S, const Epi& E) {
;     ...
;             PG8_LDB(B0, 1, 0); PG8_LDB(B1, 1, 1); PG8_SCHED; PG8_LDA(At, 1, 0); PG8_STAGE(PG8_SA(0, 1), a2 + hstepA, voffA);
;             PG8_WAIT_V(8); PG8_WAIT_L(0); PG8_BAR; PG8_MMA(0, 0, At, B0); PG8_MMA(0, 1, At, B1); PG8_BAR; PG8_SCHED;
;             PG8_LDA(At, 1, 1); PG8_STAGE(PG8_SB(1, 0), b3, voffB); PG8_STAGE(PG8_SB(1, 1), b3 + hstepB, voffB); PG8_STAGE(PG8_SA(1, 0), a3, voffA);
;             PG8_WAIT_V(8); PG8_WAIT_L(0); PG8_BAR; PG8_MMA(1, 0, At, B0); PG8_MMA(1, 1, At, B1); PG8_BAR; PG8_SCHED;
	s_add_i32 s48, 0, 0x18000
	s_add_i32 s49, 0, 0x1c000
	v_add_u32_e32 v162, s48, v149
	v_add_u32_e32 v178, s49, v149
	ds_read_b128 v[144:147], v162
	ds_read_b128 v[154:157], v162 offset:1024
	ds_read_b128 v[158:161], v162 offset:2048
	ds_read_b128 v[162:165], v162 offset:3072
	ds_read_b128 v[166:169], v178
	ds_read_b128 v[170:173], v178 offset:1024
	ds_read_b128 v[174:177], v178 offset:2048
	ds_read_b128 v[178:181], v178 offset:3072
	s_add_u32 s20, s20, 0xb0000
	s_addc_u32 s21, s21, 0
	s_mov_b32 m0, s33
	ds_read_b128 v[182:185], v153 offset:32768
	ds_read_b128 v[186:189], v153 offset:33792
	ds_read_b128 v[190:193], v153 offset:34816
	ds_read_b128 v[194:197], v153 offset:35840
	ds_read_b128 v[198:201], v153 offset:36864
	ds_read_b128 v[202:205], v153 offset:37888
	ds_read_b128 v[206:209], v153 offset:38912
	ds_read_b128 v[210:213], v153 offset:39936
	global_load_lds_dwordx4 v128, s[20:21]
	s_mov_b32 m0, s34
	s_nop 0
	global_load_lds_dwordx4 v132, s[20:21]
	s_waitcnt vmcnt(8)
	s_waitcnt lgkmcnt(0)
	s_barrier
	s_setprio 1
	v_mfma_f32_16x16x32_bf16 v[124:127], v[144:147], v[182:185], v[124:127]
	v_mfma_f32_16x16x32_bf16 v[120:123], v[158:161], v[182:185], v[120:123]
	v_mfma_f32_16x16x32_bf16 v[108:111], v[144:147], v[190:193], v[108:111]
	v_mfma_f32_16x16x32_bf16 v[104:107], v[158:161], v[190:193], v[104:107]
	v_mfma_f32_16x16x32_bf16 v[92:95], v[144:147], v[198:201], v[92:95]
	v_mfma_f32_16x16x32_bf16 v[88:91], v[158:161], v[198:201], v[88:91]
	v_mfma_f32_16x16x32_bf16 v[76:79], v[144:147], v[206:209], v[76:79]
	v_mfma_f32_16x16x32_bf16 v[72:75], v[158:161], v[206:209], v[72:75]
	v_mfma_f32_16x16x32_bf16 v[124:127], v[154:157], v[186:189], v[124:127]
	v_mfma_f32_16x16x32_bf16 v[120:123], v[162:165], v[186:189], v[120:123]
	v_mfma_f32_16x16x32_bf16 v[108:111], v[154:157], v[194:197], v[108:111]
	v_mfma_f32_16x16x32_bf16 v[104:107], v[162:165], v[194:197], v[104:107]
	v_mfma_f32_16x16x32_bf16 v[92:95], v[154:157], v[202:205], v[92:95]
	v_mfma_f32_16x16x32_bf16 v[88:91], v[162:165], v[202:205], v[88:91]
	v_mfma_f32_16x16x32_bf16 v[76:79], v[154:157], v[210:213], v[76:79]
	v_mfma_f32_16x16x32_bf16 v[72:75], v[162:165], v[210:213], v[72:75]
	v_mfma_f32_16x16x32_bf16 v[116:119], v[166:169], v[182:185], v[116:119]
	v_mfma_f32_16x16x32_bf16 v[112:115], v[174:177], v[182:185], v[112:115]
	v_mfma_f32_16x16x32_bf16 v[100:103], v[166:169], v[190:193], v[100:103]
	v_mfma_f32_16x16x32_bf16 v[96:99], v[174:177], v[190:193], v[96:99]
	v_mfma_f32_16x16x32_bf16 v[84:87], v[166:169], v[198:201], v[84:87]
	v_mfma_f32_16x16x32_bf16 v[80:83], v[174:177], v[198:201], v[80:83]
	v_mfma_f32_16x16x32_bf16 v[68:71], v[166:169], v[206:209], v[68:71]
	v_mfma_f32_16x16x32_bf16 v[64:67], v[174:177], v[206:209], v[64:67]
	v_mfma_f32_16x16x32_bf16 v[116:119], v[170:173], v[186:189], v[116:119]
	v_mfma_f32_16x16x32_bf16 v[112:115], v[178:181], v[186:189], v[112:115]
	v_mfma_f32_16x16x32_bf16 v[100:103], v[170:173], v[194:197], v[100:103]
	v_mfma_f32_16x16x32_bf16 v[96:99], v[178:181], v[194:197], v[96:99]
	v_mfma_f32_16x16x32_bf16 v[84:87], v[170:173], v[202:205], v[84:87]
	v_mfma_f32_16x16x32_bf16 v[80:83], v[178:181], v[202:205], v[80:83]
	v_mfma_f32_16x16x32_bf16 v[68:71], v[170:173], v[210:213], v[68:71]
	v_mfma_f32_16x16x32_bf16 v[64:67], v[178:181], v[210:213], v[64:67]
	s_setprio 0
	s_barrier
	s_add_i32 s20, s48, s27
	s_mov_b32 m0, s20
	ds_read_b128 v[182:185], v153 offset:49152
	ds_read_b128 v[186:189], v153 offset:50176
	ds_read_b128 v[190:193], v153 offset:51200
	ds_read_b128 v[194:197], v153 offset:52224
	ds_read_b128 v[198:201], v153 offset:53248
	ds_read_b128 v[202:205], v153 offset:54272
	ds_read_b128 v[206:209], v153 offset:55296
	ds_read_b128 v[210:213], v153 offset:56320
	global_load_lds_dwordx4 v130, s[88:89]
	s_add_i32 m0, s20, 0x2000
	s_add_u32 s18, s18, 0xb0080
	s_addc_u32 s19, s19, 0
	s_add_i32 s20, s49, s27
	global_load_lds_dwordx4 v134, s[88:89]
	s_mov_b32 m0, s20
	s_nop 0
	global_load_lds_dwordx4 v130, s[18:19]
	s_add_i32 m0, s20, 0x2000
	s_nop 0
	global_load_lds_dwordx4 v134, s[18:19]
	s_mov_b32 m0, s36
	s_nop 0
	global_load_lds_dwordx4 v128, s[90:91]
	s_mov_b32 m0, s37
	s_nop 0
	global_load_lds_dwordx4 v132, s[90:91]
	s_waitcnt vmcnt(8)
	s_waitcnt lgkmcnt(0)
	s_barrier
	s_setprio 1
	v_mfma_f32_16x16x32_bf16 v[60:63], v[144:147], v[182:185], v[60:63]
	v_mfma_f32_16x16x32_bf16 v[56:59], v[158:161], v[182:185], v[56:59]
	v_mfma_f32_16x16x32_bf16 v[44:47], v[144:147], v[190:193], v[44:47]
	v_mfma_f32_16x16x32_bf16 v[40:43], v[158:161], v[190:193], v[40:43]
	v_mfma_f32_16x16x32_bf16 v[28:31], v[144:147], v[198:201], v[28:31]
	v_mfma_f32_16x16x32_bf16 v[24:27], v[158:161], v[198:201], v[24:27]
	v_mfma_f32_16x16x32_bf16 v[12:15], v[144:147], v[206:209], v[12:15]
	v_mfma_f32_16x16x32_bf16 v[8:11], v[158:161], v[206:209], v[8:11]
	v_mfma_f32_16x16x32_bf16 v[60:63], v[154:157], v[186:189], v[60:63]
	v_mfma_f32_16x16x32_bf16 v[56:59], v[162:165], v[186:189], v[56:59]
	v_mfma_f32_16x16x32_bf16 v[44:47], v[154:157], v[194:197], v[44:47]
	v_mfma_f32_16x16x32_bf16 v[40:43], v[162:165], v[194:197], v[40:43]
	v_mfma_f32_16x16x32_bf16 v[28:31], v[154:157], v[202:205], v[28:31]
	v_mfma_f32_16x16x32_bf16 v[24:27], v[162:165], v[202:205], v[24:27]
	v_mfma_f32_16x16x32_bf16 v[12:15], v[154:157], v[210:213], v[12:15]
	v_mfma_f32_16x16x32_bf16 v[8:11], v[162:165], v[210:213], v[8:11]
	v_mfma_f32_16x16x32_bf16 v[52:55], v[166:169], v[182:185], v[52:55]
	v_mfma_f32_16x16x32_bf16 v[48:51], v[174:177], v[182:185], v[48:51]
	v_mfma_f32_16x16x32_bf16 v[36:39], v[166:169], v[190:193], v[36:39]
	v_mfma_f32_16x16x32_bf16 v[32:35], v[174:177], v[190:193], v[32:35]
	v_mfma_f32_16x16x32_bf16 v[20:23], v[166:169], v[198:201], v[20:23]
	v_mfma_f32_16x16x32_bf16 v[16:19], v[174:177], v[198:201], v[16:19]
	v_mfma_f32_16x16x32_bf16 v[4:7], v[166:169], v[206:209], v[4:7]
	v_mfma_f32_16x16x32_bf16 v[0:3], v[174:177], v[206:209], v[0:3]
	v_mfma_f32_16x16x32_bf16 v[52:55], v[170:173], v[186:189], v[52:55]
	v_mfma_f32_16x16x32_bf16 v[48:51], v[178:181], v[186:189], v[48:51]
	v_mfma_f32_16x16x32_bf16 v[36:39], v[170:173], v[194:197], v[36:39]
	v_mfma_f32_16x16x32_bf16 v[32:35], v[178:181], v[194:197], v[32:35]
	v_mfma_f32_16x16x32_bf16 v[20:23], v[170:173], v[202:205], v[20:23]
	v_mfma_f32_16x16x32_bf16 v[16:19], v[178:181], v[202:205], v[16:19]
	v_mfma_f32_16x16x32_bf16 v[4:7], v[170:173], v[210:213], v[4:7]
	v_mfma_f32_16x16x32_bf16 v[0:3], v[178:181], v[210:213], v[0:3]
	s_setprio 0
	s_barrier
	s_add_i32 s47, s47, 2
	s_add_u32 s16, s16, 0x100
	s_addc_u32 s17, s17, 0
	s_add_u32 s45, s45, 0x100
	s_addc_u32 s46, s46, 0
	s_cmp_gt_u32 s47, 41
; #define PG8_STAGE(bufoff, gbase, voff) do { _Pragma("unroll") for (int _i = 0; _i < 2; ++_i) \
;         __builtin_amdgcn_global_load_lds((const unsigned*)((const char*)(gbase) + (voff)[_i]), (LAS unsigned*)(lds + (bufoff) + ldsw + _i * 8192), 16, 0, 0); } while (0)
; #define PG8_LDA(dst, b, h) do { _Pragma("unroll") for (int m = 0; m < 4; ++m) _Pragma("unroll") for (int k = 0; k < 2; ++k) dst[m][k] = *(const LAS bf16x8*)(lds + PG8_SA(b, h) + aoff + m * 2048 + k * 1024); } while (0)
; #define PG8_LDB(dst, b, h) do { _Pragma("unroll") for (int n = 0; n < 2; ++n) _Pragma("unroll") for (int k = 0; k < 2; ++k) dst[n][k] = *(const LAS bf16x8*)(lds + PG8_SB(b, h) + boff + n * 2048 + k * 1024); } while (0)
; #define PG8_MMA(ai, bj, At, Bt) do { __builtin_amdgcn_s_setprio(1); _Pragma("unroll") for (int m = 0; m < 4; ++m) _Pragma("unroll") for (int n = 0; n < 2; ++n) _Pragma("unroll") for (int k = 0; k < 2; ++k) \
;         acc[ai][bj][m][n] = __builtin_amdgcn_mfma_f32_16x16x32_bf16(Bt[n][k], At[m][k], acc[ai][bj][m][n], 0, 0, 0); __builtin_amdgcn_s_setprio(0); } while (0)
; #define PG8_WAIT_V(n) asm volatile("s_waitcnt vmcnt(" #n ")" ::: "memory")
; #define PG8_WAIT_L(n) asm volatile("s_waitcnt lgkmcnt(" #n ")" ::: "memory")
; #define PG8_BAR __builtin_amdgcn_s_barrier()
; #define PG8_SCHED __builtin_amdgcn_sched_barrier(0)
; template <class Epi, class Sched>
; DI void gemm_phase(LAS unsigned char* lds, const Gemm g, const Sched& S, const Epi& E) {
;     ...
;             const bool last = (t == nt - 2);
;             const char* a1 = cA + (size_t)(t + 1) * kstep;
;             const char* a2 = last ? nA : cA + (size_t)(t + 2) * kstep; const char* b2 = last ? nB : cB + (size_t)(t + 2) * kstep;
;             const char* a3 = a2 + kstep; const char* b3 = b2 + kstep;
;             PG8_LDB(B0, 0, 0); PG8_LDB(B1, 0, 1); PG8_SCHED; PG8_LDA(At, 0, 0); PG8_STAGE(PG8_SA(1, 1), a1 + hstepA, voffA);
;             PG8_WAIT_V(8); PG8_WAIT_L(0); PG8_BAR; PG8_MMA(0, 0, At, B0); PG8_MMA(0, 1, At, B1); PG8_BAR; PG8_SCHED;
;             PG8_LDA(At, 0, 1); PG8_STAGE(PG8_SB(0, 0), b2, voffB); PG8_STAGE(PG8_SB(0, 1), b2 + hstepB, voffB); PG8_STAGE(PG8_SA(0, 0), a2, voffA);
;             PG8_WAIT_V(8); PG8_WAIT_L(0); PG8_BAR; PG8_MMA(1, 0, At, B0); PG8_MMA(1, 1, At, B1); PG8_BAR; PG8_SCHED;
.LBB0_1331:
	ds_read_b128 v[144:147], v151
	ds_read_b128 v[154:157], v151 offset:1024
	ds_read_b128 v[158:161], v151 offset:2048
	ds_read_b128 v[162:165], v151 offset:3072
	ds_read_b128 v[166:169], v152
	ds_read_b128 v[170:173], v152 offset:1024
	ds_read_b128 v[174:177], v152 offset:2048
	ds_read_b128 v[178:181], v152 offset:3072
	s_add_u32 s18, s16, 0xfff50080
	s_addc_u32 s19, s17, -1
	s_cmp_eq_u32 s47, 40
	s_cselect_b32 s21, s5, s19
	s_cselect_b32 s20, s4, s18
	s_cselect_b32 s19, s15, s46
	s_cselect_b32 s18, s14, s45
	s_add_i32 m0, s28, 0xc000
	ds_read_b128 v[182:185], v153
	ds_read_b128 v[186:189], v153 offset:1024
	ds_read_b128 v[190:193], v153 offset:2048
	ds_read_b128 v[194:197], v153 offset:3072
	ds_read_b128 v[198:201], v153 offset:4096
	ds_read_b128 v[202:205], v153 offset:5120
	ds_read_b128 v[206:209], v153 offset:6144
	ds_read_b128 v[210:213], v153 offset:7168
	global_load_lds_dwordx4 v136, s[16:17]
	s_add_i32 m0, s28, 0xe000
	s_nop 0
	global_load_lds_dwordx4 v138, s[16:17]
	s_waitcnt vmcnt(8)
	s_waitcnt lgkmcnt(0)
	s_barrier
	s_setprio 1
	v_mfma_f32_16x16x32_bf16 v[124:127], v[144:147], v[182:185], v[124:127]
	v_mfma_f32_16x16x32_bf16 v[120:123], v[158:161], v[182:185], v[120:123]
	v_mfma_f32_16x16x32_bf16 v[108:111], v[144:147], v[190:193], v[108:111]
	v_mfma_f32_16x16x32_bf16 v[104:107], v[158:161], v[190:193], v[104:107]
	v_mfma_f32_16x16x32_bf16 v[92:95], v[144:147], v[198:201], v[92:95]
	v_mfma_f32_16x16x32_bf16 v[88:91], v[158:161], v[198:201], v[88:91]
	v_mfma_f32_16x16x32_bf16 v[76:79], v[144:147], v[206:209], v[76:79]
	v_mfma_f32_16x16x32_bf16 v[72:75], v[158:161], v[206:209], v[72:75]
	v_mfma_f32_16x16x32_bf16 v[124:127], v[154:157], v[186:189], v[124:127]
	v_mfma_f32_16x16x32_bf16 v[120:123], v[162:165], v[186:189], v[120:123]
	v_mfma_f32_16x16x32_bf16 v[108:111], v[154:157], v[194:197], v[108:111]
	v_mfma_f32_16x16x32_bf16 v[104:107], v[162:165], v[194:197], v[104:107]
	v_mfma_f32_16x16x32_bf16 v[92:95], v[154:157], v[202:205], v[92:95]
	v_mfma_f32_16x16x32_bf16 v[88:91], v[162:165], v[202:205], v[88:91]
	v_mfma_f32_16x16x32_bf16 v[76:79], v[154:157], v[210:213], v[76:79]
	v_mfma_f32_16x16x32_bf16 v[72:75], v[162:165], v[210:213], v[72:75]
	v_mfma_f32_16x16x32_bf16 v[116:119], v[166:169], v[182:185], v[116:119]
	v_mfma_f32_16x16x32_bf16 v[112:115], v[174:177], v[182:185], v[112:115]
	v_mfma_f32_16x16x32_bf16 v[100:103], v[166:169], v[190:193], v[100:103]
	v_mfma_f32_16x16x32_bf16 v[96:99], v[174:177], v[190:193], v[96:99]
	v_mfma_f32_16x16x32_bf16 v[84:87], v[166:169], v[198:201], v[84:87]
	v_mfma_f32_16x16x32_bf16 v[80:83], v[174:177], v[198:201], v[80:83]
	v_mfma_f32_16x16x32_bf16 v[68:71], v[166:169], v[206:209], v[68:71]
	v_mfma_f32_16x16x32_bf16 v[64:67], v[174:177], v[206:209], v[64:67]
	v_mfma_f32_16x16x32_bf16 v[116:119], v[170:173], v[186:189], v[116:119]
	v_mfma_f32_16x16x32_bf16 v[112:115], v[178:181], v[186:189], v[112:115]
	v_mfma_f32_16x16x32_bf16 v[100:103], v[170:173], v[194:197], v[100:103]
	v_mfma_f32_16x16x32_bf16 v[96:99], v[178:181], v[194:197], v[96:99]
	v_mfma_f32_16x16x32_bf16 v[84:87], v[170:173], v[202:205], v[84:87]
	v_mfma_f32_16x16x32_bf16 v[80:83], v[178:181], v[202:205], v[80:83]
	v_mfma_f32_16x16x32_bf16 v[68:71], v[170:173], v[210:213], v[68:71]
	v_mfma_f32_16x16x32_bf16 v[64:67], v[178:181], v[210:213], v[64:67]
	s_setprio 0
	s_barrier
	s_add_u32 s88, s18, s10
	s_addc_u32 s89, s19, s11
	s_add_u32 s90, s20, s10
	s_addc_u32 s91, s21, s11
	s_add_i32 s48, s39, s27
	s_mov_b32 m0, s48
	ds_read_b128 v[182:185], v153 offset:16384
	ds_read_b128 v[186:189], v153 offset:17408
	ds_read_b128 v[190:193], v153 offset:18432
	ds_read_b128 v[194:197], v153 offset:19456
	ds_read_b128 v[198:201], v153 offset:20480
	ds_read_b128 v[202:205], v153 offset:21504
	ds_read_b128 v[206:209], v153 offset:22528
	ds_read_b128 v[210:213], v153 offset:23552
	global_load_lds_dwordx4 v130, s[18:19]
	s_add_i32 m0, s48, 0x2000
	s_add_u32 s48, s18, 0xb0000
	s_addc_u32 s49, s19, 0
	s_add_i32 s50, s40, s27
	global_load_lds_dwordx4 v134, s[18:19]
	s_mov_b32 m0, s50
	s_nop 0
	global_load_lds_dwordx4 v130, s[48:49]
	s_add_i32 m0, s50, 0x2000
	s_nop 0
	global_load_lds_dwordx4 v134, s[48:49]
	s_mov_b32 m0, s28
	s_nop 0
	global_load_lds_dwordx4 v128, s[20:21]
	s_mov_b32 m0, s29
	s_nop 0
	global_load_lds_dwordx4 v132, s[20:21]
	s_waitcnt vmcnt(8)
	s_waitcnt lgkmcnt(0)
	s_barrier
	s_setprio 1
	v_mfma_f32_16x16x32_bf16 v[60:63], v[144:147], v[182:185], v[60:63]
	v_mfma_f32_16x16x32_bf16 v[56:59], v[158:161], v[182:185], v[56:59]
	v_mfma_f32_16x16x32_bf16 v[44:47], v[144:147], v[190:193], v[44:47]
	v_mfma_f32_16x16x32_bf16 v[40:43], v[158:161], v[190:193], v[40:43]
	v_mfma_f32_16x16x32_bf16 v[28:31], v[144:147], v[198:201], v[28:31]
	v_mfma_f32_16x16x32_bf16 v[24:27], v[158:161], v[198:201], v[24:27]
	v_mfma_f32_16x16x32_bf16 v[12:15], v[144:147], v[206:209], v[12:15]
	v_mfma_f32_16x16x32_bf16 v[8:11], v[158:161], v[206:209], v[8:11]
	v_mfma_f32_16x16x32_bf16 v[60:63], v[154:157], v[186:189], v[60:63]
	v_mfma_f32_16x16x32_bf16 v[56:59], v[162:165], v[186:189], v[56:59]
	v_mfma_f32_16x16x32_bf16 v[44:47], v[154:157], v[194:197], v[44:47]
	v_mfma_f32_16x16x32_bf16 v[40:43], v[162:165], v[194:197], v[40:43]
	v_mfma_f32_16x16x32_bf16 v[28:31], v[154:157], v[202:205], v[28:31]
	v_mfma_f32_16x16x32_bf16 v[24:27], v[162:165], v[202:205], v[24:27]
	v_mfma_f32_16x16x32_bf16 v[12:15], v[154:157], v[210:213], v[12:15]
	v_mfma_f32_16x16x32_bf16 v[8:11], v[162:165], v[210:213], v[8:11]
	v_mfma_f32_16x16x32_bf16 v[52:55], v[166:169], v[182:185], v[52:55]
	v_mfma_f32_16x16x32_bf16 v[48:51], v[174:177], v[182:185], v[48:51]
	v_mfma_f32_16x16x32_bf16 v[36:39], v[166:169], v[190:193], v[36:39]
	v_mfma_f32_16x16x32_bf16 v[32:35], v[174:177], v[190:193], v[32:35]
	v_mfma_f32_16x16x32_bf16 v[20:23], v[166:169], v[198:201], v[20:23]
	v_mfma_f32_16x16x32_bf16 v[16:19], v[174:177], v[198:201], v[16:19]
	v_mfma_f32_16x16x32_bf16 v[4:7], v[166:169], v[206:209], v[4:7]
	v_mfma_f32_16x16x32_bf16 v[0:3], v[174:177], v[206:209], v[0:3]
	v_mfma_f32_16x16x32_bf16 v[52:55], v[170:173], v[186:189], v[52:55]
	v_mfma_f32_16x16x32_bf16 v[48:51], v[178:181], v[186:189], v[48:51]
	v_mfma_f32_16x16x32_bf16 v[36:39], v[170:173], v[194:197], v[36:39]
	v_mfma_f32_16x16x32_bf16 v[32:35], v[178:181], v[194:197], v[32:35]
	v_mfma_f32_16x16x32_bf16 v[20:23], v[170:173], v[202:205], v[20:23]
	v_mfma_f32_16x16x32_bf16 v[16:19], v[178:181], v[202:205], v[16:19]
	v_mfma_f32_16x16x32_bf16 v[4:7], v[170:173], v[210:213], v[4:7]
	v_mfma_f32_16x16x32_bf16 v[0:3], v[178:181], v[210:213], v[0:3]
	s_setprio 0
	s_barrier
; #define PG8_STAGE(bufoff, gbase, voff) do { _Pragma("unroll") for (int _i = 0; _i < 2; ++_i) \
;         __builtin_amdgcn_global_load_lds((const unsigned*)((const char*)(gbase) + (voff)[_i]), (LAS unsigned*)(lds + (bufoff) + ldsw + _i * 8192), 16, 0, 0); } while (0)
; #define PG8_LDA(dst, b, h) do { _Pragma("unroll") for (int m = 0; m < 4; ++m) _Pragma("unroll") for (int k = 0; k < 2; ++k) dst[m][k] = *(const LAS bf16x8*)(lds + PG8_SA(b, h) + aoff + m * 2048 + k * 1024); } while (0)
; #define PG8_LDB(dst, b, h) do { _Pragma("unroll") for (int n = 0; n < 2; ++n) _Pragma("unroll") for (int k = 0; k < 2; ++k) dst[n][k] = *(const LAS bf16x8*)(lds + PG8_SB(b, h) + boff + n * 2048 + k * 1024); } while (0)
; #define PG8_MMA(ai, bj, At, Bt) do { __builtin_amdgcn_s_setprio(1); _Pragma("unroll") for (int m = 0; m < 4; ++m) _Pragma("unroll") for (int n = 0; n < 2; ++n) _Pragma("unroll") for (int k = 0; k < 2; ++k) \
;         acc[ai][bj][m][n] = __builtin_amdgcn_mfma_f32_16x16x32_bf16(Bt[n][k], At[m][k], acc[ai][bj][m][n], 0, 0, 0); __builtin_amdgcn_s_setprio(0); } while (0)
; #define PG8_WAIT_V(n) asm volatile("s_waitcnt vmcnt(" #n ")" ::: "memory")
; #define PG8_WAIT_L(n) asm volatile("s_waitcnt lgkmcnt(" #n ")" ::: "memory")
; #define PG8_BAR __builtin_amdgcn_s_barrier()
; #define PG8_SCHED __builtin_amdgcn_sched_barrier(0)
; template <class Epi, class Sched>
; DI void gemm_phase(LAS unsigned char* lds, const Gemm g, const Sched& S, const Epi& E) {
;     ...
;             PG8_LDB(B0, 1, 0); PG8_LDB(B1, 1, 1); PG8_SCHED; PG8_LDA(At, 1, 0); PG8_STAGE(PG8_SA(0, 1), a2 + hstepA, voffA);
;             PG8_WAIT_V(8); PG8_WAIT_L(0); PG8_BAR; PG8_MMA(0, 0, At, B0); PG8_MMA(0, 1, At, B1); PG8_BAR; PG8_SCHED;
;             PG8_LDA(At, 1, 1); PG8_STAGE(PG8_SB(1, 0), b3, voffB); PG8_STAGE(PG8_SB(1, 1), b3 + hstepB, voffB); PG8_STAGE(PG8_SA(1, 0), a3, voffA);
;             PG8_WAIT_V(8); PG8_WAIT_L(0); PG8_BAR; PG8_MMA(1, 0, At, B0); PG8_MMA(1, 1, At, B1); PG8_BAR; PG8_SCHED;
;         }
	s_add_i32 s48, 0, 0x18000
	s_add_i32 s49, 0, 0x1c000
	v_add_u32_e32 v162, s48, v149
	v_add_u32_e32 v178, s49, v149
	ds_read_b128 v[144:147], v162
	ds_read_b128 v[154:157], v162 offset:1024
	ds_read_b128 v[158:161], v162 offset:2048
	ds_read_b128 v[162:165], v162 offset:3072
	ds_read_b128 v[166:169], v178
	ds_read_b128 v[170:173], v178 offset:1024
	ds_read_b128 v[174:177], v178 offset:2048
	ds_read_b128 v[178:181], v178 offset:3072
	s_add_u32 s20, s20, 0xb0000
	s_addc_u32 s21, s21, 0
	s_mov_b32 m0, s33
	ds_read_b128 v[182:185], v153 offset:32768
	ds_read_b128 v[186:189], v153 offset:33792
	ds_read_b128 v[190:193], v153 offset:34816
	ds_read_b128 v[194:197], v153 offset:35840
	ds_read_b128 v[198:201], v153 offset:36864
	ds_read_b128 v[202:205], v153 offset:37888
	ds_read_b128 v[206:209], v153 offset:38912
	ds_read_b128 v[210:213], v153 offset:39936
	global_load_lds_dwordx4 v128, s[20:21]
	s_mov_b32 m0, s34
	s_nop 0
	global_load_lds_dwordx4 v132, s[20:21]
	s_waitcnt vmcnt(8)
	s_waitcnt lgkmcnt(0)
	s_barrier
	s_setprio 1
	v_mfma_f32_16x16x32_bf16 v[124:127], v[144:147], v[182:185], v[124:127]
	v_mfma_f32_16x16x32_bf16 v[120:123], v[158:161], v[182:185], v[120:123]
	v_mfma_f32_16x16x32_bf16 v[108:111], v[144:147], v[190:193], v[108:111]
	v_mfma_f32_16x16x32_bf16 v[104:107], v[158:161], v[190:193], v[104:107]
	v_mfma_f32_16x16x32_bf16 v[92:95], v[144:147], v[198:201], v[92:95]
	v_mfma_f32_16x16x32_bf16 v[88:91], v[158:161], v[198:201], v[88:91]
	v_mfma_f32_16x16x32_bf16 v[76:79], v[144:147], v[206:209], v[76:79]
	v_mfma_f32_16x16x32_bf16 v[72:75], v[158:161], v[206:209], v[72:75]
	v_mfma_f32_16x16x32_bf16 v[124:127], v[154:157], v[186:189], v[124:127]
	v_mfma_f32_16x16x32_bf16 v[120:123], v[162:165], v[186:189], v[120:123]
	v_mfma_f32_16x16x32_bf16 v[108:111], v[154:157], v[194:197], v[108:111]
	v_mfma_f32_16x16x32_bf16 v[104:107], v[162:165], v[194:197], v[104:107]
	v_mfma_f32_16x16x32_bf16 v[92:95], v[154:157], v[202:205], v[92:95]
	v_mfma_f32_16x16x32_bf16 v[88:91], v[162:165], v[202:205], v[88:91]
	v_mfma_f32_16x16x32_bf16 v[76:79], v[154:157], v[210:213], v[76:79]
	v_mfma_f32_16x16x32_bf16 v[72:75], v[162:165], v[210:213], v[72:75]
	v_mfma_f32_16x16x32_bf16 v[116:119], v[166:169], v[182:185], v[116:119]
	v_mfma_f32_16x16x32_bf16 v[112:115], v[174:177], v[182:185], v[112:115]
	v_mfma_f32_16x16x32_bf16 v[100:103], v[166:169], v[190:193], v[100:103]
	v_mfma_f32_16x16x32_bf16 v[96:99], v[174:177], v[190:193], v[96:99]
	v_mfma_f32_16x16x32_bf16 v[84:87], v[166:169], v[198:201], v[84:87]
	v_mfma_f32_16x16x32_bf16 v[80:83], v[174:177], v[198:201], v[80:83]
	v_mfma_f32_16x16x32_bf16 v[68:71], v[166:169], v[206:209], v[68:71]
	v_mfma_f32_16x16x32_bf16 v[64:67], v[174:177], v[206:209], v[64:67]
	v_mfma_f32_16x16x32_bf16 v[116:119], v[170:173], v[186:189], v[116:119]
	v_mfma_f32_16x16x32_bf16 v[112:115], v[178:181], v[186:189], v[112:115]
	v_mfma_f32_16x16x32_bf16 v[100:103], v[170:173], v[194:197], v[100:103]
	v_mfma_f32_16x16x32_bf16 v[96:99], v[178:181], v[194:197], v[96:99]
	v_mfma_f32_16x16x32_bf16 v[84:87], v[170:173], v[202:205], v[84:87]
	v_mfma_f32_16x16x32_bf16 v[80:83], v[178:181], v[202:205], v[80:83]
	v_mfma_f32_16x16x32_bf16 v[68:71], v[170:173], v[210:213], v[68:71]
	v_mfma_f32_16x16x32_bf16 v[64:67], v[178:181], v[210:213], v[64:67]
	s_setprio 0
	s_barrier
	s_add_i32 s20, s48, s27
	s_mov_b32 m0, s20
	ds_read_b128 v[182:185], v153 offset:49152
	ds_read_b128 v[186:189], v153 offset:50176
	ds_read_b128 v[190:193], v153 offset:51200
	ds_read_b128 v[194:197], v153 offset:52224
	ds_read_b128 v[198:201], v153 offset:53248
	ds_read_b128 v[202:205], v153 offset:54272
	ds_read_b128 v[206:209], v153 offset:55296
	ds_read_b128 v[210:213], v153 offset:56320
	global_load_lds_dwordx4 v130, s[88:89]
	s_add_i32 m0, s20, 0x2000
	s_add_u32 s18, s18, 0xb0080
	s_addc_u32 s19, s19, 0
	s_add_i32 s20, s49, s27
	global_load_lds_dwordx4 v134, s[88:89]
	s_mov_b32 m0, s20
	s_nop 0
	global_load_lds_dwordx4 v130, s[18:19]
	s_add_i32 m0, s20, 0x2000
	s_nop 0
	global_load_lds_dwordx4 v134, s[18:19]
	s_mov_b32 m0, s36
	s_nop 0
	global_load_lds_dwordx4 v128, s[90:91]
	s_mov_b32 m0, s37
	s_nop 0
	global_load_lds_dwordx4 v132, s[90:91]
	s_waitcnt vmcnt(8)
	s_waitcnt lgkmcnt(0)
	s_barrier
	s_setprio 1
	v_mfma_f32_16x16x32_bf16 v[60:63], v[144:147], v[182:185], v[60:63]
	v_mfma_f32_16x16x32_bf16 v[56:59], v[158:161], v[182:185], v[56:59]
	v_mfma_f32_16x16x32_bf16 v[44:47], v[144:147], v[190:193], v[44:47]
	v_mfma_f32_16x16x32_bf16 v[40:43], v[158:161], v[190:193], v[40:43]
	v_mfma_f32_16x16x32_bf16 v[28:31], v[144:147], v[198:201], v[28:31]
	v_mfma_f32_16x16x32_bf16 v[24:27], v[158:161], v[198:201], v[24:27]
	v_mfma_f32_16x16x32_bf16 v[12:15], v[144:147], v[206:209], v[12:15]
	v_mfma_f32_16x16x32_bf16 v[8:11], v[158:161], v[206:209], v[8:11]
	v_mfma_f32_16x16x32_bf16 v[60:63], v[154:157], v[186:189], v[60:63]
	v_mfma_f32_16x16x32_bf16 v[56:59], v[162:165], v[186:189], v[56:59]
	v_mfma_f32_16x16x32_bf16 v[44:47], v[154:157], v[194:197], v[44:47]
	v_mfma_f32_16x16x32_bf16 v[40:43], v[162:165], v[194:197], v[40:43]
	v_mfma_f32_16x16x32_bf16 v[28:31], v[154:157], v[202:205], v[28:31]
	v_mfma_f32_16x16x32_bf16 v[24:27], v[162:165], v[202:205], v[24:27]
	v_mfma_f32_16x16x32_bf16 v[12:15], v[154:157], v[210:213], v[12:15]
	v_mfma_f32_16x16x32_bf16 v[8:11], v[162:165], v[210:213], v[8:11]
	v_mfma_f32_16x16x32_bf16 v[52:55], v[166:169], v[182:185], v[52:55]
	v_mfma_f32_16x16x32_bf16 v[48:51], v[174:177], v[182:185], v[48:51]
	v_mfma_f32_16x16x32_bf16 v[36:39], v[166:169], v[190:193], v[36:39]
	v_mfma_f32_16x16x32_bf16 v[32:35], v[174:177], v[190:193], v[32:35]
	v_mfma_f32_16x16x32_bf16 v[20:23], v[166:169], v[198:201], v[20:23]
	v_mfma_f32_16x16x32_bf16 v[16:19], v[174:177], v[198:201], v[16:19]
	v_mfma_f32_16x16x32_bf16 v[4:7], v[166:169], v[206:209], v[4:7]
	v_mfma_f32_16x16x32_bf16 v[0:3], v[174:177], v[206:209], v[0:3]
	v_mfma_f32_16x16x32_bf16 v[52:55], v[170:173], v[186:189], v[52:55]
	v_mfma_f32_16x16x32_bf16 v[48:51], v[178:181], v[186:189], v[48:51]
	v_mfma_f32_16x16x32_bf16 v[36:39], v[170:173], v[194:197], v[36:39]
	v_mfma_f32_16x16x32_bf16 v[32:35], v[178:181], v[194:197], v[32:35]
	v_mfma_f32_16x16x32_bf16 v[20:23], v[170:173], v[202:205], v[20:23]
	v_mfma_f32_16x16x32_bf16 v[16:19], v[178:181], v[202:205], v[16:19]
	v_mfma_f32_16x16x32_bf16 v[4:7], v[170:173], v[210:213], v[4:7]
	v_mfma_f32_16x16x32_bf16 v[0:3], v[178:181], v[210:213], v[0:3]
	s_setprio 0
	s_barrier
	s_add_i32 s47, s47, 2
	s_add_u32 s16, s16, 0x100
	s_addc_u32 s17, s17, 0
	s_add_u32 s45, s45, 0x100
	s_addc_u32 s46, s46, 0
	s_cmp_gt_u32 s47, 41
	s_cbranch_scc0 .LBB0_1331
	s_mov_b32 s99, 1
	s_and_b64 vcc, exec, s[12:13]
	s_cbranch_vccz .LBB0_1334
	s_barrier
